# strategy 4: GEMM K-loops with one static s_setprio 1 for waves 4-7 and hipcc's 80 per-phase s_setprio flips removed
# speedup vs baseline: 1.0137x; 1.0137x over previous
.LBB0_21:
	s_setprio 0
	s_cmp_lg_u32 s81, 44
	s_cselect_b64 s[4:5], -1, 0
	s_cmp_eq_u32 s81, 44
	s_mov_b64 s[8:9], -1
	s_cbranch_scc1 .LBB0_30
	s_mul_hi_i32 s2, s81, 0x2e8ba2e9
	s_lshr_b32 s8, s2, 31
	s_ashr_i32 s2, s2, 2
	s_add_i32 s2, s2, s8
	s_mul_i32 s2, s2, 22
	s_sub_i32 s2, s81, s2
	s_cmp_lt_i32 s2, 11
	s_cbranch_scc1 .LBB0_25
	s_cmp_gt_i32 s2, 15
	s_cbranch_scc0 .LBB0_26
	s_cmp_lg_u32 s2, 16
	s_cselect_b64 s[8:9], -1, 0
	s_cbranch_execz .LBB0_27
	s_branch .LBB0_28

.LBB0_132:
	s_add_u32 s34, s28, 0x100
	v_mov_b32_e32 v0, 0
	s_addc_u32 s79, s29, 0
	s_mov_b32 s84, -2
	v_mov_b32_e32 v1, v0
	v_mov_b32_e32 v2, v0
	v_mov_b32_e32 v3, v0
	v_mov_b32_e32 v4, v0
	v_mov_b32_e32 v5, v0
	v_mov_b32_e32 v6, v0
	v_mov_b32_e32 v7, v0
	v_mov_b32_e32 v8, v0
	v_mov_b32_e32 v9, v0
	v_mov_b32_e32 v10, v0
	v_mov_b32_e32 v11, v0
	v_mov_b32_e32 v12, v0
	v_mov_b32_e32 v13, v0
	v_mov_b32_e32 v14, v0
	v_mov_b32_e32 v15, v0
	v_mov_b32_e32 v22, v0
	v_mov_b32_e32 v23, v0
	v_mov_b32_e32 v24, v0
	v_mov_b32_e32 v25, v0
	v_mov_b32_e32 v26, v0
	v_mov_b32_e32 v27, v0
	v_mov_b32_e32 v28, v0
	v_mov_b32_e32 v29, v0
	v_mov_b32_e32 v34, v0
	v_mov_b32_e32 v35, v0
	v_mov_b32_e32 v36, v0
	v_mov_b32_e32 v37, v0
	v_mov_b32_e32 v42, v0
	v_mov_b32_e32 v43, v0
	v_mov_b32_e32 v44, v0
	v_mov_b32_e32 v45, v0
	v_mov_b32_e32 v18, v0
	v_mov_b32_e32 v19, v0
	v_mov_b32_e32 v20, v0
	v_mov_b32_e32 v21, v0
	v_mov_b32_e32 v30, v0
	v_mov_b32_e32 v31, v0
	v_mov_b32_e32 v32, v0
	v_mov_b32_e32 v33, v0
	v_mov_b32_e32 v38, v0
	v_mov_b32_e32 v39, v0
	v_mov_b32_e32 v40, v0
	v_mov_b32_e32 v41, v0
	v_mov_b32_e32 v46, v0
	v_mov_b32_e32 v47, v0
	v_mov_b32_e32 v48, v0
	v_mov_b32_e32 v49, v0
	v_mov_b32_e32 v50, v0
	v_mov_b32_e32 v51, v0
	v_mov_b32_e32 v52, v0
	v_mov_b32_e32 v53, v0
	v_mov_b32_e32 v54, v0
	v_mov_b32_e32 v55, v0
	v_mov_b32_e32 v56, v0
	v_mov_b32_e32 v57, v0
	v_mov_b32_e32 v58, v0
	v_mov_b32_e32 v59, v0
	v_mov_b32_e32 v60, v0
	v_mov_b32_e32 v61, v0
	v_mov_b32_e32 v62, v0
	v_mov_b32_e32 v63, v0
	v_mov_b32_e32 v64, v0
	v_mov_b32_e32 v65, v0
	v_mov_b32_e32 v66, v0
	v_mov_b32_e32 v67, v0
	v_mov_b32_e32 v68, v0
	v_mov_b32_e32 v69, v0
	v_mov_b32_e32 v70, v0
	v_mov_b32_e32 v71, v0
	v_mov_b32_e32 v72, v0
	v_mov_b32_e32 v73, v0
	v_mov_b32_e32 v78, v0
	v_mov_b32_e32 v79, v0
	v_mov_b32_e32 v80, v0
	v_mov_b32_e32 v81, v0
	v_mov_b32_e32 v82, v0
	v_mov_b32_e32 v83, v0
	v_mov_b32_e32 v84, v0
	v_mov_b32_e32 v85, v0
	v_mov_b32_e32 v94, v0
	v_mov_b32_e32 v95, v0
	v_mov_b32_e32 v96, v0
	v_mov_b32_e32 v97, v0
	v_mov_b32_e32 v98, v0
	v_mov_b32_e32 v99, v0
	v_mov_b32_e32 v100, v0
	v_mov_b32_e32 v101, v0
	v_mov_b32_e32 v110, v0
	v_mov_b32_e32 v111, v0
	v_mov_b32_e32 v112, v0
	v_mov_b32_e32 v113, v0
	v_mov_b32_e32 v114, v0
	v_mov_b32_e32 v115, v0
	v_mov_b32_e32 v116, v0
	v_mov_b32_e32 v117, v0
	v_mov_b32_e32 v74, v0
	v_mov_b32_e32 v75, v0
	v_mov_b32_e32 v76, v0
	v_mov_b32_e32 v77, v0
	v_mov_b32_e32 v86, v0
	v_mov_b32_e32 v87, v0
	v_mov_b32_e32 v88, v0
	v_mov_b32_e32 v89, v0
	v_mov_b32_e32 v90, v0
	v_mov_b32_e32 v91, v0
	v_mov_b32_e32 v92, v0
	v_mov_b32_e32 v93, v0
	v_mov_b32_e32 v102, v0
	v_mov_b32_e32 v103, v0
	v_mov_b32_e32 v104, v0
	v_mov_b32_e32 v105, v0
	v_mov_b32_e32 v106, v0
	v_mov_b32_e32 v107, v0
	v_mov_b32_e32 v108, v0
	v_mov_b32_e32 v109, v0
	v_mov_b32_e32 v118, v0
	v_mov_b32_e32 v119, v0
	v_mov_b32_e32 v120, v0
	v_mov_b32_e32 v121, v0
	v_mov_b32_e32 v122, v0
	v_mov_b32_e32 v123, v0
	v_mov_b32_e32 v124, v0
	v_mov_b32_e32 v125, v0
	v_mov_b32_e32 v126, v0
	v_mov_b32_e32 v127, v0
	v_mov_b32_e32 v128, v0
	v_mov_b32_e32 v129, v0
	v_readfirstlane_b32 s98, v228
	s_lshr_b32 s98, s98, 8
	s_cmp_lg_u32 s98, 0
	s_cbranch_scc0 .Lprio_skip_0
	s_setprio 1
.Lprio_skip_0:
.LBB0_133:
	s_add_u32 s28, s22, 0x100
	s_addc_u32 s29, s23, 0
	s_add_i32 s85, 0, 0x10000
	v_add_u32_e32 v148, s85, v157
	ds_read_b128 v[130:133], v148
	ds_read_b128 v[134:137], v148 offset:1024
	ds_read_b128 v[138:141], v148 offset:2048
	ds_read_b128 v[148:151], v148 offset:3072
	s_cmp_eq_u32 s84, 40
	s_cselect_b32 s43, s17, s29
	s_cselect_b32 s42, s16, s28
	s_cselect_b32 s41, s19, s79
	s_cselect_b32 s40, s18, s34
	v_lshl_add_u64 v[188:189], s[22:23], 0, v[146:147]
	s_add_i32 m0, s54, 0xc000
	ds_read_b128 v[152:155], v159
	ds_read_b128 v[160:163], v159 offset:1024
	ds_read_b128 v[164:167], v159 offset:2048
	ds_read_b128 v[168:171], v159 offset:3072
	ds_read_b128 v[172:175], v159 offset:4096
	ds_read_b128 v[176:179], v159 offset:5120
	ds_read_b128 v[180:183], v159 offset:6144
	ds_read_b128 v[184:187], v159 offset:7168
	global_load_lds_dwordx4 v[188:189], off
	v_lshl_add_u64 v[188:189], s[22:23], 0, v[144:145]
	s_add_i32 m0, s54, 0xe000
	s_nop 0
	global_load_lds_dwordx4 v[188:189], off
	s_waitcnt lgkmcnt(8)
	s_barrier
	s_waitcnt lgkmcnt(0)
	s_waitcnt lgkmcnt(0)
	v_mfma_f32_16x16x32_bf16 v[126:129], v[130:133], v[152:155], v[126:129]
	v_mfma_f32_16x16x32_bf16 v[122:125], v[138:141], v[152:155], v[122:125]
	v_mfma_f32_16x16x32_bf16 v[118:121], v[130:133], v[164:167], v[118:121]
	v_mfma_f32_16x16x32_bf16 v[106:109], v[138:141], v[164:167], v[106:109]
	v_mfma_f32_16x16x32_bf16 v[102:105], v[130:133], v[172:175], v[102:105]
	v_mfma_f32_16x16x32_bf16 v[90:93], v[138:141], v[172:175], v[90:93]
	v_mfma_f32_16x16x32_bf16 v[86:89], v[130:133], v[180:183], v[86:89]
	v_mfma_f32_16x16x32_bf16 v[74:77], v[138:141], v[180:183], v[74:77]
	v_mfma_f32_16x16x32_bf16 v[126:129], v[134:137], v[160:163], v[126:129]
	v_mfma_f32_16x16x32_bf16 v[122:125], v[148:151], v[160:163], v[122:125]
	v_mfma_f32_16x16x32_bf16 v[118:121], v[134:137], v[168:171], v[118:121]
	v_mfma_f32_16x16x32_bf16 v[106:109], v[148:151], v[168:171], v[106:109]
	v_mfma_f32_16x16x32_bf16 v[102:105], v[134:137], v[176:179], v[102:105]
	v_mfma_f32_16x16x32_bf16 v[90:93], v[148:151], v[176:179], v[90:93]
	v_mfma_f32_16x16x32_bf16 v[86:89], v[134:137], v[184:187], v[86:89]
	v_mfma_f32_16x16x32_bf16 v[74:77], v[148:151], v[184:187], v[74:77]
	s_barrier
	s_add_i32 s86, 0, 0x14000
	v_add_u32_e32 v196, s86, v157
	s_add_i32 s22, s85, s50
	ds_read_b128 v[188:191], v196
	ds_read_b128 v[192:195], v196 offset:1024
	ds_read_b128 v[208:211], v196 offset:2048
	ds_read_b128 v[212:215], v196 offset:3072
	v_lshl_add_u64 v[196:197], s[40:41], 0, v[16:17]
	s_mov_b32 m0, s22
	v_lshl_add_u64 v[216:217], s[40:41], 0, v[142:143]
	global_load_lds_dwordx4 v[196:197], off
	s_add_i32 m0, s22, 0x2000
	s_nop 0
	global_load_lds_dwordx4 v[216:217], off
	s_barrier
	s_waitcnt lgkmcnt(0)
	s_waitcnt lgkmcnt(0)
	v_mfma_f32_16x16x32_bf16 v[114:117], v[188:191], v[152:155], v[114:117]
	v_mfma_f32_16x16x32_bf16 v[110:113], v[208:211], v[152:155], v[110:113]
	v_mfma_f32_16x16x32_bf16 v[98:101], v[188:191], v[164:167], v[98:101]
	v_mfma_f32_16x16x32_bf16 v[94:97], v[208:211], v[164:167], v[94:97]
	v_mfma_f32_16x16x32_bf16 v[82:85], v[188:191], v[172:175], v[82:85]
	v_mfma_f32_16x16x32_bf16 v[78:81], v[208:211], v[172:175], v[78:81]
	v_mfma_f32_16x16x32_bf16 v[70:73], v[188:191], v[180:183], v[70:73]
	v_mfma_f32_16x16x32_bf16 v[66:69], v[208:211], v[180:183], v[66:69]
	v_mfma_f32_16x16x32_bf16 v[114:117], v[192:195], v[160:163], v[114:117]
	v_mfma_f32_16x16x32_bf16 v[110:113], v[212:215], v[160:163], v[110:113]
	v_mfma_f32_16x16x32_bf16 v[98:101], v[192:195], v[168:171], v[98:101]
	v_mfma_f32_16x16x32_bf16 v[94:97], v[212:215], v[168:171], v[94:97]
	v_mfma_f32_16x16x32_bf16 v[82:85], v[192:195], v[176:179], v[82:85]
	v_mfma_f32_16x16x32_bf16 v[78:81], v[212:215], v[176:179], v[78:81]
	v_mfma_f32_16x16x32_bf16 v[70:73], v[192:195], v[184:187], v[70:73]
	v_mfma_f32_16x16x32_bf16 v[66:69], v[212:215], v[184:187], v[66:69]
	s_mov_b32 m0, s54
	v_lshl_add_u64 v[218:219], s[42:43], 0, v[16:17]
	s_barrier
	ds_read_b128 v[152:155], v159 offset:16384
	ds_read_b128 v[160:163], v159 offset:17408
	ds_read_b128 v[164:167], v159 offset:18432
	ds_read_b128 v[168:171], v159 offset:19456
	ds_read_b128 v[172:175], v159 offset:20480
	ds_read_b128 v[176:179], v159 offset:21504
	ds_read_b128 v[180:183], v159 offset:22528
	ds_read_b128 v[184:187], v159 offset:23552
	global_load_lds_dwordx4 v[218:219], off
	v_lshl_add_u64 v[220:221], s[42:43], 0, v[142:143]
	s_mov_b32 m0, s55
	s_nop 0
	global_load_lds_dwordx4 v[220:221], off
	s_barrier
	s_waitcnt lgkmcnt(0)
	s_waitcnt lgkmcnt(0)
	v_mfma_f32_16x16x32_bf16 v[62:65], v[130:133], v[152:155], v[62:65]
	v_mfma_f32_16x16x32_bf16 v[58:61], v[138:141], v[152:155], v[58:61]
	v_mfma_f32_16x16x32_bf16 v[54:57], v[130:133], v[164:167], v[54:57]
	v_mfma_f32_16x16x32_bf16 v[50:53], v[138:141], v[164:167], v[50:53]
	v_mfma_f32_16x16x32_bf16 v[46:49], v[130:133], v[172:175], v[46:49]
	v_mfma_f32_16x16x32_bf16 v[38:41], v[138:141], v[172:175], v[38:41]
	v_mfma_f32_16x16x32_bf16 v[30:33], v[130:133], v[180:183], v[30:33]
	v_mfma_f32_16x16x32_bf16 v[18:21], v[138:141], v[180:183], v[18:21]
	v_mfma_f32_16x16x32_bf16 v[62:65], v[134:137], v[160:163], v[62:65]
	v_mfma_f32_16x16x32_bf16 v[58:61], v[148:151], v[160:163], v[58:61]
	v_mfma_f32_16x16x32_bf16 v[54:57], v[134:137], v[168:171], v[54:57]
	v_mfma_f32_16x16x32_bf16 v[50:53], v[148:151], v[168:171], v[50:53]
	v_mfma_f32_16x16x32_bf16 v[46:49], v[134:137], v[176:179], v[46:49]
	v_mfma_f32_16x16x32_bf16 v[38:41], v[148:151], v[176:179], v[38:41]
	v_mfma_f32_16x16x32_bf16 v[30:33], v[134:137], v[184:187], v[30:33]
	v_mfma_f32_16x16x32_bf16 v[18:21], v[148:151], v[184:187], v[18:21]
	s_barrier
	s_add_u32 s22, s40, 0xb0000
	s_addc_u32 s23, s41, 0
	s_add_i32 s85, s86, s50
	v_lshl_add_u64 v[130:131], s[22:23], 0, v[16:17]
	s_mov_b32 m0, s85
	s_nop 0
	global_load_lds_dwordx4 v[130:131], off
	v_lshl_add_u64 v[130:131], s[22:23], 0, v[142:143]
	s_add_i32 m0, s85, 0x2000
	s_nop 0
	global_load_lds_dwordx4 v[130:131], off
	s_waitcnt vmcnt(6)
	s_barrier
	v_mfma_f32_16x16x32_bf16 v[42:45], v[188:191], v[152:155], v[42:45]
	v_mfma_f32_16x16x32_bf16 v[34:37], v[208:211], v[152:155], v[34:37]
	v_mfma_f32_16x16x32_bf16 v[26:29], v[188:191], v[164:167], v[26:29]
	v_mfma_f32_16x16x32_bf16 v[22:25], v[208:211], v[164:167], v[22:25]
	v_mfma_f32_16x16x32_bf16 v[12:15], v[188:191], v[172:175], v[12:15]
	v_mfma_f32_16x16x32_bf16 v[8:11], v[208:211], v[172:175], v[8:11]
	v_mfma_f32_16x16x32_bf16 v[4:7], v[188:191], v[180:183], v[4:7]
	v_mfma_f32_16x16x32_bf16 v[0:3], v[208:211], v[180:183], v[0:3]
	v_mfma_f32_16x16x32_bf16 v[42:45], v[192:195], v[160:163], v[42:45]
	v_mfma_f32_16x16x32_bf16 v[34:37], v[212:215], v[160:163], v[34:37]
	v_mfma_f32_16x16x32_bf16 v[26:29], v[192:195], v[168:171], v[26:29]
	v_mfma_f32_16x16x32_bf16 v[22:25], v[212:215], v[168:171], v[22:25]
	v_mfma_f32_16x16x32_bf16 v[12:15], v[192:195], v[176:179], v[12:15]
	v_mfma_f32_16x16x32_bf16 v[8:11], v[212:215], v[176:179], v[8:11]
	v_mfma_f32_16x16x32_bf16 v[4:7], v[192:195], v[184:187], v[4:7]
	v_mfma_f32_16x16x32_bf16 v[0:3], v[212:215], v[184:187], v[0:3]
	s_add_i32 s85, 0, 0x18000
	v_add_u32_e32 v148, s85, v157
	s_barrier
	ds_read_b128 v[130:133], v148
	ds_read_b128 v[134:137], v148 offset:1024
	ds_read_b128 v[138:141], v148 offset:2048
	ds_read_b128 v[148:151], v148 offset:3072
	s_add_u32 s22, s42, 0xb0000
	s_addc_u32 s23, s43, 0
	s_mov_b32 m0, s56
	v_lshl_add_u64 v[188:189], s[22:23], 0, v[16:17]
	ds_read_b128 v[152:155], v159 offset:32768
	ds_read_b128 v[160:163], v159 offset:33792
	ds_read_b128 v[164:167], v159 offset:34816
	ds_read_b128 v[168:171], v159 offset:35840
	ds_read_b128 v[172:175], v159 offset:36864
	ds_read_b128 v[176:179], v159 offset:37888
	ds_read_b128 v[180:183], v159 offset:38912
	ds_read_b128 v[184:187], v159 offset:39936
	global_load_lds_dwordx4 v[188:189], off
	v_lshl_add_u64 v[188:189], s[22:23], 0, v[142:143]
	s_mov_b32 m0, s57
	s_nop 0
	global_load_lds_dwordx4 v[188:189], off
	s_waitcnt lgkmcnt(8)
	s_barrier
	s_waitcnt lgkmcnt(0)
	s_waitcnt lgkmcnt(0)
	v_mfma_f32_16x16x32_bf16 v[126:129], v[130:133], v[152:155], v[126:129]
	v_mfma_f32_16x16x32_bf16 v[122:125], v[138:141], v[152:155], v[122:125]
	v_mfma_f32_16x16x32_bf16 v[118:121], v[130:133], v[164:167], v[118:121]
	v_mfma_f32_16x16x32_bf16 v[106:109], v[138:141], v[164:167], v[106:109]
	v_mfma_f32_16x16x32_bf16 v[102:105], v[130:133], v[172:175], v[102:105]
	v_mfma_f32_16x16x32_bf16 v[90:93], v[138:141], v[172:175], v[90:93]
	v_mfma_f32_16x16x32_bf16 v[86:89], v[130:133], v[180:183], v[86:89]
	v_mfma_f32_16x16x32_bf16 v[74:77], v[138:141], v[180:183], v[74:77]
	v_mfma_f32_16x16x32_bf16 v[126:129], v[134:137], v[160:163], v[126:129]
	v_mfma_f32_16x16x32_bf16 v[122:125], v[148:151], v[160:163], v[122:125]
	v_mfma_f32_16x16x32_bf16 v[118:121], v[134:137], v[168:171], v[118:121]
	v_mfma_f32_16x16x32_bf16 v[106:109], v[148:151], v[168:171], v[106:109]
	v_mfma_f32_16x16x32_bf16 v[102:105], v[134:137], v[176:179], v[102:105]
	v_mfma_f32_16x16x32_bf16 v[90:93], v[148:151], v[176:179], v[90:93]
	v_mfma_f32_16x16x32_bf16 v[86:89], v[134:137], v[184:187], v[86:89]
	v_mfma_f32_16x16x32_bf16 v[74:77], v[148:151], v[184:187], v[74:77]
	s_barrier
	s_add_i32 s42, 0, 0x1c000
	s_add_i32 s22, s85, s50
	v_add_u32_e32 v212, s42, v157
	v_lshl_add_u64 v[196:197], v[196:197], 0, s[10:11]
	s_mov_b32 m0, s22
	ds_read_b128 v[188:191], v212
	ds_read_b128 v[192:195], v212 offset:1024
	ds_read_b128 v[208:211], v212 offset:2048
	ds_read_b128 v[212:215], v212 offset:3072
	global_load_lds_dwordx4 v[196:197], off
	v_lshl_add_u64 v[196:197], v[216:217], 0, s[10:11]
	s_add_i32 m0, s22, 0x2000
	s_nop 0
	global_load_lds_dwordx4 v[196:197], off
	s_barrier
	s_waitcnt lgkmcnt(0)
	s_waitcnt lgkmcnt(0)
	v_mfma_f32_16x16x32_bf16 v[114:117], v[188:191], v[152:155], v[114:117]
	v_mfma_f32_16x16x32_bf16 v[110:113], v[208:211], v[152:155], v[110:113]
	v_mfma_f32_16x16x32_bf16 v[98:101], v[188:191], v[164:167], v[98:101]
	v_mfma_f32_16x16x32_bf16 v[94:97], v[208:211], v[164:167], v[94:97]
	v_mfma_f32_16x16x32_bf16 v[82:85], v[188:191], v[172:175], v[82:85]
	v_mfma_f32_16x16x32_bf16 v[78:81], v[208:211], v[172:175], v[78:81]
	v_mfma_f32_16x16x32_bf16 v[70:73], v[188:191], v[180:183], v[70:73]
	v_mfma_f32_16x16x32_bf16 v[66:69], v[208:211], v[180:183], v[66:69]
	v_mfma_f32_16x16x32_bf16 v[114:117], v[192:195], v[160:163], v[114:117]
	v_mfma_f32_16x16x32_bf16 v[110:113], v[212:215], v[160:163], v[110:113]
	v_mfma_f32_16x16x32_bf16 v[98:101], v[192:195], v[168:171], v[98:101]
	v_mfma_f32_16x16x32_bf16 v[94:97], v[212:215], v[168:171], v[94:97]
	v_mfma_f32_16x16x32_bf16 v[82:85], v[192:195], v[176:179], v[82:85]
	v_mfma_f32_16x16x32_bf16 v[78:81], v[212:215], v[176:179], v[78:81]
	v_mfma_f32_16x16x32_bf16 v[70:73], v[192:195], v[184:187], v[70:73]
	v_mfma_f32_16x16x32_bf16 v[66:69], v[212:215], v[184:187], v[66:69]
	s_mov_b32 m0, s58
	v_lshl_add_u64 v[196:197], v[218:219], 0, s[10:11]
	s_barrier
	ds_read_b128 v[152:155], v159 offset:49152
	ds_read_b128 v[160:163], v159 offset:50176
	ds_read_b128 v[164:167], v159 offset:51200
	ds_read_b128 v[168:171], v159 offset:52224
	ds_read_b128 v[172:175], v159 offset:53248
	ds_read_b128 v[176:179], v159 offset:54272
	ds_read_b128 v[180:183], v159 offset:55296
	ds_read_b128 v[184:187], v159 offset:56320
	global_load_lds_dwordx4 v[196:197], off
	v_lshl_add_u64 v[196:197], v[220:221], 0, s[10:11]
	s_mov_b32 m0, s59
	s_nop 0
	global_load_lds_dwordx4 v[196:197], off
	s_barrier
	s_waitcnt lgkmcnt(0)
	s_waitcnt lgkmcnt(0)
	v_mfma_f32_16x16x32_bf16 v[62:65], v[130:133], v[152:155], v[62:65]
	v_mfma_f32_16x16x32_bf16 v[58:61], v[138:141], v[152:155], v[58:61]
	v_mfma_f32_16x16x32_bf16 v[54:57], v[130:133], v[164:167], v[54:57]
	v_mfma_f32_16x16x32_bf16 v[50:53], v[138:141], v[164:167], v[50:53]
	v_mfma_f32_16x16x32_bf16 v[46:49], v[130:133], v[172:175], v[46:49]
	v_mfma_f32_16x16x32_bf16 v[38:41], v[138:141], v[172:175], v[38:41]
	v_mfma_f32_16x16x32_bf16 v[30:33], v[130:133], v[180:183], v[30:33]
	v_mfma_f32_16x16x32_bf16 v[18:21], v[138:141], v[180:183], v[18:21]
	v_mfma_f32_16x16x32_bf16 v[62:65], v[134:137], v[160:163], v[62:65]
	v_mfma_f32_16x16x32_bf16 v[58:61], v[148:151], v[160:163], v[58:61]
	v_mfma_f32_16x16x32_bf16 v[54:57], v[134:137], v[168:171], v[54:57]
	v_mfma_f32_16x16x32_bf16 v[50:53], v[148:151], v[168:171], v[50:53]
	v_mfma_f32_16x16x32_bf16 v[46:49], v[134:137], v[176:179], v[46:49]
	v_mfma_f32_16x16x32_bf16 v[38:41], v[148:151], v[176:179], v[38:41]
	v_mfma_f32_16x16x32_bf16 v[30:33], v[134:137], v[184:187], v[30:33]
	v_mfma_f32_16x16x32_bf16 v[18:21], v[148:151], v[184:187], v[18:21]
	s_barrier
	s_add_u32 s22, s40, 0xb0080
	s_addc_u32 s23, s41, 0
	s_add_i32 s40, s42, s50
	v_lshl_add_u64 v[130:131], s[22:23], 0, v[16:17]
	s_mov_b32 m0, s40
	s_nop 0
	global_load_lds_dwordx4 v[130:131], off
	v_lshl_add_u64 v[130:131], s[22:23], 0, v[142:143]
	s_add_i32 m0, s40, 0x2000
	s_nop 0
	global_load_lds_dwordx4 v[130:131], off
	s_waitcnt vmcnt(6)
	s_barrier
	v_mfma_f32_16x16x32_bf16 v[42:45], v[188:191], v[152:155], v[42:45]
	v_mfma_f32_16x16x32_bf16 v[34:37], v[208:211], v[152:155], v[34:37]
	v_mfma_f32_16x16x32_bf16 v[26:29], v[188:191], v[164:167], v[26:29]
	v_mfma_f32_16x16x32_bf16 v[22:25], v[208:211], v[164:167], v[22:25]
	v_mfma_f32_16x16x32_bf16 v[12:15], v[188:191], v[172:175], v[12:15]
	v_mfma_f32_16x16x32_bf16 v[8:11], v[208:211], v[172:175], v[8:11]
	v_mfma_f32_16x16x32_bf16 v[4:7], v[188:191], v[180:183], v[4:7]
	v_mfma_f32_16x16x32_bf16 v[0:3], v[208:211], v[180:183], v[0:3]
	v_mfma_f32_16x16x32_bf16 v[42:45], v[192:195], v[160:163], v[42:45]
	v_mfma_f32_16x16x32_bf16 v[34:37], v[212:215], v[160:163], v[34:37]
	v_mfma_f32_16x16x32_bf16 v[26:29], v[192:195], v[168:171], v[26:29]
	v_mfma_f32_16x16x32_bf16 v[22:25], v[212:215], v[168:171], v[22:25]
	v_mfma_f32_16x16x32_bf16 v[12:15], v[192:195], v[176:179], v[12:15]
	v_mfma_f32_16x16x32_bf16 v[8:11], v[212:215], v[176:179], v[8:11]
	v_mfma_f32_16x16x32_bf16 v[4:7], v[192:195], v[184:187], v[4:7]
	v_mfma_f32_16x16x32_bf16 v[0:3], v[212:215], v[184:187], v[0:3]
	s_add_i32 s84, s84, 2
	s_add_u32 s34, s34, 0x100
	s_addc_u32 s79, s79, 0
	s_cmp_gt_u32 s84, 41
	s_mov_b64 s[22:23], s[28:29]
	s_barrier
	s_cbranch_scc0 .LBB0_133
	v_lshl_or_b32 v132, s12, 8, v158
	v_lshl_add_u32 v130, s2, 8, v156
	v_ashrrev_i32_e32 v133, 31, v132
	v_lshlrev_b64 v[148:149], 2, v[132:133]
	v_ashrrev_i32_e32 v131, 31, v130
	v_lshl_add_u64 v[150:151], s[4:5], 0, v[148:149]
	v_lshlrev_b64 v[152:153], 12, v[130:131]
	v_lshl_add_u64 v[132:133], v[150:151], 0, v[152:153]
	global_load_dwordx4 v[160:163], v[132:133], off
	global_load_dwordx4 v[164:167], v[132:133], off offset:64
	global_load_dwordx4 v[168:171], v[132:133], off offset:512
	global_load_dwordx4 v[172:175], v[132:133], off offset:576
	v_or_b32_e32 v132, 16, v130
	v_ashrrev_i32_e32 v133, 31, v132
	v_lshlrev_b64 v[196:197], 12, v[132:133]
	v_lshl_add_u64 v[132:133], v[150:151], 0, v[196:197]
	global_load_dwordx4 v[176:179], v[132:133], off
	global_load_dwordx4 v[180:183], v[132:133], off offset:64
	global_load_dwordx4 v[184:187], v[132:133], off offset:512
	global_load_dwordx4 v[188:191], v[132:133], off offset:576
	v_or_b32_e32 v132, 32, v130
	v_ashrrev_i32_e32 v133, 31, v132
	v_or_b32_e32 v130, 48, v130
	v_lshlrev_b64 v[224:225], 12, v[132:133]
	v_ashrrev_i32_e32 v131, 31, v130
	v_lshl_add_u64 v[132:133], v[150:151], 0, v[224:225]
	v_lshlrev_b64 v[154:155], 12, v[130:131]
	global_load_dwordx4 v[192:195], v[132:133], off
	global_load_dwordx4 v[208:211], v[132:133], off offset:64
	global_load_dwordx4 v[212:215], v[132:133], off offset:512
	global_load_dwordx4 v[216:219], v[132:133], off offset:576
	v_lshl_add_u64 v[130:131], v[150:151], 0, v[154:155]
	global_load_dwordx4 v[220:223], v[130:131], off
	global_load_dwordx4 v[138:141], v[130:131], off offset:64
	global_load_dwordx4 v[134:137], v[130:131], off offset:512
	s_nop 0
	global_load_dwordx4 v[130:133], v[130:131], off offset:576
	s_waitcnt vmcnt(0) lgkmcnt(0)
	v_pk_fma_f32 v[126:127], v[126:127], 0.5, v[160:161] op_sel_hi:[1,0,1]
	v_lshl_add_u64 v[160:161], s[14:15], 0, v[152:153]
	v_lshl_add_u64 v[160:161], v[160:161], 0, v[148:149]
	v_pk_fma_f32 v[116:117], v[116:117], 0.5, v[170:171] op_sel_hi:[1,0,1]
	v_pk_fma_f32 v[114:115], v[114:115], 0.5, v[168:169] op_sel_hi:[1,0,1]
	global_store_dwordx4 v[160:161], v[114:117], off offset:512
	v_pk_fma_f32 v[112:113], v[112:113], 0.5, v[174:175] op_sel_hi:[1,0,1]
	v_pk_fma_f32 v[100:101], v[100:101], 0.5, v[186:187] op_sel_hi:[1,0,1]
	v_lshl_add_u64 v[114:115], s[14:15], 0, v[196:197]
	v_lshl_add_u64 v[114:115], v[114:115], 0, v[148:149]
	v_pk_fma_f32 v[98:99], v[98:99], 0.5, v[184:185] op_sel_hi:[1,0,1]
	global_store_dwordx4 v[114:115], v[98:101], off offset:512
	v_pk_fma_f32 v[110:111], v[110:111], 0.5, v[172:173] op_sel_hi:[1,0,1]
	v_pk_fma_f32 v[96:97], v[96:97], 0.5, v[190:191] op_sel_hi:[1,0,1]
	v_lshl_add_u64 v[98:99], s[14:15], 0, v[224:225]
	v_lshl_add_u64 v[98:99], v[98:99], 0, v[148:149]
	v_pk_fma_f32 v[84:85], v[84:85], 0.5, v[214:215] op_sel_hi:[1,0,1]
	v_pk_fma_f32 v[82:83], v[82:83], 0.5, v[212:213] op_sel_hi:[1,0,1]
	v_pk_fma_f32 v[94:95], v[94:95], 0.5, v[188:189] op_sel_hi:[1,0,1]
	global_store_dwordx4 v[98:99], v[82:85], off offset:512
	v_pk_fma_f32 v[80:81], v[80:81], 0.5, v[218:219] op_sel_hi:[1,0,1]
	v_pk_fma_f32 v[78:79], v[78:79], 0.5, v[216:217] op_sel_hi:[1,0,1]
	v_lshl_add_u64 v[82:83], s[14:15], 0, v[154:155]
	v_pk_fma_f32 v[128:129], v[128:129], 0.5, v[162:163] op_sel_hi:[1,0,1]
	v_pk_fma_f32 v[124:125], v[124:125], 0.5, v[166:167] op_sel_hi:[1,0,1]
	v_pk_fma_f32 v[122:123], v[122:123], 0.5, v[164:165] op_sel_hi:[1,0,1]
	global_store_dwordx4 v[160:161], v[110:113], off offset:576
	v_pk_fma_f32 v[108:109], v[108:109], 0.5, v[182:183] op_sel_hi:[1,0,1]
	v_pk_fma_f32 v[106:107], v[106:107], 0.5, v[180:181] op_sel_hi:[1,0,1]
	v_pk_fma_f32 v[112:113], v[120:121], 0.5, v[178:179] op_sel_hi:[1,0,1]
	v_pk_fma_f32 v[110:111], v[118:119], 0.5, v[176:177] op_sel_hi:[1,0,1]
	global_store_dwordx4 v[114:115], v[94:97], off offset:576
	v_pk_fma_f32 v[92:93], v[92:93], 0.5, v[210:211] op_sel_hi:[1,0,1]
	v_pk_fma_f32 v[90:91], v[90:91], 0.5, v[208:209] op_sel_hi:[1,0,1]
	v_pk_fma_f32 v[96:97], v[104:105], 0.5, v[194:195] op_sel_hi:[1,0,1]
	v_pk_fma_f32 v[94:95], v[102:103], 0.5, v[192:193] op_sel_hi:[1,0,1]
	global_store_dwordx4 v[98:99], v[78:81], off offset:576
	v_lshl_add_u64 v[82:83], v[82:83], 0, v[148:149]
	v_pk_fma_f32 v[76:77], v[76:77], 0.5, v[140:141] op_sel_hi:[1,0,1]
	v_pk_fma_f32 v[80:81], v[88:89], 0.5, v[222:223] op_sel_hi:[1,0,1]
	v_pk_fma_f32 v[78:79], v[86:87], 0.5, v[220:221] op_sel_hi:[1,0,1]
	v_pk_fma_f32 v[74:75], v[74:75], 0.5, v[138:139] op_sel_hi:[1,0,1]
	v_pk_fma_f32 v[72:73], v[72:73], 0.5, v[136:137] op_sel_hi:[1,0,1]
	v_pk_fma_f32 v[70:71], v[70:71], 0.5, v[134:135] op_sel_hi:[1,0,1]
	v_pk_fma_f32 v[68:69], v[68:69], 0.5, v[132:133] op_sel_hi:[1,0,1]
	v_pk_fma_f32 v[66:67], v[66:67], 0.5, v[130:131] op_sel_hi:[1,0,1]
	global_store_dwordx4 v[160:161], v[126:129], off
	global_store_dwordx4 v[160:161], v[122:125], off offset:64
	global_store_dwordx4 v[114:115], v[110:113], off
	global_store_dwordx4 v[114:115], v[106:109], off offset:64
	global_store_dwordx4 v[98:99], v[94:97], off
	global_store_dwordx4 v[98:99], v[90:93], off offset:64
	global_store_dwordx4 v[82:83], v[78:81], off
	global_store_dwordx4 v[82:83], v[74:77], off offset:64
	global_store_dwordx4 v[82:83], v[70:73], off offset:512
	global_store_dwordx4 v[82:83], v[66:69], off offset:576
	s_mov_b64 s[22:23], 0x80000
	v_lshl_add_u64 v[130:131], v[152:153], 0, s[22:23]
	s_mov_b64 s[22:23], 0x90000
	v_lshl_add_u64 v[132:133], v[152:153], 0, s[22:23]
	s_mov_b64 s[22:23], 0xa0000
	v_lshl_add_u64 v[134:135], v[152:153], 0, s[22:23]
	s_mov_b64 s[22:23], 0xb0000
	v_lshl_add_u64 v[136:137], v[152:153], 0, s[22:23]
	v_lshl_add_u64 v[78:79], v[150:151], 0, v[130:131]
	v_lshl_add_u64 v[94:95], v[150:151], 0, v[132:133]
	v_lshl_add_u64 v[110:111], v[150:151], 0, v[134:135]
	v_lshl_add_u64 v[126:127], v[150:151], 0, v[136:137]
	global_load_dwordx4 v[66:69], v[78:79], off
	global_load_dwordx4 v[70:73], v[78:79], off offset:64
	global_load_dwordx4 v[74:77], v[78:79], off offset:512
	v_lshl_add_u64 v[130:131], s[14:15], 0, v[130:131]
	global_load_dwordx4 v[78:81], v[78:79], off offset:576
	s_nop 0
	global_load_dwordx4 v[82:85], v[94:95], off
	global_load_dwordx4 v[86:89], v[94:95], off offset:64
	global_load_dwordx4 v[90:93], v[94:95], off offset:512
	v_lshl_add_u64 v[132:133], s[14:15], 0, v[132:133]
	global_load_dwordx4 v[94:97], v[94:95], off offset:576
	s_nop 0
	global_load_dwordx4 v[98:101], v[110:111], off
	global_load_dwordx4 v[102:105], v[110:111], off offset:64
	global_load_dwordx4 v[106:109], v[110:111], off offset:512
	v_lshl_add_u64 v[134:135], s[14:15], 0, v[134:135]
	global_load_dwordx4 v[110:113], v[110:111], off offset:576
	s_nop 0
	global_load_dwordx4 v[114:117], v[126:127], off
	global_load_dwordx4 v[118:121], v[126:127], off offset:64
	global_load_dwordx4 v[122:125], v[126:127], off offset:512
	s_nop 0
	global_load_dwordx4 v[126:129], v[126:127], off offset:576
	v_lshl_add_u64 v[136:137], s[14:15], 0, v[136:137]
	v_lshl_add_u64 v[130:131], v[130:131], 0, v[148:149]
	v_lshl_add_u64 v[132:133], v[132:133], 0, v[148:149]
	v_lshl_add_u64 v[134:135], v[134:135], 0, v[148:149]
	v_lshl_add_u64 v[136:137], v[136:137], 0, v[148:149]
	s_waitcnt vmcnt(0) lgkmcnt(0)
	v_pk_fma_f32 v[64:65], v[64:65], 0.5, v[68:69] op_sel_hi:[1,0,1]
	v_pk_fma_f32 v[62:63], v[62:63], 0.5, v[66:67] op_sel_hi:[1,0,1]
	v_pk_fma_f32 v[60:61], v[60:61], 0.5, v[72:73] op_sel_hi:[1,0,1]
	v_pk_fma_f32 v[58:59], v[58:59], 0.5, v[70:71] op_sel_hi:[1,0,1]
	v_pk_fma_f32 v[44:45], v[44:45], 0.5, v[76:77] op_sel_hi:[1,0,1]
	v_pk_fma_f32 v[42:43], v[42:43], 0.5, v[74:75] op_sel_hi:[1,0,1]
	v_pk_fma_f32 v[36:37], v[36:37], 0.5, v[80:81] op_sel_hi:[1,0,1]
	v_pk_fma_f32 v[34:35], v[34:35], 0.5, v[78:79] op_sel_hi:[1,0,1]
	v_pk_fma_f32 v[56:57], v[56:57], 0.5, v[84:85] op_sel_hi:[1,0,1]
	v_pk_fma_f32 v[54:55], v[54:55], 0.5, v[82:83] op_sel_hi:[1,0,1]
	v_pk_fma_f32 v[52:53], v[52:53], 0.5, v[88:89] op_sel_hi:[1,0,1]
	v_pk_fma_f32 v[50:51], v[50:51], 0.5, v[86:87] op_sel_hi:[1,0,1]
	v_pk_fma_f32 v[28:29], v[28:29], 0.5, v[92:93] op_sel_hi:[1,0,1]
	v_pk_fma_f32 v[26:27], v[26:27], 0.5, v[90:91] op_sel_hi:[1,0,1]
	v_pk_fma_f32 v[24:25], v[24:25], 0.5, v[96:97] op_sel_hi:[1,0,1]
	v_pk_fma_f32 v[22:23], v[22:23], 0.5, v[94:95] op_sel_hi:[1,0,1]
	v_pk_fma_f32 v[48:49], v[48:49], 0.5, v[100:101] op_sel_hi:[1,0,1]
	v_pk_fma_f32 v[46:47], v[46:47], 0.5, v[98:99] op_sel_hi:[1,0,1]
	v_pk_fma_f32 v[40:41], v[40:41], 0.5, v[104:105] op_sel_hi:[1,0,1]
	v_pk_fma_f32 v[38:39], v[38:39], 0.5, v[102:103] op_sel_hi:[1,0,1]
	v_pk_fma_f32 v[14:15], v[14:15], 0.5, v[108:109] op_sel_hi:[1,0,1]
	v_pk_fma_f32 v[12:13], v[12:13], 0.5, v[106:107] op_sel_hi:[1,0,1]
	v_pk_fma_f32 v[10:11], v[10:11], 0.5, v[112:113] op_sel_hi:[1,0,1]
	v_pk_fma_f32 v[8:9], v[8:9], 0.5, v[110:111] op_sel_hi:[1,0,1]
	v_pk_fma_f32 v[32:33], v[32:33], 0.5, v[116:117] op_sel_hi:[1,0,1]
	v_pk_fma_f32 v[30:31], v[30:31], 0.5, v[114:115] op_sel_hi:[1,0,1]
	v_pk_fma_f32 v[20:21], v[20:21], 0.5, v[120:121] op_sel_hi:[1,0,1]
	v_pk_fma_f32 v[18:19], v[18:19], 0.5, v[118:119] op_sel_hi:[1,0,1]
	v_pk_fma_f32 v[6:7], v[6:7], 0.5, v[124:125] op_sel_hi:[1,0,1]
	v_pk_fma_f32 v[4:5], v[4:5], 0.5, v[122:123] op_sel_hi:[1,0,1]
	v_pk_fma_f32 v[2:3], v[2:3], 0.5, v[128:129] op_sel_hi:[1,0,1]
	v_pk_fma_f32 v[0:1], v[0:1], 0.5, v[126:127] op_sel_hi:[1,0,1]
	global_store_dwordx4 v[130:131], v[62:65], off
	global_store_dwordx4 v[130:131], v[58:61], off offset:64
	global_store_dwordx4 v[130:131], v[42:45], off offset:512
	global_store_dwordx4 v[130:131], v[34:37], off offset:576
	global_store_dwordx4 v[132:133], v[54:57], off
	global_store_dwordx4 v[132:133], v[50:53], off offset:64
	global_store_dwordx4 v[132:133], v[26:29], off offset:512
	global_store_dwordx4 v[132:133], v[22:25], off offset:576
	global_store_dwordx4 v[134:135], v[46:49], off
	global_store_dwordx4 v[134:135], v[38:41], off offset:64
	global_store_dwordx4 v[134:135], v[12:15], off offset:512
	global_store_dwordx4 v[134:135], v[8:11], off offset:576
	global_store_dwordx4 v[136:137], v[30:33], off
	global_store_dwordx4 v[136:137], v[18:21], off offset:64
	global_store_dwordx4 v[136:137], v[4:7], off offset:512
	global_store_dwordx4 v[136:137], v[0:3], off offset:576
	s_and_b64 vcc, exec, s[38:39]
	s_mov_b32 s12, s82
	s_mov_b32 s2, s83
	s_mov_b64 s[28:29], s[18:19]
	s_mov_b64 s[22:23], s[16:17]
	s_mov_b32 s86, 0x38c0000
	s_cbranch_vccz .LBB0_122
	s_waitcnt vmcnt(0)
	s_cmpk_gt_u32 s48, 0xff
	s_cbranch_scc1 .LBB0_137
	s_barrier

.LBB0_146:
	s_ashr_i32 s29, s28, 31
	v_cmp_lt_i64_e32 vcc, s[22:23], v[198:199]
	s_lshl_b64 s[22:23], s[28:29], 19
	s_add_u32 s40, s30, s22
	s_addc_u32 s41, s31, s23
	s_and_b64 s[22:23], vcc, exec
	s_cselect_b32 s12, s41, s19
	s_cselect_b32 s29, s40, s18
	s_ashr_i32 s9, s8, 31
	s_lshl_b64 s[22:23], s[8:9], 19
	s_add_u32 s42, s49, s22
	s_addc_u32 s43, s50, s23
	s_and_b64 s[22:23], vcc, exec
	s_cselect_b32 s9, s43, s17
	s_cselect_b32 s34, s42, s16
	s_add_u32 s61, s16, 0x100
	s_addc_u32 s79, s17, 0
	s_add_u32 s16, s18, 0x40080
	v_mov_b32_e32 v0, 0
	s_addc_u32 s17, s19, 0
	s_mov_b32 s82, -2
	v_mov_b32_e32 v1, v0
	v_mov_b32_e32 v2, v0
	v_mov_b32_e32 v3, v0
	v_mov_b32_e32 v8, v0
	v_mov_b32_e32 v9, v0
	v_mov_b32_e32 v10, v0
	v_mov_b32_e32 v11, v0
	v_mov_b32_e32 v18, v0
	v_mov_b32_e32 v19, v0
	v_mov_b32_e32 v20, v0
	v_mov_b32_e32 v21, v0
	v_mov_b32_e32 v26, v0
	v_mov_b32_e32 v27, v0
	v_mov_b32_e32 v28, v0
	v_mov_b32_e32 v29, v0
	s_waitcnt lgkmcnt(0)
	v_mov_b32_e32 v34, v0
	v_mov_b32_e32 v35, v0
	v_mov_b32_e32 v36, v0
	v_mov_b32_e32 v37, v0
	v_mov_b32_e32 v42, v0
	v_mov_b32_e32 v43, v0
	v_mov_b32_e32 v44, v0
	v_mov_b32_e32 v45, v0
	v_mov_b32_e32 v50, v0
	v_mov_b32_e32 v51, v0
	v_mov_b32_e32 v52, v0
	v_mov_b32_e32 v53, v0
	v_mov_b32_e32 v58, v0
	v_mov_b32_e32 v59, v0
	v_mov_b32_e32 v60, v0
	v_mov_b32_e32 v61, v0
	v_mov_b32_e32 v4, v0
	v_mov_b32_e32 v5, v0
	v_mov_b32_e32 v6, v0
	v_mov_b32_e32 v7, v0
	v_mov_b32_e32 v12, v0
	v_mov_b32_e32 v13, v0
	v_mov_b32_e32 v14, v0
	v_mov_b32_e32 v15, v0
	v_mov_b32_e32 v22, v0
	v_mov_b32_e32 v23, v0
	v_mov_b32_e32 v24, v0
	v_mov_b32_e32 v25, v0
	v_mov_b32_e32 v30, v0
	v_mov_b32_e32 v31, v0
	v_mov_b32_e32 v32, v0
	v_mov_b32_e32 v33, v0
	v_mov_b32_e32 v38, v0
	v_mov_b32_e32 v39, v0
	v_mov_b32_e32 v40, v0
	v_mov_b32_e32 v41, v0
	v_mov_b32_e32 v46, v0
	v_mov_b32_e32 v47, v0
	v_mov_b32_e32 v48, v0
	v_mov_b32_e32 v49, v0
	v_mov_b32_e32 v54, v0
	v_mov_b32_e32 v55, v0
	v_mov_b32_e32 v56, v0
	v_mov_b32_e32 v57, v0
	v_mov_b32_e32 v62, v0
	v_mov_b32_e32 v63, v0
	v_mov_b32_e32 v64, v0
	v_mov_b32_e32 v65, v0
	v_mov_b32_e32 v66, v0
	v_mov_b32_e32 v67, v0
	v_mov_b32_e32 v68, v0
	v_mov_b32_e32 v69, v0
	v_mov_b32_e32 v74, v0
	v_mov_b32_e32 v75, v0
	v_mov_b32_e32 v76, v0
	v_mov_b32_e32 v77, v0
	v_mov_b32_e32 v82, v0
	v_mov_b32_e32 v83, v0
	v_mov_b32_e32 v84, v0
	v_mov_b32_e32 v85, v0
	v_mov_b32_e32 v90, v0
	v_mov_b32_e32 v91, v0
	v_mov_b32_e32 v92, v0
	v_mov_b32_e32 v93, v0
	v_mov_b32_e32 v98, v0
	v_mov_b32_e32 v99, v0
	v_mov_b32_e32 v100, v0
	v_mov_b32_e32 v101, v0
	v_mov_b32_e32 v106, v0
	v_mov_b32_e32 v107, v0
	v_mov_b32_e32 v108, v0
	v_mov_b32_e32 v109, v0
	v_mov_b32_e32 v114, v0
	v_mov_b32_e32 v115, v0
	v_mov_b32_e32 v116, v0
	v_mov_b32_e32 v117, v0
	v_mov_b32_e32 v122, v0
	v_mov_b32_e32 v123, v0
	v_mov_b32_e32 v124, v0
	v_mov_b32_e32 v125, v0
	v_mov_b32_e32 v70, v0
	v_mov_b32_e32 v71, v0
	v_mov_b32_e32 v72, v0
	v_mov_b32_e32 v73, v0
	v_mov_b32_e32 v78, v0
	v_mov_b32_e32 v79, v0
	v_mov_b32_e32 v80, v0
	v_mov_b32_e32 v81, v0
	v_mov_b32_e32 v86, v0
	v_mov_b32_e32 v87, v0
	v_mov_b32_e32 v88, v0
	v_mov_b32_e32 v89, v0
	v_mov_b32_e32 v94, v0
	v_mov_b32_e32 v95, v0
	v_mov_b32_e32 v96, v0
	v_mov_b32_e32 v97, v0
	v_mov_b32_e32 v102, v0
	v_mov_b32_e32 v103, v0
	v_mov_b32_e32 v104, v0
	v_mov_b32_e32 v105, v0
	v_mov_b32_e32 v110, v0
	v_mov_b32_e32 v111, v0
	v_mov_b32_e32 v112, v0
	v_mov_b32_e32 v113, v0
	v_mov_b32_e32 v118, v0
	v_mov_b32_e32 v119, v0
	v_mov_b32_e32 v120, v0
	v_mov_b32_e32 v121, v0
	v_mov_b32_e32 v126, v0
	v_mov_b32_e32 v127, v0
	v_mov_b32_e32 v128, v0
	v_mov_b32_e32 v129, v0
	v_readfirstlane_b32 s98, v228
	s_lshr_b32 s98, s98, 8
	s_cmp_lg_u32 s98, 0
	s_cbranch_scc0 .Lprio_skip_1
	s_setprio 1
.Lprio_skip_1:
.LBB0_147:
	s_add_u32 s18, s16, 0xfffc0080
	s_addc_u32 s19, s17, -1
	s_add_i32 s83, 0, 0x10000
	v_add_u32_e32 v140, s83, v143
	ds_read_b128 v[146:149], v140
	ds_read_b128 v[150:153], v140 offset:1024
	ds_read_b128 v[154:157], v140 offset:2048
	ds_read_b128 v[158:161], v140 offset:3072
	s_cmp_eq_u32 s82, 12
	s_cselect_b32 s23, s12, s19
	s_cselect_b32 s22, s29, s18
	s_cselect_b32 s19, s9, s79
	s_cselect_b32 s18, s34, s61
	v_lshl_add_u64 v[140:141], s[16:17], 0, v[138:139]
	s_add_i32 m0, s15, 0xc000
	ds_read_b128 v[162:165], v145
	ds_read_b128 v[166:169], v145 offset:1024
	ds_read_b128 v[170:173], v145 offset:2048
	ds_read_b128 v[174:177], v145 offset:3072
	ds_read_b128 v[178:181], v145 offset:4096
	ds_read_b128 v[182:185], v145 offset:5120
	ds_read_b128 v[186:189], v145 offset:6144
	ds_read_b128 v[190:193], v145 offset:7168
	global_load_lds_dwordx4 v[140:141], off
	v_lshl_add_u64 v[140:141], s[16:17], 0, v[136:137]
	s_add_i32 m0, s15, 0xe000
	s_nop 0
	global_load_lds_dwordx4 v[140:141], off
	s_waitcnt lgkmcnt(8)
	s_barrier
	s_waitcnt lgkmcnt(0)
	s_waitcnt lgkmcnt(0)
	v_mfma_f32_16x16x32_bf16 v[126:129], v[146:149], v[162:165], v[126:129]
	v_mfma_f32_16x16x32_bf16 v[118:121], v[154:157], v[162:165], v[118:121]
	v_mfma_f32_16x16x32_bf16 v[110:113], v[146:149], v[170:173], v[110:113]
	v_mfma_f32_16x16x32_bf16 v[102:105], v[154:157], v[170:173], v[102:105]
	v_mfma_f32_16x16x32_bf16 v[94:97], v[146:149], v[178:181], v[94:97]
	v_mfma_f32_16x16x32_bf16 v[86:89], v[154:157], v[178:181], v[86:89]
	v_mfma_f32_16x16x32_bf16 v[78:81], v[146:149], v[186:189], v[78:81]
	v_mfma_f32_16x16x32_bf16 v[70:73], v[154:157], v[186:189], v[70:73]
	v_mfma_f32_16x16x32_bf16 v[126:129], v[150:153], v[166:169], v[126:129]
	v_mfma_f32_16x16x32_bf16 v[118:121], v[158:161], v[166:169], v[118:121]
	v_mfma_f32_16x16x32_bf16 v[110:113], v[150:153], v[174:177], v[110:113]
	v_mfma_f32_16x16x32_bf16 v[102:105], v[158:161], v[174:177], v[102:105]
	v_mfma_f32_16x16x32_bf16 v[94:97], v[150:153], v[182:185], v[94:97]
	v_mfma_f32_16x16x32_bf16 v[86:89], v[158:161], v[182:185], v[86:89]
	v_mfma_f32_16x16x32_bf16 v[78:81], v[150:153], v[190:193], v[78:81]
	v_mfma_f32_16x16x32_bf16 v[70:73], v[158:161], v[190:193], v[70:73]
	s_barrier
	s_add_i32 s86, 0, 0x14000
	v_add_u32_e32 v140, s86, v143
	s_add_i32 s83, s83, s51
	ds_read_b128 v[194:197], v140
	ds_read_b128 v[208:211], v140 offset:1024
	ds_read_b128 v[212:215], v140 offset:2048
	ds_read_b128 v[216:219], v140 offset:3072
	v_lshl_add_u64 v[140:141], s[18:19], 0, v[16:17]
	s_mov_b32 m0, s83
	v_lshl_add_u64 v[220:221], s[18:19], 0, v[130:131]
	global_load_lds_dwordx4 v[140:141], off
	s_add_i32 m0, s83, 0x2000
	s_nop 0
	global_load_lds_dwordx4 v[220:221], off
	s_barrier
	s_waitcnt lgkmcnt(0)
	s_waitcnt lgkmcnt(0)
	v_mfma_f32_16x16x32_bf16 v[122:125], v[194:197], v[162:165], v[122:125]
	v_mfma_f32_16x16x32_bf16 v[114:117], v[212:215], v[162:165], v[114:117]
	v_mfma_f32_16x16x32_bf16 v[106:109], v[194:197], v[170:173], v[106:109]
	v_mfma_f32_16x16x32_bf16 v[98:101], v[212:215], v[170:173], v[98:101]
	v_mfma_f32_16x16x32_bf16 v[90:93], v[194:197], v[178:181], v[90:93]
	v_mfma_f32_16x16x32_bf16 v[82:85], v[212:215], v[178:181], v[82:85]
	v_mfma_f32_16x16x32_bf16 v[74:77], v[194:197], v[186:189], v[74:77]
	v_mfma_f32_16x16x32_bf16 v[66:69], v[212:215], v[186:189], v[66:69]
	v_mfma_f32_16x16x32_bf16 v[122:125], v[208:211], v[166:169], v[122:125]
	v_mfma_f32_16x16x32_bf16 v[114:117], v[216:219], v[166:169], v[114:117]
	v_mfma_f32_16x16x32_bf16 v[106:109], v[208:211], v[174:177], v[106:109]
	v_mfma_f32_16x16x32_bf16 v[98:101], v[216:219], v[174:177], v[98:101]
	v_mfma_f32_16x16x32_bf16 v[90:93], v[208:211], v[182:185], v[90:93]
	v_mfma_f32_16x16x32_bf16 v[82:85], v[216:219], v[182:185], v[82:85]
	v_mfma_f32_16x16x32_bf16 v[74:77], v[208:211], v[190:193], v[74:77]
	v_mfma_f32_16x16x32_bf16 v[66:69], v[216:219], v[190:193], v[66:69]
	s_mov_b32 m0, s15
	v_lshl_add_u64 v[222:223], s[22:23], 0, v[134:135]
	s_barrier
	ds_read_b128 v[162:165], v145 offset:16384
	ds_read_b128 v[166:169], v145 offset:17408
	ds_read_b128 v[170:173], v145 offset:18432
	ds_read_b128 v[174:177], v145 offset:19456
	ds_read_b128 v[178:181], v145 offset:20480
	ds_read_b128 v[182:185], v145 offset:21504
	ds_read_b128 v[186:189], v145 offset:22528
	ds_read_b128 v[190:193], v145 offset:23552
	global_load_lds_dwordx4 v[222:223], off
	v_lshl_add_u64 v[224:225], s[22:23], 0, v[132:133]
	s_mov_b32 m0, s54
	s_nop 0
	global_load_lds_dwordx4 v[224:225], off
	s_barrier
	s_waitcnt lgkmcnt(0)
	s_waitcnt lgkmcnt(0)
	v_mfma_f32_16x16x32_bf16 v[62:65], v[146:149], v[162:165], v[62:65]
	v_mfma_f32_16x16x32_bf16 v[54:57], v[154:157], v[162:165], v[54:57]
	v_mfma_f32_16x16x32_bf16 v[46:49], v[146:149], v[170:173], v[46:49]
	v_mfma_f32_16x16x32_bf16 v[38:41], v[154:157], v[170:173], v[38:41]
	v_mfma_f32_16x16x32_bf16 v[30:33], v[146:149], v[178:181], v[30:33]
	v_mfma_f32_16x16x32_bf16 v[22:25], v[154:157], v[178:181], v[22:25]
	v_mfma_f32_16x16x32_bf16 v[12:15], v[146:149], v[186:189], v[12:15]
	v_mfma_f32_16x16x32_bf16 v[4:7], v[154:157], v[186:189], v[4:7]
	v_mfma_f32_16x16x32_bf16 v[62:65], v[150:153], v[166:169], v[62:65]
	v_mfma_f32_16x16x32_bf16 v[54:57], v[158:161], v[166:169], v[54:57]
	v_mfma_f32_16x16x32_bf16 v[46:49], v[150:153], v[174:177], v[46:49]
	v_mfma_f32_16x16x32_bf16 v[38:41], v[158:161], v[174:177], v[38:41]
	v_mfma_f32_16x16x32_bf16 v[30:33], v[150:153], v[182:185], v[30:33]
	v_mfma_f32_16x16x32_bf16 v[22:25], v[158:161], v[182:185], v[22:25]
	v_mfma_f32_16x16x32_bf16 v[12:15], v[150:153], v[190:193], v[12:15]
	v_mfma_f32_16x16x32_bf16 v[4:7], v[158:161], v[190:193], v[4:7]
	s_barrier
	s_add_u32 s84, s18, 0x40000
	s_addc_u32 s85, s19, 0
	s_add_i32 s83, s86, s51
	v_lshl_add_u64 v[146:147], s[84:85], 0, v[16:17]
	s_mov_b32 m0, s83
	s_nop 0
	global_load_lds_dwordx4 v[146:147], off
	v_lshl_add_u64 v[146:147], s[84:85], 0, v[130:131]
	s_add_i32 m0, s83, 0x2000
	s_nop 0
	global_load_lds_dwordx4 v[146:147], off
	s_waitcnt vmcnt(6)
	s_barrier
	v_mfma_f32_16x16x32_bf16 v[58:61], v[194:197], v[162:165], v[58:61]
	v_mfma_f32_16x16x32_bf16 v[50:53], v[212:215], v[162:165], v[50:53]
	v_mfma_f32_16x16x32_bf16 v[42:45], v[194:197], v[170:173], v[42:45]
	v_mfma_f32_16x16x32_bf16 v[34:37], v[212:215], v[170:173], v[34:37]
	v_mfma_f32_16x16x32_bf16 v[26:29], v[194:197], v[178:181], v[26:29]
	v_mfma_f32_16x16x32_bf16 v[18:21], v[212:215], v[178:181], v[18:21]
	v_mfma_f32_16x16x32_bf16 v[8:11], v[194:197], v[186:189], v[8:11]
	v_mfma_f32_16x16x32_bf16 v[0:3], v[212:215], v[186:189], v[0:3]
	v_mfma_f32_16x16x32_bf16 v[58:61], v[208:211], v[166:169], v[58:61]
	v_mfma_f32_16x16x32_bf16 v[50:53], v[216:219], v[166:169], v[50:53]
	v_mfma_f32_16x16x32_bf16 v[42:45], v[208:211], v[174:177], v[42:45]
	v_mfma_f32_16x16x32_bf16 v[34:37], v[216:219], v[174:177], v[34:37]
	v_mfma_f32_16x16x32_bf16 v[26:29], v[208:211], v[182:185], v[26:29]
	v_mfma_f32_16x16x32_bf16 v[18:21], v[216:219], v[182:185], v[18:21]
	v_mfma_f32_16x16x32_bf16 v[8:11], v[208:211], v[190:193], v[8:11]
	v_mfma_f32_16x16x32_bf16 v[0:3], v[216:219], v[190:193], v[0:3]
	s_add_i32 s83, 0, 0x18000
	v_add_u32_e32 v158, s83, v143
	s_barrier
	ds_read_b128 v[146:149], v158
	ds_read_b128 v[150:153], v158 offset:1024
	ds_read_b128 v[154:157], v158 offset:2048
	ds_read_b128 v[158:161], v158 offset:3072
	s_add_u32 s22, s22, 0x40000
	s_addc_u32 s23, s23, 0
	s_mov_b32 m0, s55
	v_lshl_add_u64 v[194:195], s[22:23], 0, v[134:135]
	ds_read_b128 v[162:165], v145 offset:32768
	ds_read_b128 v[166:169], v145 offset:33792
	ds_read_b128 v[170:173], v145 offset:34816
	ds_read_b128 v[174:177], v145 offset:35840
	ds_read_b128 v[178:181], v145 offset:36864
	ds_read_b128 v[182:185], v145 offset:37888
	ds_read_b128 v[186:189], v145 offset:38912
	ds_read_b128 v[190:193], v145 offset:39936
	global_load_lds_dwordx4 v[194:195], off
	v_lshl_add_u64 v[194:195], s[22:23], 0, v[132:133]
	s_mov_b32 m0, s56
	s_nop 0
	global_load_lds_dwordx4 v[194:195], off
	s_waitcnt lgkmcnt(8)
	s_barrier
	s_waitcnt lgkmcnt(0)
	s_waitcnt lgkmcnt(0)
	v_mfma_f32_16x16x32_bf16 v[126:129], v[146:149], v[162:165], v[126:129]
	v_mfma_f32_16x16x32_bf16 v[118:121], v[154:157], v[162:165], v[118:121]
	v_mfma_f32_16x16x32_bf16 v[110:113], v[146:149], v[170:173], v[110:113]
	v_mfma_f32_16x16x32_bf16 v[102:105], v[154:157], v[170:173], v[102:105]
	v_mfma_f32_16x16x32_bf16 v[94:97], v[146:149], v[178:181], v[94:97]
	v_mfma_f32_16x16x32_bf16 v[86:89], v[154:157], v[178:181], v[86:89]
	v_mfma_f32_16x16x32_bf16 v[78:81], v[146:149], v[186:189], v[78:81]
	v_mfma_f32_16x16x32_bf16 v[70:73], v[154:157], v[186:189], v[70:73]
	v_mfma_f32_16x16x32_bf16 v[126:129], v[150:153], v[166:169], v[126:129]
	v_mfma_f32_16x16x32_bf16 v[118:121], v[158:161], v[166:169], v[118:121]
	v_mfma_f32_16x16x32_bf16 v[110:113], v[150:153], v[174:177], v[110:113]
	v_mfma_f32_16x16x32_bf16 v[102:105], v[158:161], v[174:177], v[102:105]
	v_mfma_f32_16x16x32_bf16 v[94:97], v[150:153], v[182:185], v[94:97]
	v_mfma_f32_16x16x32_bf16 v[86:89], v[158:161], v[182:185], v[86:89]
	v_mfma_f32_16x16x32_bf16 v[78:81], v[150:153], v[190:193], v[78:81]
	v_mfma_f32_16x16x32_bf16 v[70:73], v[158:161], v[190:193], v[70:73]
	s_barrier
	s_add_i32 s22, 0, 0x1c000
	s_add_i32 s23, s83, s51
	v_add_u32_e32 v216, s22, v143
	v_lshl_add_u64 v[140:141], v[140:141], 0, s[10:11]
	s_mov_b32 m0, s23
	ds_read_b128 v[194:197], v216
	ds_read_b128 v[208:211], v216 offset:1024
	ds_read_b128 v[212:215], v216 offset:2048
	ds_read_b128 v[216:219], v216 offset:3072
	global_load_lds_dwordx4 v[140:141], off
	v_lshl_add_u64 v[140:141], v[220:221], 0, s[10:11]
	s_add_i32 m0, s23, 0x2000
	s_nop 0
	global_load_lds_dwordx4 v[140:141], off
	s_barrier
	s_waitcnt lgkmcnt(0)
	s_waitcnt lgkmcnt(0)
	v_mfma_f32_16x16x32_bf16 v[122:125], v[194:197], v[162:165], v[122:125]
	v_mfma_f32_16x16x32_bf16 v[114:117], v[212:215], v[162:165], v[114:117]
	v_mfma_f32_16x16x32_bf16 v[106:109], v[194:197], v[170:173], v[106:109]
	v_mfma_f32_16x16x32_bf16 v[98:101], v[212:215], v[170:173], v[98:101]
	v_mfma_f32_16x16x32_bf16 v[90:93], v[194:197], v[178:181], v[90:93]
	v_mfma_f32_16x16x32_bf16 v[82:85], v[212:215], v[178:181], v[82:85]
	v_mfma_f32_16x16x32_bf16 v[74:77], v[194:197], v[186:189], v[74:77]
	v_mfma_f32_16x16x32_bf16 v[66:69], v[212:215], v[186:189], v[66:69]
	v_mfma_f32_16x16x32_bf16 v[122:125], v[208:211], v[166:169], v[122:125]
	v_mfma_f32_16x16x32_bf16 v[114:117], v[216:219], v[166:169], v[114:117]
	v_mfma_f32_16x16x32_bf16 v[106:109], v[208:211], v[174:177], v[106:109]
	v_mfma_f32_16x16x32_bf16 v[98:101], v[216:219], v[174:177], v[98:101]
	v_mfma_f32_16x16x32_bf16 v[90:93], v[208:211], v[182:185], v[90:93]
	v_mfma_f32_16x16x32_bf16 v[82:85], v[216:219], v[182:185], v[82:85]
	v_mfma_f32_16x16x32_bf16 v[74:77], v[208:211], v[190:193], v[74:77]
	v_mfma_f32_16x16x32_bf16 v[66:69], v[216:219], v[190:193], v[66:69]
	s_mov_b32 m0, s57
	v_lshl_add_u64 v[140:141], v[222:223], 0, s[10:11]
	s_barrier
	ds_read_b128 v[162:165], v145 offset:49152
	ds_read_b128 v[166:169], v145 offset:50176
	ds_read_b128 v[170:173], v145 offset:51200
	ds_read_b128 v[174:177], v145 offset:52224
	ds_read_b128 v[178:181], v145 offset:53248
	ds_read_b128 v[182:185], v145 offset:54272
	ds_read_b128 v[186:189], v145 offset:55296
	ds_read_b128 v[190:193], v145 offset:56320
	global_load_lds_dwordx4 v[140:141], off
	v_lshl_add_u64 v[140:141], v[224:225], 0, s[10:11]
	s_mov_b32 m0, s58
	s_nop 0
	global_load_lds_dwordx4 v[140:141], off
	s_barrier
	s_waitcnt lgkmcnt(0)
	s_waitcnt lgkmcnt(0)
	v_mfma_f32_16x16x32_bf16 v[62:65], v[146:149], v[162:165], v[62:65]
	v_mfma_f32_16x16x32_bf16 v[54:57], v[154:157], v[162:165], v[54:57]
	v_mfma_f32_16x16x32_bf16 v[46:49], v[146:149], v[170:173], v[46:49]
	v_mfma_f32_16x16x32_bf16 v[38:41], v[154:157], v[170:173], v[38:41]
	v_mfma_f32_16x16x32_bf16 v[30:33], v[146:149], v[178:181], v[30:33]
	v_mfma_f32_16x16x32_bf16 v[22:25], v[154:157], v[178:181], v[22:25]
	v_mfma_f32_16x16x32_bf16 v[12:15], v[146:149], v[186:189], v[12:15]
	v_mfma_f32_16x16x32_bf16 v[4:7], v[154:157], v[186:189], v[4:7]
	v_mfma_f32_16x16x32_bf16 v[62:65], v[150:153], v[166:169], v[62:65]
	v_mfma_f32_16x16x32_bf16 v[54:57], v[158:161], v[166:169], v[54:57]
	v_mfma_f32_16x16x32_bf16 v[46:49], v[150:153], v[174:177], v[46:49]
	v_mfma_f32_16x16x32_bf16 v[38:41], v[158:161], v[174:177], v[38:41]
	v_mfma_f32_16x16x32_bf16 v[30:33], v[150:153], v[182:185], v[30:33]
	v_mfma_f32_16x16x32_bf16 v[22:25], v[158:161], v[182:185], v[22:25]
	v_mfma_f32_16x16x32_bf16 v[12:15], v[150:153], v[190:193], v[12:15]
	v_mfma_f32_16x16x32_bf16 v[4:7], v[158:161], v[190:193], v[4:7]
	s_barrier
	s_add_u32 s18, s18, 0x40080
	s_addc_u32 s19, s19, 0
	s_add_i32 s22, s22, s51
	v_lshl_add_u64 v[140:141], s[18:19], 0, v[16:17]
	s_mov_b32 m0, s22
	s_nop 0
	global_load_lds_dwordx4 v[140:141], off
	v_lshl_add_u64 v[140:141], s[18:19], 0, v[130:131]
	s_add_i32 m0, s22, 0x2000
	s_nop 0
	global_load_lds_dwordx4 v[140:141], off
	s_waitcnt vmcnt(6)
	s_barrier
	v_mfma_f32_16x16x32_bf16 v[58:61], v[194:197], v[162:165], v[58:61]
	v_mfma_f32_16x16x32_bf16 v[50:53], v[212:215], v[162:165], v[50:53]
	v_mfma_f32_16x16x32_bf16 v[42:45], v[194:197], v[170:173], v[42:45]
	v_mfma_f32_16x16x32_bf16 v[34:37], v[212:215], v[170:173], v[34:37]
	v_mfma_f32_16x16x32_bf16 v[26:29], v[194:197], v[178:181], v[26:29]
	v_mfma_f32_16x16x32_bf16 v[18:21], v[212:215], v[178:181], v[18:21]
	v_mfma_f32_16x16x32_bf16 v[8:11], v[194:197], v[186:189], v[8:11]
	v_mfma_f32_16x16x32_bf16 v[0:3], v[212:215], v[186:189], v[0:3]
	v_mfma_f32_16x16x32_bf16 v[58:61], v[208:211], v[166:169], v[58:61]
	v_mfma_f32_16x16x32_bf16 v[50:53], v[216:219], v[166:169], v[50:53]
	v_mfma_f32_16x16x32_bf16 v[42:45], v[208:211], v[174:177], v[42:45]
	v_mfma_f32_16x16x32_bf16 v[34:37], v[216:219], v[174:177], v[34:37]
	v_mfma_f32_16x16x32_bf16 v[26:29], v[208:211], v[182:185], v[26:29]
	v_mfma_f32_16x16x32_bf16 v[18:21], v[216:219], v[182:185], v[18:21]
	v_mfma_f32_16x16x32_bf16 v[8:11], v[208:211], v[190:193], v[8:11]
	v_mfma_f32_16x16x32_bf16 v[0:3], v[216:219], v[190:193], v[0:3]
	s_add_i32 s82, s82, 2
	s_add_u32 s61, s61, 0x100
	s_addc_u32 s79, s79, 0
	s_add_u32 s16, s16, 0x100
	s_addc_u32 s17, s17, 0
	s_cmp_gt_u32 s82, 13
	s_barrier
	s_cbranch_scc0 .LBB0_147
	v_mul_f32_e32 v147, 0xbfb8aa3b, v126
	v_exp_f32_e32 v147, v147
	v_lshl_or_b32 v148, s2, 7, v144
	v_lshl_add_u32 v146, s14, 8, v142
	v_ashrrev_i32_e32 v149, 31, v148
	v_add_f32_e32 v147, 1.0, v147
	v_rcp_f32_e32 v147, v147
	v_mov_b64_e32 v[140:141], s[94:95]
	v_mad_i64_i32 v[150:151], s[16:17], v146, s65, v[140:141]
	v_mul_f32_e32 v126, v126, v147
	v_mul_f32_e32 v122, v126, v122
	v_mul_f32_e32 v126, 0xbfb8aa3b, v127
	v_exp_f32_e32 v126, v126
	s_nop 0
	v_add_f32_e32 v126, 1.0, v126
	v_rcp_f32_e32 v126, v126
	s_nop 0
	v_mul_f32_e32 v126, v127, v126
	v_mul_f32_e32 v123, v126, v123
	v_mul_f32_e32 v126, 0xbfb8aa3b, v128
	v_exp_f32_e32 v126, v126
	s_nop 0
	v_add_f32_e32 v126, 1.0, v126
	v_rcp_f32_e32 v126, v126
	s_nop 0
	v_mul_f32_e32 v126, v128, v126
	v_mul_f32_e32 v124, v126, v124
	v_mul_f32_e32 v126, 0xbfb8aa3b, v129
	v_exp_f32_e32 v126, v126
	s_nop 0
	v_add_f32_e32 v126, 1.0, v126
	v_rcp_f32_e32 v126, v126
	s_nop 0
	v_mul_f32_e32 v126, v129, v126
	v_mul_f32_e32 v125, v126, v125
	v_mul_f32_e32 v126, 0xbfb8aa3b, v118
	v_exp_f32_e32 v126, v126
	s_nop 0
	v_add_f32_e32 v126, 1.0, v126
	v_rcp_f32_e32 v126, v126
	s_nop 0
	v_mul_f32_e32 v118, v118, v126
	v_mul_f32_e32 v118, v118, v114
	v_mul_f32_e32 v114, 0xbfb8aa3b, v119
	v_exp_f32_e32 v114, v114
	s_nop 0
	v_add_f32_e32 v114, 1.0, v114
	v_rcp_f32_e32 v114, v114
	s_nop 0
	v_mul_f32_e32 v114, v119, v114
	v_mul_f32_e32 v119, v114, v115
	v_mul_f32_e32 v114, 0xbfb8aa3b, v120
	v_exp_f32_e32 v114, v114
	v_cvt_pk_bf16_f32 v118, v118, v119
	s_nop 0
	v_add_f32_e32 v114, 1.0, v114
	v_rcp_f32_e32 v114, v114
	s_nop 0
	v_mul_f32_e32 v114, v120, v114
	v_mul_f32_e32 v126, v114, v116
	v_mul_f32_e32 v114, 0xbfb8aa3b, v121
	v_exp_f32_e32 v114, v114
	v_cvt_pk_bf16_f32 v116, v122, v123
	s_nop 0
	v_add_f32_e32 v114, 1.0, v114
	v_rcp_f32_e32 v114, v114
	s_nop 0
	v_mul_f32_e32 v114, v121, v114
	v_mul_f32_e32 v127, v114, v117
	v_lshlrev_b64 v[114:115], 1, v[148:149]
	v_lshl_add_u64 v[120:121], v[150:151], 0, v[114:115]
	v_cvt_pk_bf16_f32 v117, v124, v125
	v_cvt_pk_bf16_f32 v119, v126, v127
	global_store_dwordx4 v[120:121], v[116:119], off
	s_nop 1
	v_mul_f32_e32 v118, 0xbfb8aa3b, v110
	v_exp_f32_e32 v118, v118
	v_or_b32_e32 v116, 16, v146
	v_mad_i64_i32 v[116:117], s[16:17], v116, s65, v[140:141]
	v_add_f32_e32 v118, 1.0, v118
	v_rcp_f32_e32 v118, v118
	s_nop 0
	v_mul_f32_e32 v110, v110, v118
	v_mul_f32_e32 v106, v110, v106
	v_mul_f32_e32 v110, 0xbfb8aa3b, v111
	v_exp_f32_e32 v110, v110
	s_nop 0
	v_add_f32_e32 v110, 1.0, v110
	v_rcp_f32_e32 v110, v110
	s_nop 0
	v_mul_f32_e32 v110, v111, v110
	v_mul_f32_e32 v107, v110, v107
	v_mul_f32_e32 v110, 0xbfb8aa3b, v112
	v_exp_f32_e32 v110, v110
	s_nop 0
	v_add_f32_e32 v110, 1.0, v110
	v_rcp_f32_e32 v110, v110
	s_nop 0
	v_mul_f32_e32 v110, v112, v110
	v_mul_f32_e32 v108, v110, v108
	v_mul_f32_e32 v110, 0xbfb8aa3b, v113
	v_exp_f32_e32 v110, v110
	s_nop 0
	v_add_f32_e32 v110, 1.0, v110
	v_rcp_f32_e32 v110, v110
	s_nop 0
	v_mul_f32_e32 v110, v113, v110
	v_mul_f32_e32 v109, v110, v109
	v_mul_f32_e32 v110, 0xbfb8aa3b, v102
	v_exp_f32_e32 v110, v110
	s_nop 0
	v_add_f32_e32 v110, 1.0, v110
	v_rcp_f32_e32 v110, v110
	s_nop 0
	v_mul_f32_e32 v102, v102, v110
	v_mul_f32_e32 v110, v102, v98
	v_mul_f32_e32 v98, 0xbfb8aa3b, v103
	v_exp_f32_e32 v98, v98
	s_nop 0
	v_add_f32_e32 v98, 1.0, v98
	v_rcp_f32_e32 v98, v98
	s_nop 0
	v_mul_f32_e32 v98, v103, v98
	v_mul_f32_e32 v111, v98, v99
	v_mul_f32_e32 v98, 0xbfb8aa3b, v104
	v_exp_f32_e32 v98, v98
	v_lshl_add_u64 v[102:103], v[116:117], 0, v[114:115]
	v_cvt_pk_bf16_f32 v99, v108, v109
	v_add_f32_e32 v98, 1.0, v98
	v_rcp_f32_e32 v98, v98
	s_nop 0
	v_mul_f32_e32 v98, v104, v98
	v_mul_f32_e32 v104, v98, v100
	v_mul_f32_e32 v98, 0xbfb8aa3b, v105
	v_exp_f32_e32 v98, v98
	v_cvt_pk_bf16_f32 v100, v110, v111
	s_nop 0
	v_add_f32_e32 v98, 1.0, v98
	v_rcp_f32_e32 v98, v98
	s_nop 0
	v_mul_f32_e32 v98, v105, v98
	v_mul_f32_e32 v101, v98, v101
	v_cvt_pk_bf16_f32 v98, v106, v107
	v_cvt_pk_bf16_f32 v101, v104, v101
	global_store_dwordx4 v[102:103], v[98:101], off
	s_nop 1
	v_mul_f32_e32 v100, 0xbfb8aa3b, v94
	v_exp_f32_e32 v100, v100
	v_or_b32_e32 v98, 32, v146
	v_mad_i64_i32 v[98:99], s[16:17], v98, s65, v[140:141]
	v_add_f32_e32 v100, 1.0, v100
	v_rcp_f32_e32 v100, v100
	s_nop 0
	v_mul_f32_e32 v94, v94, v100
	v_mul_f32_e32 v90, v94, v90
	v_mul_f32_e32 v94, 0xbfb8aa3b, v95
	v_exp_f32_e32 v94, v94
	s_nop 0
	v_add_f32_e32 v94, 1.0, v94
	v_rcp_f32_e32 v94, v94
	s_nop 0
	v_mul_f32_e32 v94, v95, v94
	v_mul_f32_e32 v91, v94, v91
	v_mul_f32_e32 v94, 0xbfb8aa3b, v96
	v_exp_f32_e32 v94, v94
	s_nop 0
	v_add_f32_e32 v94, 1.0, v94
	v_rcp_f32_e32 v94, v94
	s_nop 0
	v_mul_f32_e32 v94, v96, v94
	v_mul_f32_e32 v92, v94, v92
	v_mul_f32_e32 v94, 0xbfb8aa3b, v97
	v_exp_f32_e32 v94, v94
	s_nop 0
	v_add_f32_e32 v94, 1.0, v94
	v_rcp_f32_e32 v94, v94
	s_nop 0
	v_mul_f32_e32 v94, v97, v94
	v_mul_f32_e32 v93, v94, v93
	v_mul_f32_e32 v94, 0xbfb8aa3b, v86
	v_exp_f32_e32 v94, v94
	s_nop 0
	v_add_f32_e32 v94, 1.0, v94
	v_rcp_f32_e32 v94, v94
	s_nop 0
	v_mul_f32_e32 v86, v86, v94
	v_mul_f32_e32 v94, v86, v82
	v_mul_f32_e32 v82, 0xbfb8aa3b, v87
	v_exp_f32_e32 v82, v82
	s_nop 0
	v_add_f32_e32 v82, 1.0, v82
	v_rcp_f32_e32 v82, v82
	s_nop 0
	v_mul_f32_e32 v82, v87, v82
	v_mul_f32_e32 v95, v82, v83
	v_mul_f32_e32 v82, 0xbfb8aa3b, v88
	v_exp_f32_e32 v82, v82
	v_lshl_add_u64 v[86:87], v[98:99], 0, v[114:115]
	v_cvt_pk_bf16_f32 v83, v92, v93
	v_add_f32_e32 v82, 1.0, v82
	v_rcp_f32_e32 v82, v82
	s_nop 0
	v_mul_f32_e32 v82, v88, v82
	v_mul_f32_e32 v88, v82, v84
	v_mul_f32_e32 v82, 0xbfb8aa3b, v89
	v_exp_f32_e32 v82, v82
	v_cvt_pk_bf16_f32 v84, v94, v95
	s_nop 0
	v_add_f32_e32 v82, 1.0, v82
	v_rcp_f32_e32 v82, v82
	s_nop 0
	v_mul_f32_e32 v82, v89, v82
	v_mul_f32_e32 v85, v82, v85
	v_cvt_pk_bf16_f32 v82, v90, v91
	v_cvt_pk_bf16_f32 v85, v88, v85
	global_store_dwordx4 v[86:87], v[82:85], off
	s_nop 1
	v_mul_f32_e32 v84, 0xbfb8aa3b, v78
	v_exp_f32_e32 v84, v84
	v_or_b32_e32 v82, 48, v146
	v_mad_i64_i32 v[82:83], s[16:17], v82, s65, v[140:141]
	v_add_f32_e32 v84, 1.0, v84
	v_rcp_f32_e32 v84, v84
	s_nop 0
	v_mul_f32_e32 v78, v78, v84
	v_mul_f32_e32 v74, v78, v74
	v_mul_f32_e32 v78, 0xbfb8aa3b, v79
	v_exp_f32_e32 v78, v78
	s_nop 0
	v_add_f32_e32 v78, 1.0, v78
	v_rcp_f32_e32 v78, v78
	s_nop 0
	v_mul_f32_e32 v78, v79, v78
	v_mul_f32_e32 v75, v78, v75
	v_mul_f32_e32 v78, 0xbfb8aa3b, v80
	v_exp_f32_e32 v78, v78
	s_nop 0
	v_add_f32_e32 v78, 1.0, v78
	v_rcp_f32_e32 v78, v78
	s_nop 0
	v_mul_f32_e32 v78, v80, v78
	v_mul_f32_e32 v76, v78, v76
	v_mul_f32_e32 v78, 0xbfb8aa3b, v81
	v_exp_f32_e32 v78, v78
	s_nop 0
	v_add_f32_e32 v78, 1.0, v78
	v_rcp_f32_e32 v78, v78
	s_nop 0
	v_mul_f32_e32 v78, v81, v78
	v_mul_f32_e32 v77, v78, v77
	v_mul_f32_e32 v78, 0xbfb8aa3b, v70
	v_exp_f32_e32 v78, v78
	s_nop 0
	v_add_f32_e32 v78, 1.0, v78
	v_rcp_f32_e32 v78, v78
	s_nop 0
	v_mul_f32_e32 v70, v70, v78
	v_mul_f32_e32 v78, v70, v66
	v_mul_f32_e32 v66, 0xbfb8aa3b, v71
	v_exp_f32_e32 v66, v66
	s_nop 0
	v_add_f32_e32 v66, 1.0, v66
	v_rcp_f32_e32 v66, v66
	s_nop 0
	v_mul_f32_e32 v66, v71, v66
	v_mul_f32_e32 v79, v66, v67
	v_mul_f32_e32 v66, 0xbfb8aa3b, v72
	v_exp_f32_e32 v66, v66
	v_lshl_add_u64 v[70:71], v[82:83], 0, v[114:115]
	v_cvt_pk_bf16_f32 v67, v76, v77
	v_add_f32_e32 v66, 1.0, v66
	v_rcp_f32_e32 v66, v66
	s_nop 0
	v_mul_f32_e32 v66, v72, v66
	v_mul_f32_e32 v72, v66, v68
	v_mul_f32_e32 v66, 0xbfb8aa3b, v73
	v_exp_f32_e32 v66, v66
	v_cvt_pk_bf16_f32 v68, v78, v79
	s_nop 0
	v_add_f32_e32 v66, 1.0, v66
	v_rcp_f32_e32 v66, v66
	s_nop 0
	v_mul_f32_e32 v66, v73, v66
	v_mul_f32_e32 v69, v66, v69
	v_cvt_pk_bf16_f32 v66, v74, v75
	v_cvt_pk_bf16_f32 v69, v72, v69
	global_store_dwordx4 v[70:71], v[66:69], off
	s_nop 1
	v_mul_f32_e32 v68, 0xbfb8aa3b, v62
	v_exp_f32_e32 v68, v68
	v_add_u32_e32 v66, 0x80, v146
	v_mad_i64_i32 v[66:67], s[16:17], v66, s65, v[140:141]
	v_add_f32_e32 v68, 1.0, v68
	v_rcp_f32_e32 v68, v68
	s_nop 0
	v_mul_f32_e32 v62, v62, v68
	v_mul_f32_e32 v58, v62, v58
	v_mul_f32_e32 v62, 0xbfb8aa3b, v63
	v_exp_f32_e32 v62, v62
	s_nop 0
	v_add_f32_e32 v62, 1.0, v62
	v_rcp_f32_e32 v62, v62
	s_nop 0
	v_mul_f32_e32 v62, v63, v62
	v_mul_f32_e32 v59, v62, v59
	v_mul_f32_e32 v62, 0xbfb8aa3b, v64
	v_exp_f32_e32 v62, v62
	s_nop 0
	v_add_f32_e32 v62, 1.0, v62
	v_rcp_f32_e32 v62, v62
	s_nop 0
	v_mul_f32_e32 v62, v64, v62
	v_mul_f32_e32 v60, v62, v60
	v_mul_f32_e32 v62, 0xbfb8aa3b, v65
	v_exp_f32_e32 v62, v62
	s_nop 0
	v_add_f32_e32 v62, 1.0, v62
	v_rcp_f32_e32 v62, v62
	s_nop 0
	v_mul_f32_e32 v62, v65, v62
	v_mul_f32_e32 v61, v62, v61
	v_mul_f32_e32 v62, 0xbfb8aa3b, v54
	v_exp_f32_e32 v62, v62
	s_nop 0
	v_add_f32_e32 v62, 1.0, v62
	v_rcp_f32_e32 v62, v62
	s_nop 0
	v_mul_f32_e32 v54, v54, v62
	v_mul_f32_e32 v62, v54, v50
	v_mul_f32_e32 v50, 0xbfb8aa3b, v55
	v_exp_f32_e32 v50, v50
	s_nop 0
	v_add_f32_e32 v50, 1.0, v50
	v_rcp_f32_e32 v50, v50
	s_nop 0
	v_mul_f32_e32 v50, v55, v50
	v_mul_f32_e32 v63, v50, v51
	v_mul_f32_e32 v50, 0xbfb8aa3b, v56
	v_exp_f32_e32 v50, v50
	v_lshl_add_u64 v[54:55], v[66:67], 0, v[114:115]
	v_cvt_pk_bf16_f32 v51, v60, v61
	v_add_f32_e32 v50, 1.0, v50
	v_rcp_f32_e32 v50, v50
	s_nop 0
	v_mul_f32_e32 v50, v56, v50
	v_mul_f32_e32 v56, v50, v52
	v_mul_f32_e32 v50, 0xbfb8aa3b, v57
	v_exp_f32_e32 v50, v50
	v_cvt_pk_bf16_f32 v52, v62, v63
	s_nop 0
	v_add_f32_e32 v50, 1.0, v50
	v_rcp_f32_e32 v50, v50
	s_nop 0
	v_mul_f32_e32 v50, v57, v50
	v_mul_f32_e32 v53, v50, v53
	v_cvt_pk_bf16_f32 v50, v58, v59
	v_cvt_pk_bf16_f32 v53, v56, v53
	global_store_dwordx4 v[54:55], v[50:53], off
	s_nop 1
	v_mul_f32_e32 v52, 0xbfb8aa3b, v46
	v_exp_f32_e32 v52, v52
	v_add_u32_e32 v50, 0x90, v146
	v_mad_i64_i32 v[50:51], s[16:17], v50, s65, v[140:141]
	v_add_f32_e32 v52, 1.0, v52
	v_rcp_f32_e32 v52, v52
	s_nop 0
	v_mul_f32_e32 v46, v46, v52
	v_mul_f32_e32 v42, v46, v42
	v_mul_f32_e32 v46, 0xbfb8aa3b, v47
	v_exp_f32_e32 v46, v46
	s_nop 0
	v_add_f32_e32 v46, 1.0, v46
	v_rcp_f32_e32 v46, v46
	s_nop 0
	v_mul_f32_e32 v46, v47, v46
	v_mul_f32_e32 v43, v46, v43
	v_mul_f32_e32 v46, 0xbfb8aa3b, v48
	v_exp_f32_e32 v46, v46
	s_nop 0
	v_add_f32_e32 v46, 1.0, v46
	v_rcp_f32_e32 v46, v46
	s_nop 0
	v_mul_f32_e32 v46, v48, v46
	v_mul_f32_e32 v44, v46, v44
	v_mul_f32_e32 v46, 0xbfb8aa3b, v49
	v_exp_f32_e32 v46, v46
	s_nop 0
	v_add_f32_e32 v46, 1.0, v46
	v_rcp_f32_e32 v46, v46
	s_nop 0
	v_mul_f32_e32 v46, v49, v46
	v_mul_f32_e32 v45, v46, v45
	v_mul_f32_e32 v46, 0xbfb8aa3b, v38
	v_exp_f32_e32 v46, v46
	s_nop 0
	v_add_f32_e32 v46, 1.0, v46
	v_rcp_f32_e32 v46, v46
	s_nop 0
	v_mul_f32_e32 v38, v38, v46
	v_mul_f32_e32 v46, v38, v34
	v_mul_f32_e32 v34, 0xbfb8aa3b, v39
	v_exp_f32_e32 v34, v34
	s_nop 0
	v_add_f32_e32 v34, 1.0, v34
	v_rcp_f32_e32 v34, v34
	s_nop 0
	v_mul_f32_e32 v34, v39, v34
	v_mul_f32_e32 v47, v34, v35
	v_mul_f32_e32 v34, 0xbfb8aa3b, v40
	v_exp_f32_e32 v34, v34
	v_lshl_add_u64 v[38:39], v[50:51], 0, v[114:115]
	v_cvt_pk_bf16_f32 v35, v44, v45
	v_add_f32_e32 v34, 1.0, v34
	v_rcp_f32_e32 v34, v34
	s_nop 0
	v_mul_f32_e32 v34, v40, v34
	v_mul_f32_e32 v40, v34, v36
	v_mul_f32_e32 v34, 0xbfb8aa3b, v41
	v_exp_f32_e32 v34, v34
	v_cvt_pk_bf16_f32 v36, v46, v47
	s_nop 0
	v_add_f32_e32 v34, 1.0, v34
	v_rcp_f32_e32 v34, v34
	s_nop 0
	v_mul_f32_e32 v34, v41, v34
	v_mul_f32_e32 v37, v34, v37
	v_cvt_pk_bf16_f32 v34, v42, v43
	v_cvt_pk_bf16_f32 v37, v40, v37
	global_store_dwordx4 v[38:39], v[34:37], off
	s_nop 1
	v_mul_f32_e32 v36, 0xbfb8aa3b, v30
	v_exp_f32_e32 v36, v36
	v_add_u32_e32 v34, 0xa0, v146
	v_mad_i64_i32 v[34:35], s[16:17], v34, s65, v[140:141]
	v_add_f32_e32 v36, 1.0, v36
	v_rcp_f32_e32 v36, v36
	s_nop 0
	v_mul_f32_e32 v30, v30, v36
	v_mul_f32_e32 v26, v30, v26
	v_mul_f32_e32 v30, 0xbfb8aa3b, v31
	v_exp_f32_e32 v30, v30
	s_nop 0
	v_add_f32_e32 v30, 1.0, v30
	v_rcp_f32_e32 v30, v30
	s_nop 0
	v_mul_f32_e32 v30, v31, v30
	v_mul_f32_e32 v27, v30, v27
	v_mul_f32_e32 v30, 0xbfb8aa3b, v32
	v_exp_f32_e32 v30, v30
	s_nop 0
	v_add_f32_e32 v30, 1.0, v30
	v_rcp_f32_e32 v30, v30
	s_nop 0
	v_mul_f32_e32 v30, v32, v30
	v_mul_f32_e32 v28, v30, v28
	v_mul_f32_e32 v30, 0xbfb8aa3b, v33
	v_exp_f32_e32 v30, v30
	s_nop 0
	v_add_f32_e32 v30, 1.0, v30
	v_rcp_f32_e32 v30, v30
	s_nop 0
	v_mul_f32_e32 v30, v33, v30
	v_mul_f32_e32 v29, v30, v29
	v_mul_f32_e32 v30, 0xbfb8aa3b, v22
	v_exp_f32_e32 v30, v30
	s_nop 0
	v_add_f32_e32 v30, 1.0, v30
	v_rcp_f32_e32 v30, v30
	s_nop 0
	v_mul_f32_e32 v22, v22, v30
	v_mul_f32_e32 v30, v22, v18
	v_mul_f32_e32 v18, 0xbfb8aa3b, v23
	v_exp_f32_e32 v18, v18
	s_nop 0
	v_add_f32_e32 v18, 1.0, v18
	v_rcp_f32_e32 v18, v18
	s_nop 0
	v_mul_f32_e32 v18, v23, v18
	v_mul_f32_e32 v31, v18, v19
	v_mul_f32_e32 v18, 0xbfb8aa3b, v24
	v_exp_f32_e32 v18, v18
	v_lshl_add_u64 v[22:23], v[34:35], 0, v[114:115]
	v_cvt_pk_bf16_f32 v19, v28, v29
	v_add_f32_e32 v18, 1.0, v18
	v_rcp_f32_e32 v18, v18
	s_nop 0
	v_mul_f32_e32 v18, v24, v18
	v_mul_f32_e32 v24, v18, v20
	v_mul_f32_e32 v18, 0xbfb8aa3b, v25
	v_exp_f32_e32 v18, v18
	v_cvt_pk_bf16_f32 v20, v30, v31
	s_nop 0
	v_add_f32_e32 v18, 1.0, v18
	v_rcp_f32_e32 v18, v18
	s_nop 0
	v_mul_f32_e32 v18, v25, v18
	v_mul_f32_e32 v21, v18, v21
	v_cvt_pk_bf16_f32 v18, v26, v27
	v_cvt_pk_bf16_f32 v21, v24, v21
	global_store_dwordx4 v[22:23], v[18:21], off
	s_nop 1
	v_mul_f32_e32 v20, 0xbfb8aa3b, v12
	v_exp_f32_e32 v20, v20
	v_add_u32_e32 v18, 0xb0, v146
	v_mad_i64_i32 v[18:19], s[16:17], v18, s65, v[140:141]
	v_add_f32_e32 v20, 1.0, v20
	v_rcp_f32_e32 v20, v20
	s_nop 0
	v_mul_f32_e32 v12, v12, v20
	v_mul_f32_e32 v8, v12, v8
	v_mul_f32_e32 v12, 0xbfb8aa3b, v13
	v_exp_f32_e32 v12, v12
	s_nop 0
	v_add_f32_e32 v12, 1.0, v12
	v_rcp_f32_e32 v12, v12
	s_nop 0
	v_mul_f32_e32 v12, v13, v12
	v_mul_f32_e32 v9, v12, v9
	v_mul_f32_e32 v12, 0xbfb8aa3b, v14
	v_exp_f32_e32 v12, v12
	s_nop 0
	v_add_f32_e32 v12, 1.0, v12
	v_rcp_f32_e32 v12, v12
	s_nop 0
	v_mul_f32_e32 v12, v14, v12
	v_mul_f32_e32 v10, v12, v10
	v_mul_f32_e32 v12, 0xbfb8aa3b, v15
	v_exp_f32_e32 v12, v12
	s_nop 0
	v_add_f32_e32 v12, 1.0, v12
	v_rcp_f32_e32 v12, v12
	s_nop 0
	v_mul_f32_e32 v12, v15, v12
	v_mul_f32_e32 v11, v12, v11
	v_mul_f32_e32 v12, 0xbfb8aa3b, v4
	v_exp_f32_e32 v12, v12
	s_nop 0
	v_add_f32_e32 v12, 1.0, v12
	v_rcp_f32_e32 v12, v12
	s_nop 0
	v_mul_f32_e32 v4, v4, v12
	v_mul_f32_e32 v12, v4, v0
	v_mul_f32_e32 v0, 0xbfb8aa3b, v5
	v_exp_f32_e32 v0, v0
	s_nop 0
	v_add_f32_e32 v0, 1.0, v0
	v_rcp_f32_e32 v0, v0
	s_nop 0
	v_mul_f32_e32 v0, v5, v0
	v_mul_f32_e32 v13, v0, v1
	v_mul_f32_e32 v0, 0xbfb8aa3b, v6
	v_exp_f32_e32 v0, v0
	v_lshl_add_u64 v[4:5], v[18:19], 0, v[114:115]
	v_cvt_pk_bf16_f32 v1, v10, v11
	v_add_f32_e32 v0, 1.0, v0
	v_rcp_f32_e32 v0, v0
	s_nop 0
	v_mul_f32_e32 v0, v6, v0
	v_mul_f32_e32 v6, v0, v2
	v_mul_f32_e32 v0, 0xbfb8aa3b, v7
	v_exp_f32_e32 v0, v0
	v_cvt_pk_bf16_f32 v2, v12, v13
	s_nop 0
	v_add_f32_e32 v0, 1.0, v0
	v_rcp_f32_e32 v0, v0
	s_nop 0
	v_mul_f32_e32 v0, v7, v0
	v_mul_f32_e32 v3, v0, v3
	v_cvt_pk_bf16_f32 v0, v8, v9
	v_cvt_pk_bf16_f32 v3, v6, v3
	global_store_dwordx4 v[4:5], v[0:3], off
	s_and_b64 vcc, exec, s[38:39]
	s_mov_b32 s2, s8
	s_mov_b32 s14, s28
	s_mov_b64 s[16:17], s[42:43]
	s_mov_b64 s[18:19], s[40:41]
	s_cbranch_vccz .LBB0_144
	s_waitcnt vmcnt(0)
	s_cmpk_gt_u32 s48, 0xff
	s_cbranch_scc1 .LBB0_151
	s_barrier

.LBB0_173:
	s_ashr_i32 s9, s8, 31
	v_cmp_lt_i64_e32 vcc, s[14:15], v[202:203]
	s_lshl_b64 s[14:15], s[8:9], 19
	s_add_u32 s14, s96, s14
	s_addc_u32 s15, s97, s15
	s_and_b64 s[16:17], vcc, exec
	s_cselect_b32 s9, s15, s23
	s_cselect_b32 s12, s14, s22
	s_ashr_i32 s5, s4, 31
	s_lshl_b64 s[16:17], s[4:5], 19
	s_add_u32 s16, s50, s16
	s_addc_u32 s17, s51, s17
	s_and_b64 s[42:43], vcc, exec
	s_cselect_b32 s5, s17, s41
	s_cselect_b32 s34, s16, s40
	s_add_u32 s61, s40, 0x100
	v_mov_b32_e32 v0, 0
	s_addc_u32 s79, s41, 0
	s_mov_b32 s82, -2
	v_mov_b32_e32 v1, v0
	v_mov_b32_e32 v2, v0
	v_mov_b32_e32 v3, v0
	v_mov_b32_e32 v4, v0
	v_mov_b32_e32 v5, v0
	v_mov_b32_e32 v6, v0
	v_mov_b32_e32 v7, v0
	v_mov_b32_e32 v8, v0
	v_mov_b32_e32 v9, v0
	v_mov_b32_e32 v10, v0
	v_mov_b32_e32 v11, v0
	v_mov_b32_e32 v12, v0
	v_mov_b32_e32 v13, v0
	v_mov_b32_e32 v14, v0
	v_mov_b32_e32 v15, v0
	v_mov_b32_e32 v22, v0
	v_mov_b32_e32 v23, v0
	v_mov_b32_e32 v24, v0
	v_mov_b32_e32 v25, v0
	v_mov_b32_e32 v26, v0
	v_mov_b32_e32 v27, v0
	v_mov_b32_e32 v28, v0
	v_mov_b32_e32 v29, v0
	v_mov_b32_e32 v34, v0
	v_mov_b32_e32 v35, v0
	v_mov_b32_e32 v36, v0
	v_mov_b32_e32 v37, v0
	v_mov_b32_e32 v42, v0
	v_mov_b32_e32 v43, v0
	v_mov_b32_e32 v44, v0
	v_mov_b32_e32 v45, v0
	v_mov_b32_e32 v18, v0
	v_mov_b32_e32 v19, v0
	v_mov_b32_e32 v20, v0
	v_mov_b32_e32 v21, v0
	v_mov_b32_e32 v30, v0
	v_mov_b32_e32 v31, v0
	v_mov_b32_e32 v32, v0
	v_mov_b32_e32 v33, v0
	v_mov_b32_e32 v38, v0
	v_mov_b32_e32 v39, v0
	v_mov_b32_e32 v40, v0
	v_mov_b32_e32 v41, v0
	v_mov_b32_e32 v46, v0
	v_mov_b32_e32 v47, v0
	v_mov_b32_e32 v48, v0
	v_mov_b32_e32 v49, v0
	v_mov_b32_e32 v50, v0
	v_mov_b32_e32 v51, v0
	v_mov_b32_e32 v52, v0
	v_mov_b32_e32 v53, v0
	v_mov_b32_e32 v54, v0
	v_mov_b32_e32 v55, v0
	v_mov_b32_e32 v56, v0
	v_mov_b32_e32 v57, v0
	v_mov_b32_e32 v58, v0
	v_mov_b32_e32 v59, v0
	v_mov_b32_e32 v60, v0
	v_mov_b32_e32 v61, v0
	v_mov_b32_e32 v62, v0
	v_mov_b32_e32 v63, v0
	v_mov_b32_e32 v64, v0
	v_mov_b32_e32 v65, v0
	v_mov_b32_e32 v66, v0
	v_mov_b32_e32 v67, v0
	v_mov_b32_e32 v68, v0
	v_mov_b32_e32 v69, v0
	v_mov_b32_e32 v70, v0
	v_mov_b32_e32 v71, v0
	v_mov_b32_e32 v72, v0
	v_mov_b32_e32 v73, v0
	v_mov_b32_e32 v78, v0
	v_mov_b32_e32 v79, v0
	v_mov_b32_e32 v80, v0
	v_mov_b32_e32 v81, v0
	v_mov_b32_e32 v82, v0
	v_mov_b32_e32 v83, v0
	v_mov_b32_e32 v84, v0
	v_mov_b32_e32 v85, v0
	v_mov_b32_e32 v94, v0
	v_mov_b32_e32 v95, v0
	v_mov_b32_e32 v96, v0
	v_mov_b32_e32 v97, v0
	v_mov_b32_e32 v98, v0
	v_mov_b32_e32 v99, v0
	v_mov_b32_e32 v100, v0
	v_mov_b32_e32 v101, v0
	v_mov_b32_e32 v110, v0
	v_mov_b32_e32 v111, v0
	v_mov_b32_e32 v112, v0
	v_mov_b32_e32 v113, v0
	v_mov_b32_e32 v114, v0
	v_mov_b32_e32 v115, v0
	v_mov_b32_e32 v116, v0
	v_mov_b32_e32 v117, v0
	v_mov_b32_e32 v74, v0
	v_mov_b32_e32 v75, v0
	v_mov_b32_e32 v76, v0
	v_mov_b32_e32 v77, v0
	v_mov_b32_e32 v86, v0
	v_mov_b32_e32 v87, v0
	v_mov_b32_e32 v88, v0
	v_mov_b32_e32 v89, v0
	v_mov_b32_e32 v90, v0
	v_mov_b32_e32 v91, v0
	v_mov_b32_e32 v92, v0
	v_mov_b32_e32 v93, v0
	v_mov_b32_e32 v102, v0
	v_mov_b32_e32 v103, v0
	v_mov_b32_e32 v104, v0
	v_mov_b32_e32 v105, v0
	v_mov_b32_e32 v106, v0
	v_mov_b32_e32 v107, v0
	v_mov_b32_e32 v108, v0
	v_mov_b32_e32 v109, v0
	v_mov_b32_e32 v118, v0
	v_mov_b32_e32 v119, v0
	v_mov_b32_e32 v120, v0
	v_mov_b32_e32 v121, v0
	v_mov_b32_e32 v122, v0
	v_mov_b32_e32 v123, v0
	v_mov_b32_e32 v124, v0
	v_mov_b32_e32 v125, v0
	v_mov_b32_e32 v126, v0
	v_mov_b32_e32 v127, v0
	v_mov_b32_e32 v128, v0
	v_mov_b32_e32 v129, v0
	v_readfirstlane_b32 s98, v228
	s_lshr_b32 s98, s98, 8
	s_cmp_lg_u32 s98, 0
	s_cbranch_scc0 .Lprio_skip_2
	s_setprio 1
.Lprio_skip_2:
.LBB0_174:
	s_add_u32 s40, s22, 0x100
	s_addc_u32 s41, s23, 0
	s_add_i32 s83, 0, 0x10000
	v_add_u32_e32 v148, s83, v157
	ds_read_b128 v[130:133], v148
	ds_read_b128 v[134:137], v148 offset:1024
	ds_read_b128 v[138:141], v148 offset:2048
	ds_read_b128 v[148:151], v148 offset:3072
	s_cmp_eq_u32 s82, 12
	s_cselect_b32 s49, s9, s41
	s_cselect_b32 s48, s12, s40
	s_cselect_b32 s43, s5, s79
	s_cselect_b32 s42, s34, s61
	v_lshl_add_u64 v[188:189], s[22:23], 0, v[146:147]
	s_add_i32 m0, s19, 0xc000
	ds_read_b128 v[152:155], v159
	ds_read_b128 v[160:163], v159 offset:1024
	ds_read_b128 v[164:167], v159 offset:2048
	ds_read_b128 v[168:171], v159 offset:3072
	ds_read_b128 v[172:175], v159 offset:4096
	ds_read_b128 v[176:179], v159 offset:5120
	ds_read_b128 v[180:183], v159 offset:6144
	ds_read_b128 v[184:187], v159 offset:7168
	global_load_lds_dwordx4 v[188:189], off
	v_lshl_add_u64 v[188:189], s[22:23], 0, v[144:145]
	s_add_i32 m0, s19, 0xe000
	s_nop 0
	global_load_lds_dwordx4 v[188:189], off
	s_waitcnt lgkmcnt(8)
	s_barrier
	s_waitcnt lgkmcnt(0)
	s_waitcnt lgkmcnt(0)
	v_mfma_f32_16x16x32_bf16 v[126:129], v[130:133], v[152:155], v[126:129]
	v_mfma_f32_16x16x32_bf16 v[122:125], v[138:141], v[152:155], v[122:125]
	v_mfma_f32_16x16x32_bf16 v[118:121], v[130:133], v[164:167], v[118:121]
	v_mfma_f32_16x16x32_bf16 v[106:109], v[138:141], v[164:167], v[106:109]
	v_mfma_f32_16x16x32_bf16 v[102:105], v[130:133], v[172:175], v[102:105]
	v_mfma_f32_16x16x32_bf16 v[90:93], v[138:141], v[172:175], v[90:93]
	v_mfma_f32_16x16x32_bf16 v[86:89], v[130:133], v[180:183], v[86:89]
	v_mfma_f32_16x16x32_bf16 v[74:77], v[138:141], v[180:183], v[74:77]
	v_mfma_f32_16x16x32_bf16 v[126:129], v[134:137], v[160:163], v[126:129]
	v_mfma_f32_16x16x32_bf16 v[122:125], v[148:151], v[160:163], v[122:125]
	v_mfma_f32_16x16x32_bf16 v[118:121], v[134:137], v[168:171], v[118:121]
	v_mfma_f32_16x16x32_bf16 v[106:109], v[148:151], v[168:171], v[106:109]
	v_mfma_f32_16x16x32_bf16 v[102:105], v[134:137], v[176:179], v[102:105]
	v_mfma_f32_16x16x32_bf16 v[90:93], v[148:151], v[176:179], v[90:93]
	v_mfma_f32_16x16x32_bf16 v[86:89], v[134:137], v[184:187], v[86:89]
	v_mfma_f32_16x16x32_bf16 v[74:77], v[148:151], v[184:187], v[74:77]
	s_barrier
	s_add_i32 s84, 0, 0x14000
	v_add_u32_e32 v196, s84, v157
	s_add_i32 s22, s83, s52
	ds_read_b128 v[188:191], v196
	ds_read_b128 v[192:195], v196 offset:1024
	ds_read_b128 v[208:211], v196 offset:2048
	ds_read_b128 v[212:215], v196 offset:3072
	v_lshl_add_u64 v[196:197], s[42:43], 0, v[16:17]
	s_mov_b32 m0, s22
	v_lshl_add_u64 v[216:217], s[42:43], 0, v[142:143]
	global_load_lds_dwordx4 v[196:197], off
	s_add_i32 m0, s22, 0x2000
	s_nop 0
	global_load_lds_dwordx4 v[216:217], off
	s_barrier
	s_waitcnt lgkmcnt(0)
	s_waitcnt lgkmcnt(0)
	v_mfma_f32_16x16x32_bf16 v[114:117], v[188:191], v[152:155], v[114:117]
	v_mfma_f32_16x16x32_bf16 v[110:113], v[208:211], v[152:155], v[110:113]
	v_mfma_f32_16x16x32_bf16 v[98:101], v[188:191], v[164:167], v[98:101]
	v_mfma_f32_16x16x32_bf16 v[94:97], v[208:211], v[164:167], v[94:97]
	v_mfma_f32_16x16x32_bf16 v[82:85], v[188:191], v[172:175], v[82:85]
	v_mfma_f32_16x16x32_bf16 v[78:81], v[208:211], v[172:175], v[78:81]
	v_mfma_f32_16x16x32_bf16 v[70:73], v[188:191], v[180:183], v[70:73]
	v_mfma_f32_16x16x32_bf16 v[66:69], v[208:211], v[180:183], v[66:69]
	v_mfma_f32_16x16x32_bf16 v[114:117], v[192:195], v[160:163], v[114:117]
	v_mfma_f32_16x16x32_bf16 v[110:113], v[212:215], v[160:163], v[110:113]
	v_mfma_f32_16x16x32_bf16 v[98:101], v[192:195], v[168:171], v[98:101]
	v_mfma_f32_16x16x32_bf16 v[94:97], v[212:215], v[168:171], v[94:97]
	v_mfma_f32_16x16x32_bf16 v[82:85], v[192:195], v[176:179], v[82:85]
	v_mfma_f32_16x16x32_bf16 v[78:81], v[212:215], v[176:179], v[78:81]
	v_mfma_f32_16x16x32_bf16 v[70:73], v[192:195], v[184:187], v[70:73]
	v_mfma_f32_16x16x32_bf16 v[66:69], v[212:215], v[184:187], v[66:69]
	s_mov_b32 m0, s19
	v_lshl_add_u64 v[218:219], s[48:49], 0, v[16:17]
	s_barrier
	ds_read_b128 v[152:155], v159 offset:16384
	ds_read_b128 v[160:163], v159 offset:17408
	ds_read_b128 v[164:167], v159 offset:18432
	ds_read_b128 v[168:171], v159 offset:19456
	ds_read_b128 v[172:175], v159 offset:20480
	ds_read_b128 v[176:179], v159 offset:21504
	ds_read_b128 v[180:183], v159 offset:22528
	ds_read_b128 v[184:187], v159 offset:23552
	global_load_lds_dwordx4 v[218:219], off
	v_lshl_add_u64 v[220:221], s[48:49], 0, v[142:143]
	s_mov_b32 m0, s54
	s_nop 0
	global_load_lds_dwordx4 v[220:221], off
	s_barrier
	s_waitcnt lgkmcnt(0)
	s_waitcnt lgkmcnt(0)
	v_mfma_f32_16x16x32_bf16 v[62:65], v[130:133], v[152:155], v[62:65]
	v_mfma_f32_16x16x32_bf16 v[58:61], v[138:141], v[152:155], v[58:61]
	v_mfma_f32_16x16x32_bf16 v[54:57], v[130:133], v[164:167], v[54:57]
	v_mfma_f32_16x16x32_bf16 v[50:53], v[138:141], v[164:167], v[50:53]
	v_mfma_f32_16x16x32_bf16 v[46:49], v[130:133], v[172:175], v[46:49]
	v_mfma_f32_16x16x32_bf16 v[38:41], v[138:141], v[172:175], v[38:41]
	v_mfma_f32_16x16x32_bf16 v[30:33], v[130:133], v[180:183], v[30:33]
	v_mfma_f32_16x16x32_bf16 v[18:21], v[138:141], v[180:183], v[18:21]
	v_mfma_f32_16x16x32_bf16 v[62:65], v[134:137], v[160:163], v[62:65]
	v_mfma_f32_16x16x32_bf16 v[58:61], v[148:151], v[160:163], v[58:61]
	v_mfma_f32_16x16x32_bf16 v[54:57], v[134:137], v[168:171], v[54:57]
	v_mfma_f32_16x16x32_bf16 v[50:53], v[148:151], v[168:171], v[50:53]
	v_mfma_f32_16x16x32_bf16 v[46:49], v[134:137], v[176:179], v[46:49]
	v_mfma_f32_16x16x32_bf16 v[38:41], v[148:151], v[176:179], v[38:41]
	v_mfma_f32_16x16x32_bf16 v[30:33], v[134:137], v[184:187], v[30:33]
	v_mfma_f32_16x16x32_bf16 v[18:21], v[148:151], v[184:187], v[18:21]
	s_barrier
	s_add_u32 s22, s42, 0x40000
	s_addc_u32 s23, s43, 0
	s_add_i32 s83, s84, s52
	v_lshl_add_u64 v[130:131], s[22:23], 0, v[16:17]
	s_mov_b32 m0, s83
	s_nop 0
	global_load_lds_dwordx4 v[130:131], off
	v_lshl_add_u64 v[130:131], s[22:23], 0, v[142:143]
	s_add_i32 m0, s83, 0x2000
	s_nop 0
	global_load_lds_dwordx4 v[130:131], off
	s_waitcnt vmcnt(6)
	s_barrier
	v_mfma_f32_16x16x32_bf16 v[42:45], v[188:191], v[152:155], v[42:45]
	v_mfma_f32_16x16x32_bf16 v[34:37], v[208:211], v[152:155], v[34:37]
	v_mfma_f32_16x16x32_bf16 v[26:29], v[188:191], v[164:167], v[26:29]
	v_mfma_f32_16x16x32_bf16 v[22:25], v[208:211], v[164:167], v[22:25]
	v_mfma_f32_16x16x32_bf16 v[12:15], v[188:191], v[172:175], v[12:15]
	v_mfma_f32_16x16x32_bf16 v[8:11], v[208:211], v[172:175], v[8:11]
	v_mfma_f32_16x16x32_bf16 v[4:7], v[188:191], v[180:183], v[4:7]
	v_mfma_f32_16x16x32_bf16 v[0:3], v[208:211], v[180:183], v[0:3]
	v_mfma_f32_16x16x32_bf16 v[42:45], v[192:195], v[160:163], v[42:45]
	v_mfma_f32_16x16x32_bf16 v[34:37], v[212:215], v[160:163], v[34:37]
	v_mfma_f32_16x16x32_bf16 v[26:29], v[192:195], v[168:171], v[26:29]
	v_mfma_f32_16x16x32_bf16 v[22:25], v[212:215], v[168:171], v[22:25]
	v_mfma_f32_16x16x32_bf16 v[12:15], v[192:195], v[176:179], v[12:15]
	v_mfma_f32_16x16x32_bf16 v[8:11], v[212:215], v[176:179], v[8:11]
	v_mfma_f32_16x16x32_bf16 v[4:7], v[192:195], v[184:187], v[4:7]
	v_mfma_f32_16x16x32_bf16 v[0:3], v[212:215], v[184:187], v[0:3]
	s_add_i32 s83, 0, 0x18000
	v_add_u32_e32 v148, s83, v157
	s_barrier
	ds_read_b128 v[130:133], v148
	ds_read_b128 v[134:137], v148 offset:1024
	ds_read_b128 v[138:141], v148 offset:2048
	ds_read_b128 v[148:151], v148 offset:3072
	s_add_u32 s22, s48, 0x40000
	s_addc_u32 s23, s49, 0
	s_mov_b32 m0, s55
	v_lshl_add_u64 v[188:189], s[22:23], 0, v[16:17]
	ds_read_b128 v[152:155], v159 offset:32768
	ds_read_b128 v[160:163], v159 offset:33792
	ds_read_b128 v[164:167], v159 offset:34816
	ds_read_b128 v[168:171], v159 offset:35840
	ds_read_b128 v[172:175], v159 offset:36864
	ds_read_b128 v[176:179], v159 offset:37888
	ds_read_b128 v[180:183], v159 offset:38912
	ds_read_b128 v[184:187], v159 offset:39936
	global_load_lds_dwordx4 v[188:189], off
	v_lshl_add_u64 v[188:189], s[22:23], 0, v[142:143]
	s_mov_b32 m0, s56
	s_nop 0
	global_load_lds_dwordx4 v[188:189], off
	s_waitcnt lgkmcnt(8)
	s_barrier
	s_waitcnt lgkmcnt(0)
	s_waitcnt lgkmcnt(0)
	v_mfma_f32_16x16x32_bf16 v[126:129], v[130:133], v[152:155], v[126:129]
	v_mfma_f32_16x16x32_bf16 v[122:125], v[138:141], v[152:155], v[122:125]
	v_mfma_f32_16x16x32_bf16 v[118:121], v[130:133], v[164:167], v[118:121]
	v_mfma_f32_16x16x32_bf16 v[106:109], v[138:141], v[164:167], v[106:109]
	v_mfma_f32_16x16x32_bf16 v[102:105], v[130:133], v[172:175], v[102:105]
	v_mfma_f32_16x16x32_bf16 v[90:93], v[138:141], v[172:175], v[90:93]
	v_mfma_f32_16x16x32_bf16 v[86:89], v[130:133], v[180:183], v[86:89]
	v_mfma_f32_16x16x32_bf16 v[74:77], v[138:141], v[180:183], v[74:77]
	v_mfma_f32_16x16x32_bf16 v[126:129], v[134:137], v[160:163], v[126:129]
	v_mfma_f32_16x16x32_bf16 v[122:125], v[148:151], v[160:163], v[122:125]
	v_mfma_f32_16x16x32_bf16 v[118:121], v[134:137], v[168:171], v[118:121]
	v_mfma_f32_16x16x32_bf16 v[106:109], v[148:151], v[168:171], v[106:109]
	v_mfma_f32_16x16x32_bf16 v[102:105], v[134:137], v[176:179], v[102:105]
	v_mfma_f32_16x16x32_bf16 v[90:93], v[148:151], v[176:179], v[90:93]
	v_mfma_f32_16x16x32_bf16 v[86:89], v[134:137], v[184:187], v[86:89]
	v_mfma_f32_16x16x32_bf16 v[74:77], v[148:151], v[184:187], v[74:77]
	s_barrier
	s_add_i32 s48, 0, 0x1c000
	s_add_i32 s22, s83, s52
	v_add_u32_e32 v212, s48, v157
	v_lshl_add_u64 v[196:197], v[196:197], 0, s[10:11]
	s_mov_b32 m0, s22
	ds_read_b128 v[188:191], v212
	ds_read_b128 v[192:195], v212 offset:1024
	ds_read_b128 v[208:211], v212 offset:2048
	ds_read_b128 v[212:215], v212 offset:3072
	global_load_lds_dwordx4 v[196:197], off
	v_lshl_add_u64 v[196:197], v[216:217], 0, s[10:11]
	s_add_i32 m0, s22, 0x2000
	s_nop 0
	global_load_lds_dwordx4 v[196:197], off
	s_barrier
	s_waitcnt lgkmcnt(0)
	s_waitcnt lgkmcnt(0)
	v_mfma_f32_16x16x32_bf16 v[114:117], v[188:191], v[152:155], v[114:117]
	v_mfma_f32_16x16x32_bf16 v[110:113], v[208:211], v[152:155], v[110:113]
	v_mfma_f32_16x16x32_bf16 v[98:101], v[188:191], v[164:167], v[98:101]
	v_mfma_f32_16x16x32_bf16 v[94:97], v[208:211], v[164:167], v[94:97]
	v_mfma_f32_16x16x32_bf16 v[82:85], v[188:191], v[172:175], v[82:85]
	v_mfma_f32_16x16x32_bf16 v[78:81], v[208:211], v[172:175], v[78:81]
	v_mfma_f32_16x16x32_bf16 v[70:73], v[188:191], v[180:183], v[70:73]
	v_mfma_f32_16x16x32_bf16 v[66:69], v[208:211], v[180:183], v[66:69]
	v_mfma_f32_16x16x32_bf16 v[114:117], v[192:195], v[160:163], v[114:117]
	v_mfma_f32_16x16x32_bf16 v[110:113], v[212:215], v[160:163], v[110:113]
	v_mfma_f32_16x16x32_bf16 v[98:101], v[192:195], v[168:171], v[98:101]
	v_mfma_f32_16x16x32_bf16 v[94:97], v[212:215], v[168:171], v[94:97]
	v_mfma_f32_16x16x32_bf16 v[82:85], v[192:195], v[176:179], v[82:85]
	v_mfma_f32_16x16x32_bf16 v[78:81], v[212:215], v[176:179], v[78:81]
	v_mfma_f32_16x16x32_bf16 v[70:73], v[192:195], v[184:187], v[70:73]
	v_mfma_f32_16x16x32_bf16 v[66:69], v[212:215], v[184:187], v[66:69]
	s_mov_b32 m0, s57
	v_lshl_add_u64 v[196:197], v[218:219], 0, s[10:11]
	s_barrier
	ds_read_b128 v[152:155], v159 offset:49152
	ds_read_b128 v[160:163], v159 offset:50176
	ds_read_b128 v[164:167], v159 offset:51200
	ds_read_b128 v[168:171], v159 offset:52224
	ds_read_b128 v[172:175], v159 offset:53248
	ds_read_b128 v[176:179], v159 offset:54272
	ds_read_b128 v[180:183], v159 offset:55296
	ds_read_b128 v[184:187], v159 offset:56320
	global_load_lds_dwordx4 v[196:197], off
	v_lshl_add_u64 v[196:197], v[220:221], 0, s[10:11]
	s_mov_b32 m0, s58
	s_nop 0
	global_load_lds_dwordx4 v[196:197], off
	s_barrier
	s_waitcnt lgkmcnt(0)
	s_waitcnt lgkmcnt(0)
	v_mfma_f32_16x16x32_bf16 v[62:65], v[130:133], v[152:155], v[62:65]
	v_mfma_f32_16x16x32_bf16 v[58:61], v[138:141], v[152:155], v[58:61]
	v_mfma_f32_16x16x32_bf16 v[54:57], v[130:133], v[164:167], v[54:57]
	v_mfma_f32_16x16x32_bf16 v[50:53], v[138:141], v[164:167], v[50:53]
	v_mfma_f32_16x16x32_bf16 v[46:49], v[130:133], v[172:175], v[46:49]
	v_mfma_f32_16x16x32_bf16 v[38:41], v[138:141], v[172:175], v[38:41]
	v_mfma_f32_16x16x32_bf16 v[30:33], v[130:133], v[180:183], v[30:33]
	v_mfma_f32_16x16x32_bf16 v[18:21], v[138:141], v[180:183], v[18:21]
	v_mfma_f32_16x16x32_bf16 v[62:65], v[134:137], v[160:163], v[62:65]
	v_mfma_f32_16x16x32_bf16 v[58:61], v[148:151], v[160:163], v[58:61]
	v_mfma_f32_16x16x32_bf16 v[54:57], v[134:137], v[168:171], v[54:57]
	v_mfma_f32_16x16x32_bf16 v[50:53], v[148:151], v[168:171], v[50:53]
	v_mfma_f32_16x16x32_bf16 v[46:49], v[134:137], v[176:179], v[46:49]
	v_mfma_f32_16x16x32_bf16 v[38:41], v[148:151], v[176:179], v[38:41]
	v_mfma_f32_16x16x32_bf16 v[30:33], v[134:137], v[184:187], v[30:33]
	v_mfma_f32_16x16x32_bf16 v[18:21], v[148:151], v[184:187], v[18:21]
	s_barrier
	s_add_u32 s22, s42, 0x40080
	s_addc_u32 s23, s43, 0
	s_add_i32 s42, s48, s52
	v_lshl_add_u64 v[130:131], s[22:23], 0, v[16:17]
	s_mov_b32 m0, s42
	s_nop 0
	global_load_lds_dwordx4 v[130:131], off
	v_lshl_add_u64 v[130:131], s[22:23], 0, v[142:143]
	s_add_i32 m0, s42, 0x2000
	s_nop 0
	global_load_lds_dwordx4 v[130:131], off
	s_waitcnt vmcnt(6)
	s_barrier
	v_mfma_f32_16x16x32_bf16 v[42:45], v[188:191], v[152:155], v[42:45]
	v_mfma_f32_16x16x32_bf16 v[34:37], v[208:211], v[152:155], v[34:37]
	v_mfma_f32_16x16x32_bf16 v[26:29], v[188:191], v[164:167], v[26:29]
	v_mfma_f32_16x16x32_bf16 v[22:25], v[208:211], v[164:167], v[22:25]
	v_mfma_f32_16x16x32_bf16 v[12:15], v[188:191], v[172:175], v[12:15]
	v_mfma_f32_16x16x32_bf16 v[8:11], v[208:211], v[172:175], v[8:11]
	v_mfma_f32_16x16x32_bf16 v[4:7], v[188:191], v[180:183], v[4:7]
	v_mfma_f32_16x16x32_bf16 v[0:3], v[208:211], v[180:183], v[0:3]
	v_mfma_f32_16x16x32_bf16 v[42:45], v[192:195], v[160:163], v[42:45]
	v_mfma_f32_16x16x32_bf16 v[34:37], v[212:215], v[160:163], v[34:37]
	v_mfma_f32_16x16x32_bf16 v[26:29], v[192:195], v[168:171], v[26:29]
	v_mfma_f32_16x16x32_bf16 v[22:25], v[212:215], v[168:171], v[22:25]
	v_mfma_f32_16x16x32_bf16 v[12:15], v[192:195], v[176:179], v[12:15]
	v_mfma_f32_16x16x32_bf16 v[8:11], v[212:215], v[176:179], v[8:11]
	v_mfma_f32_16x16x32_bf16 v[4:7], v[192:195], v[184:187], v[4:7]
	v_mfma_f32_16x16x32_bf16 v[0:3], v[212:215], v[184:187], v[0:3]
	s_add_i32 s82, s82, 2
	s_add_u32 s61, s61, 0x100
	s_addc_u32 s79, s79, 0
	s_cmp_gt_u32 s82, 13
	s_mov_b64 s[22:23], s[40:41]
	s_barrier
	s_cbranch_scc0 .LBB0_174
	v_lshl_or_b32 v132, s2, 8, v158
	v_lshl_add_u32 v130, s18, 8, v156
	v_ashrrev_i32_e32 v133, 31, v132
	v_lshlrev_b64 v[148:149], 2, v[132:133]
	v_ashrrev_i32_e32 v131, 31, v130
	v_lshl_add_u64 v[150:151], s[20:21], 0, v[148:149]
	v_lshlrev_b64 v[152:153], 12, v[130:131]
	v_lshl_add_u64 v[132:133], v[150:151], 0, v[152:153]
	global_load_dwordx4 v[160:163], v[132:133], off
	global_load_dwordx4 v[164:167], v[132:133], off offset:64
	global_load_dwordx4 v[168:171], v[132:133], off offset:512
	global_load_dwordx4 v[172:175], v[132:133], off offset:576
	v_or_b32_e32 v132, 16, v130
	v_ashrrev_i32_e32 v133, 31, v132
	v_lshlrev_b64 v[196:197], 12, v[132:133]
	v_lshl_add_u64 v[132:133], v[150:151], 0, v[196:197]
	global_load_dwordx4 v[176:179], v[132:133], off
	global_load_dwordx4 v[180:183], v[132:133], off offset:64
	global_load_dwordx4 v[184:187], v[132:133], off offset:512
	global_load_dwordx4 v[188:191], v[132:133], off offset:576
	v_or_b32_e32 v132, 32, v130
	v_ashrrev_i32_e32 v133, 31, v132
	v_or_b32_e32 v130, 48, v130
	v_lshlrev_b64 v[224:225], 12, v[132:133]
	v_ashrrev_i32_e32 v131, 31, v130
	v_lshl_add_u64 v[132:133], v[150:151], 0, v[224:225]
	v_lshlrev_b64 v[154:155], 12, v[130:131]
	global_load_dwordx4 v[192:195], v[132:133], off
	global_load_dwordx4 v[208:211], v[132:133], off offset:64
	global_load_dwordx4 v[212:215], v[132:133], off offset:512
	global_load_dwordx4 v[216:219], v[132:133], off offset:576
	v_lshl_add_u64 v[130:131], v[150:151], 0, v[154:155]
	global_load_dwordx4 v[220:223], v[130:131], off
	global_load_dwordx4 v[138:141], v[130:131], off offset:64
	global_load_dwordx4 v[134:137], v[130:131], off offset:512
	s_nop 0
	global_load_dwordx4 v[130:133], v[130:131], off offset:576
	s_waitcnt vmcnt(0) lgkmcnt(0)
	v_pk_add_f32 v[126:127], v[126:127], v[160:161]
	v_lshl_add_u64 v[160:161], s[20:21], 0, v[152:153]
	v_lshl_add_u64 v[160:161], v[160:161], 0, v[148:149]
	v_pk_add_f32 v[116:117], v[116:117], v[170:171]
	v_pk_add_f32 v[114:115], v[114:115], v[168:169]
	global_store_dwordx4 v[160:161], v[114:117], off offset:512
	v_pk_add_f32 v[112:113], v[112:113], v[174:175]
	v_pk_add_f32 v[100:101], v[100:101], v[186:187]
	v_lshl_add_u64 v[114:115], s[20:21], 0, v[196:197]
	v_lshl_add_u64 v[114:115], v[114:115], 0, v[148:149]
	v_pk_add_f32 v[98:99], v[98:99], v[184:185]
	global_store_dwordx4 v[114:115], v[98:101], off offset:512
	v_pk_add_f32 v[110:111], v[110:111], v[172:173]
	v_pk_add_f32 v[96:97], v[96:97], v[190:191]
	v_lshl_add_u64 v[98:99], s[20:21], 0, v[224:225]
	v_lshl_add_u64 v[98:99], v[98:99], 0, v[148:149]
	v_pk_add_f32 v[84:85], v[84:85], v[214:215]
	v_pk_add_f32 v[82:83], v[82:83], v[212:213]
	v_pk_add_f32 v[94:95], v[94:95], v[188:189]
	global_store_dwordx4 v[98:99], v[82:85], off offset:512
	v_pk_add_f32 v[80:81], v[80:81], v[218:219]
	v_pk_add_f32 v[78:79], v[78:79], v[216:217]
	v_lshl_add_u64 v[82:83], s[20:21], 0, v[154:155]
	v_pk_add_f32 v[128:129], v[128:129], v[162:163]
	v_pk_add_f32 v[124:125], v[124:125], v[166:167]
	v_pk_add_f32 v[122:123], v[122:123], v[164:165]
	global_store_dwordx4 v[160:161], v[110:113], off offset:576
	v_pk_add_f32 v[108:109], v[108:109], v[182:183]
	v_pk_add_f32 v[106:107], v[106:107], v[180:181]
	v_pk_add_f32 v[112:113], v[120:121], v[178:179]
	v_pk_add_f32 v[110:111], v[118:119], v[176:177]
	global_store_dwordx4 v[114:115], v[94:97], off offset:576
	v_pk_add_f32 v[92:93], v[92:93], v[210:211]
	v_pk_add_f32 v[90:91], v[90:91], v[208:209]
	v_pk_add_f32 v[96:97], v[104:105], v[194:195]
	v_pk_add_f32 v[94:95], v[102:103], v[192:193]
	global_store_dwordx4 v[98:99], v[78:81], off offset:576
	v_lshl_add_u64 v[82:83], v[82:83], 0, v[148:149]
	v_pk_add_f32 v[76:77], v[76:77], v[140:141]
	v_pk_add_f32 v[80:81], v[88:89], v[222:223]
	v_pk_add_f32 v[78:79], v[86:87], v[220:221]
	v_pk_add_f32 v[74:75], v[74:75], v[138:139]
	v_pk_add_f32 v[72:73], v[72:73], v[136:137]
	v_pk_add_f32 v[70:71], v[70:71], v[134:135]
	v_pk_add_f32 v[68:69], v[68:69], v[132:133]
	v_pk_add_f32 v[66:67], v[66:67], v[130:131]
	global_store_dwordx4 v[160:161], v[126:129], off
	global_store_dwordx4 v[160:161], v[122:125], off offset:64
	global_store_dwordx4 v[114:115], v[110:113], off
	global_store_dwordx4 v[114:115], v[106:109], off offset:64
	global_store_dwordx4 v[98:99], v[94:97], off
	global_store_dwordx4 v[98:99], v[90:93], off offset:64
	global_store_dwordx4 v[82:83], v[78:81], off
	global_store_dwordx4 v[82:83], v[74:77], off offset:64
	global_store_dwordx4 v[82:83], v[70:73], off offset:512
	global_store_dwordx4 v[82:83], v[66:69], off offset:576
	s_mov_b64 s[22:23], 0x80000
	v_lshl_add_u64 v[130:131], v[152:153], 0, s[22:23]
	s_mov_b64 s[22:23], 0x90000
	v_lshl_add_u64 v[132:133], v[152:153], 0, s[22:23]
	s_mov_b64 s[22:23], 0xa0000
	v_lshl_add_u64 v[134:135], v[152:153], 0, s[22:23]
	s_mov_b64 s[22:23], 0xb0000
	v_lshl_add_u64 v[136:137], v[152:153], 0, s[22:23]
	v_lshl_add_u64 v[78:79], v[150:151], 0, v[130:131]
	v_lshl_add_u64 v[94:95], v[150:151], 0, v[132:133]
	v_lshl_add_u64 v[110:111], v[150:151], 0, v[134:135]
	v_lshl_add_u64 v[126:127], v[150:151], 0, v[136:137]
	global_load_dwordx4 v[66:69], v[78:79], off
	global_load_dwordx4 v[70:73], v[78:79], off offset:64
	global_load_dwordx4 v[74:77], v[78:79], off offset:512
	v_lshl_add_u64 v[130:131], s[20:21], 0, v[130:131]
	global_load_dwordx4 v[78:81], v[78:79], off offset:576
	s_nop 0
	global_load_dwordx4 v[82:85], v[94:95], off
	global_load_dwordx4 v[86:89], v[94:95], off offset:64
	global_load_dwordx4 v[90:93], v[94:95], off offset:512
	v_lshl_add_u64 v[132:133], s[20:21], 0, v[132:133]
	global_load_dwordx4 v[94:97], v[94:95], off offset:576
	s_nop 0
	global_load_dwordx4 v[98:101], v[110:111], off
	global_load_dwordx4 v[102:105], v[110:111], off offset:64
	global_load_dwordx4 v[106:109], v[110:111], off offset:512
	v_lshl_add_u64 v[134:135], s[20:21], 0, v[134:135]
	global_load_dwordx4 v[110:113], v[110:111], off offset:576
	s_nop 0
	global_load_dwordx4 v[114:117], v[126:127], off
	global_load_dwordx4 v[118:121], v[126:127], off offset:64
	global_load_dwordx4 v[122:125], v[126:127], off offset:512
	s_nop 0
	global_load_dwordx4 v[126:129], v[126:127], off offset:576
	v_lshl_add_u64 v[136:137], s[20:21], 0, v[136:137]
	v_lshl_add_u64 v[130:131], v[130:131], 0, v[148:149]
	v_lshl_add_u64 v[132:133], v[132:133], 0, v[148:149]
	v_lshl_add_u64 v[134:135], v[134:135], 0, v[148:149]
	v_lshl_add_u64 v[136:137], v[136:137], 0, v[148:149]
	s_waitcnt vmcnt(0) lgkmcnt(0)
	v_pk_add_f32 v[64:65], v[64:65], v[68:69]
	v_pk_add_f32 v[62:63], v[62:63], v[66:67]
	v_pk_add_f32 v[60:61], v[60:61], v[72:73]
	v_pk_add_f32 v[58:59], v[58:59], v[70:71]
	v_pk_add_f32 v[44:45], v[44:45], v[76:77]
	v_pk_add_f32 v[42:43], v[42:43], v[74:75]
	v_pk_add_f32 v[36:37], v[36:37], v[80:81]
	v_pk_add_f32 v[34:35], v[34:35], v[78:79]
	v_pk_add_f32 v[56:57], v[56:57], v[84:85]
	v_pk_add_f32 v[54:55], v[54:55], v[82:83]
	v_pk_add_f32 v[52:53], v[52:53], v[88:89]
	v_pk_add_f32 v[50:51], v[50:51], v[86:87]
	v_pk_add_f32 v[28:29], v[28:29], v[92:93]
	v_pk_add_f32 v[26:27], v[26:27], v[90:91]
	v_pk_add_f32 v[24:25], v[24:25], v[96:97]
	v_pk_add_f32 v[22:23], v[22:23], v[94:95]
	v_pk_add_f32 v[48:49], v[48:49], v[100:101]
	v_pk_add_f32 v[46:47], v[46:47], v[98:99]
	v_pk_add_f32 v[40:41], v[40:41], v[104:105]
	v_pk_add_f32 v[38:39], v[38:39], v[102:103]
	v_pk_add_f32 v[14:15], v[14:15], v[108:109]
	v_pk_add_f32 v[12:13], v[12:13], v[106:107]
	v_pk_add_f32 v[10:11], v[10:11], v[112:113]
	v_pk_add_f32 v[8:9], v[8:9], v[110:111]
	v_pk_add_f32 v[32:33], v[32:33], v[116:117]
	v_pk_add_f32 v[30:31], v[30:31], v[114:115]
	v_pk_add_f32 v[20:21], v[20:21], v[120:121]
	v_pk_add_f32 v[18:19], v[18:19], v[118:119]
	v_pk_add_f32 v[6:7], v[6:7], v[124:125]
	v_pk_add_f32 v[4:5], v[4:5], v[122:123]
	v_pk_add_f32 v[2:3], v[2:3], v[128:129]
	v_pk_add_f32 v[0:1], v[0:1], v[126:127]
	global_store_dwordx4 v[130:131], v[62:65], off
	global_store_dwordx4 v[130:131], v[58:61], off offset:64
	global_store_dwordx4 v[130:131], v[42:45], off offset:512
	global_store_dwordx4 v[130:131], v[34:37], off offset:576
	global_store_dwordx4 v[132:133], v[54:57], off
	global_store_dwordx4 v[132:133], v[50:53], off offset:64
	global_store_dwordx4 v[132:133], v[26:29], off offset:512
	global_store_dwordx4 v[132:133], v[22:25], off offset:576
	global_store_dwordx4 v[134:135], v[46:49], off
	global_store_dwordx4 v[134:135], v[38:41], off offset:64
	global_store_dwordx4 v[134:135], v[12:15], off offset:512
	global_store_dwordx4 v[134:135], v[8:11], off offset:576
	global_store_dwordx4 v[136:137], v[30:33], off
	global_store_dwordx4 v[136:137], v[18:21], off offset:64
	global_store_dwordx4 v[136:137], v[4:7], off offset:512
	global_store_dwordx4 v[136:137], v[0:3], off offset:576
	v_readlane_b32 s82, v255, 5
	s_and_b64 vcc, exec, s[38:39]
	s_mov_b32 s2, s4
	s_mov_b32 s18, s8
	s_mov_b64 s[40:41], s[16:17]
	s_mov_b64 s[22:23], s[14:15]
	v_readlane_b32 s83, v255, 6
	s_cbranch_vccz .LBB0_167
	s_waitcnt vmcnt(0)
	s_cmpk_gt_u32 s35, 0xff
	s_cbranch_scc1 .LBB0_178
	s_barrier

.LBB0_210:
	s_ashr_i32 s91, s90, 31
	v_cmp_lt_i64_e64 s[38:39], s[4:5], v[202:203]
	s_lshl_b64 s[4:5], s[90:91], 24
	s_add_u32 s2, s50, s4
	s_addc_u32 s9, s51, s5
	s_ashr_i32 s93, s92, 31
	s_lshl_b64 s[4:5], s[92:93], 18
	s_add_u32 s56, s2, s4
	s_addc_u32 s57, s9, s5
	s_and_b64 s[4:5], s[38:39], exec
	s_cselect_b32 s2, s57, s19
	s_cselect_b32 s9, s56, s18
	s_lshl_b64 s[4:5], s[90:91], 20
	s_add_u32 s12, s37, s4
	s_addc_u32 s15, s48, s5
	s_ashr_i32 s55, s54, 31
	s_lshl_b64 s[4:5], s[54:55], 18
	s_add_u32 s4, s12, s4
	s_addc_u32 s5, s15, s5
	s_and_b64 s[22:23], s[38:39], exec
	s_cselect_b32 s12, s5, s17
	s_cselect_b32 s15, s4, s16
	s_add_u32 s34, s16, 0x100
	s_addc_u32 s40, s17, 0
	s_add_u32 s16, s18, 0x20080
	s_addc_u32 s17, s19, 0
	s_mov_b32 s41, -2
	v_readfirstlane_b32 s98, v228
	s_lshr_b32 s98, s98, 8
	s_cmp_lg_u32 s98, 0
	s_cbranch_scc0 .Lprio_skip_3
	s_setprio 1
.Lprio_skip_3:
.LBB0_211:
	s_add_u32 s18, s16, 0xfffe0080
	s_addc_u32 s19, s17, -1
	s_add_i32 s42, 0, 0x10000
	v_add_u32_e32 v12, s42, v241
	ds_read_b128 v[0:3], v12
	ds_read_b128 v[4:7], v12 offset:1024
	ds_read_b128 v[8:11], v12 offset:2048
	ds_read_b128 v[12:15], v12 offset:3072
	s_cmp_eq_u32 s41, 4
	s_cselect_b32 s23, s2, s19
	s_cselect_b32 s22, s9, s18
	s_cselect_b32 s19, s12, s40
	s_cselect_b32 s18, s15, s34
	v_lshl_add_u64 v[178:179], s[16:17], 0, v[216:217]
	s_add_i32 m0, s52, 0xc000
	ds_read_b128 v[146:149], v243
	ds_read_b128 v[150:153], v243 offset:1024
	ds_read_b128 v[154:157], v243 offset:2048
	ds_read_b128 v[158:161], v243 offset:3072
	ds_read_b128 v[162:165], v243 offset:4096
	ds_read_b128 v[166:169], v243 offset:5120
	ds_read_b128 v[170:173], v243 offset:6144
	ds_read_b128 v[174:177], v243 offset:7168
	global_load_lds_dwordx4 v[178:179], off
	v_lshl_add_u64 v[178:179], s[16:17], 0, v[214:215]
	s_add_i32 m0, s52, 0xe000
	s_nop 0
	global_load_lds_dwordx4 v[178:179], off
	s_waitcnt lgkmcnt(8)
	s_barrier
	s_waitcnt lgkmcnt(0)
	s_waitcnt lgkmcnt(0)
	v_mfma_f32_16x16x32_bf16 v[142:145], v[0:3], v[146:149], v[142:145]
	v_mfma_f32_16x16x32_bf16 v[138:141], v[8:11], v[146:149], v[138:141]
	v_mfma_f32_16x16x32_bf16 v[134:137], v[0:3], v[154:157], v[134:137]
	v_mfma_f32_16x16x32_bf16 v[130:133], v[8:11], v[154:157], v[130:133]
	v_mfma_f32_16x16x32_bf16 v[126:129], v[0:3], v[162:165], v[126:129]
	v_mfma_f32_16x16x32_bf16 v[122:125], v[8:11], v[162:165], v[122:125]
	v_mfma_f32_16x16x32_bf16 v[118:121], v[0:3], v[170:173], v[118:121]
	v_mfma_f32_16x16x32_bf16 v[114:117], v[8:11], v[170:173], v[114:117]
	v_mfma_f32_16x16x32_bf16 v[142:145], v[4:7], v[150:153], v[142:145]
	v_mfma_f32_16x16x32_bf16 v[138:141], v[12:15], v[150:153], v[138:141]
	v_mfma_f32_16x16x32_bf16 v[134:137], v[4:7], v[158:161], v[134:137]
	v_mfma_f32_16x16x32_bf16 v[130:133], v[12:15], v[158:161], v[130:133]
	v_mfma_f32_16x16x32_bf16 v[126:129], v[4:7], v[166:169], v[126:129]
	v_mfma_f32_16x16x32_bf16 v[122:125], v[12:15], v[166:169], v[122:125]
	v_mfma_f32_16x16x32_bf16 v[118:121], v[4:7], v[174:177], v[118:121]
	v_mfma_f32_16x16x32_bf16 v[114:117], v[12:15], v[174:177], v[114:117]
	s_barrier
	s_add_i32 s55, 0, 0x14000
	s_add_i32 s42, s42, s49
	v_add_u32_e32 v190, s55, v241
	v_lshl_add_u64 v[194:195], s[18:19], 0, v[16:17]
	s_mov_b32 m0, s42
	ds_read_b128 v[178:181], v190
	ds_read_b128 v[182:185], v190 offset:1024
	ds_read_b128 v[186:189], v190 offset:2048
	ds_read_b128 v[190:193], v190 offset:3072
	global_load_lds_dwordx4 v[194:195], off
	v_lshl_add_u64 v[196:197], s[18:19], 0, v[212:213]
	s_add_i32 m0, s42, 0x2000
	s_nop 0
	global_load_lds_dwordx4 v[196:197], off
	s_barrier
	s_waitcnt lgkmcnt(0)
	s_waitcnt lgkmcnt(0)
	v_mfma_f32_16x16x32_bf16 v[110:113], v[178:181], v[146:149], v[110:113]
	v_mfma_f32_16x16x32_bf16 v[106:109], v[186:189], v[146:149], v[106:109]
	v_mfma_f32_16x16x32_bf16 v[102:105], v[178:181], v[154:157], v[102:105]
	v_mfma_f32_16x16x32_bf16 v[98:101], v[186:189], v[154:157], v[98:101]
	v_mfma_f32_16x16x32_bf16 v[94:97], v[178:181], v[162:165], v[94:97]
	v_mfma_f32_16x16x32_bf16 v[90:93], v[186:189], v[162:165], v[90:93]
	v_mfma_f32_16x16x32_bf16 v[86:89], v[178:181], v[170:173], v[86:89]
	v_mfma_f32_16x16x32_bf16 v[82:85], v[186:189], v[170:173], v[82:85]
	v_mfma_f32_16x16x32_bf16 v[110:113], v[182:185], v[150:153], v[110:113]
	v_mfma_f32_16x16x32_bf16 v[106:109], v[190:193], v[150:153], v[106:109]
	v_mfma_f32_16x16x32_bf16 v[102:105], v[182:185], v[158:161], v[102:105]
	v_mfma_f32_16x16x32_bf16 v[98:101], v[190:193], v[158:161], v[98:101]
	v_mfma_f32_16x16x32_bf16 v[94:97], v[182:185], v[166:169], v[94:97]
	v_mfma_f32_16x16x32_bf16 v[90:93], v[190:193], v[166:169], v[90:93]
	v_mfma_f32_16x16x32_bf16 v[86:89], v[182:185], v[174:177], v[86:89]
	v_mfma_f32_16x16x32_bf16 v[82:85], v[190:193], v[174:177], v[82:85]
	s_mov_b32 m0, s52
	v_lshl_add_u64 v[218:219], s[22:23], 0, v[208:209]
	s_barrier
	ds_read_b128 v[146:149], v243 offset:16384
	ds_read_b128 v[150:153], v243 offset:17408
	ds_read_b128 v[154:157], v243 offset:18432
	ds_read_b128 v[158:161], v243 offset:19456
	ds_read_b128 v[162:165], v243 offset:20480
	ds_read_b128 v[166:169], v243 offset:21504
	ds_read_b128 v[170:173], v243 offset:22528
	ds_read_b128 v[174:177], v243 offset:23552
	global_load_lds_dwordx4 v[218:219], off
	v_lshl_add_u64 v[220:221], s[22:23], 0, v[210:211]
	s_mov_b32 m0, s58
	s_nop 0
	global_load_lds_dwordx4 v[220:221], off
	s_barrier
	s_waitcnt lgkmcnt(0)
	s_waitcnt lgkmcnt(0)
	v_mfma_f32_16x16x32_bf16 v[78:81], v[0:3], v[146:149], v[78:81]
	v_mfma_f32_16x16x32_bf16 v[74:77], v[8:11], v[146:149], v[74:77]
	v_mfma_f32_16x16x32_bf16 v[70:73], v[0:3], v[154:157], v[70:73]
	v_mfma_f32_16x16x32_bf16 v[66:69], v[8:11], v[154:157], v[66:69]
	v_mfma_f32_16x16x32_bf16 v[62:65], v[0:3], v[162:165], v[62:65]
	v_mfma_f32_16x16x32_bf16 v[58:61], v[8:11], v[162:165], v[58:61]
	v_mfma_f32_16x16x32_bf16 v[0:3], v[0:3], v[170:173], v[54:57]
	v_mfma_f32_16x16x32_bf16 v[78:81], v[4:7], v[150:153], v[78:81]
	v_mfma_f32_16x16x32_bf16 v[74:77], v[12:15], v[150:153], v[74:77]
	v_mfma_f32_16x16x32_bf16 v[70:73], v[4:7], v[158:161], v[70:73]
	v_mfma_f32_16x16x32_bf16 v[66:69], v[12:15], v[158:161], v[66:69]
	v_mfma_f32_16x16x32_bf16 v[62:65], v[4:7], v[166:169], v[62:65]
	v_mfma_f32_16x16x32_bf16 v[58:61], v[12:15], v[166:169], v[58:61]
	v_mfma_f32_16x16x32_bf16 v[0:3], v[4:7], v[174:177], v[0:3]
	v_mfma_f32_16x16x32_bf16 v[4:7], v[8:11], v[170:173], v[50:53]
	v_mfma_f32_16x16x32_bf16 v[4:7], v[12:15], v[174:177], v[4:7]
	s_barrier
	s_add_u32 s42, s18, 0x20000
	s_addc_u32 s43, s19, 0
	s_add_i32 s55, s55, s49
	v_lshl_add_u64 v[8:9], s[42:43], 0, v[16:17]
	s_mov_b32 m0, s55
	s_nop 0
	global_load_lds_dwordx4 v[8:9], off
	v_lshl_add_u64 v[8:9], s[42:43], 0, v[212:213]
	s_add_i32 m0, s55, 0x2000
	s_nop 0
	global_load_lds_dwordx4 v[8:9], off
	s_waitcnt vmcnt(6)
	s_barrier
	v_mfma_f32_16x16x32_bf16 v[38:41], v[178:181], v[154:157], v[38:41]
	v_mfma_f32_16x16x32_bf16 v[34:37], v[186:189], v[154:157], v[34:37]
	v_mfma_f32_16x16x32_bf16 v[30:33], v[178:181], v[162:165], v[30:33]
	v_mfma_f32_16x16x32_bf16 v[26:29], v[186:189], v[162:165], v[26:29]
	v_mfma_f32_16x16x32_bf16 v[22:25], v[178:181], v[170:173], v[22:25]
	v_mfma_f32_16x16x32_bf16 v[18:21], v[186:189], v[170:173], v[18:21]
	v_mfma_f32_16x16x32_bf16 v[8:11], v[178:181], v[146:149], v[46:49]
	v_mfma_f32_16x16x32_bf16 v[12:15], v[186:189], v[146:149], v[42:45]
	v_mfma_f32_16x16x32_bf16 v[38:41], v[182:185], v[158:161], v[38:41]
	v_mfma_f32_16x16x32_bf16 v[34:37], v[190:193], v[158:161], v[34:37]
	v_mfma_f32_16x16x32_bf16 v[30:33], v[182:185], v[166:169], v[30:33]
	v_mfma_f32_16x16x32_bf16 v[26:29], v[190:193], v[166:169], v[26:29]
	v_mfma_f32_16x16x32_bf16 v[22:25], v[182:185], v[174:177], v[22:25]
	v_mfma_f32_16x16x32_bf16 v[18:21], v[190:193], v[174:177], v[18:21]
	v_mfma_f32_16x16x32_bf16 v[8:11], v[182:185], v[150:153], v[8:11]
	v_mfma_f32_16x16x32_bf16 v[12:15], v[190:193], v[150:153], v[12:15]
	s_add_i32 s42, 0, 0x18000
	v_add_u32_e32 v54, s42, v241
	s_barrier
	ds_read_b128 v[42:45], v54
	ds_read_b128 v[46:49], v54 offset:1024
	ds_read_b128 v[50:53], v54 offset:2048
	ds_read_b128 v[146:149], v54 offset:3072
	s_add_u32 s22, s22, 0x20000
	s_addc_u32 s23, s23, 0
	s_mov_b32 m0, s59
	v_lshl_add_u64 v[178:179], s[22:23], 0, v[208:209]
	ds_read_b128 v[54:57], v243 offset:32768
	ds_read_b128 v[150:153], v243 offset:33792
	ds_read_b128 v[154:157], v243 offset:34816
	ds_read_b128 v[158:161], v243 offset:35840
	ds_read_b128 v[162:165], v243 offset:36864
	ds_read_b128 v[166:169], v243 offset:37888
	ds_read_b128 v[170:173], v243 offset:38912
	ds_read_b128 v[174:177], v243 offset:39936
	global_load_lds_dwordx4 v[178:179], off
	v_lshl_add_u64 v[178:179], s[22:23], 0, v[210:211]
	s_mov_b32 m0, s60
	s_nop 0
	global_load_lds_dwordx4 v[178:179], off
	s_waitcnt lgkmcnt(8)
	s_barrier
	s_waitcnt lgkmcnt(0)
	s_waitcnt lgkmcnt(0)
	v_mfma_f32_16x16x32_bf16 v[142:145], v[42:45], v[54:57], v[142:145]
	v_mfma_f32_16x16x32_bf16 v[138:141], v[50:53], v[54:57], v[138:141]
	v_mfma_f32_16x16x32_bf16 v[134:137], v[42:45], v[154:157], v[134:137]
	v_mfma_f32_16x16x32_bf16 v[130:133], v[50:53], v[154:157], v[130:133]
	v_mfma_f32_16x16x32_bf16 v[126:129], v[42:45], v[162:165], v[126:129]
	v_mfma_f32_16x16x32_bf16 v[122:125], v[50:53], v[162:165], v[122:125]
	v_mfma_f32_16x16x32_bf16 v[118:121], v[42:45], v[170:173], v[118:121]
	v_mfma_f32_16x16x32_bf16 v[114:117], v[50:53], v[170:173], v[114:117]
	v_mfma_f32_16x16x32_bf16 v[142:145], v[46:49], v[150:153], v[142:145]
	v_mfma_f32_16x16x32_bf16 v[138:141], v[146:149], v[150:153], v[138:141]
	v_mfma_f32_16x16x32_bf16 v[134:137], v[46:49], v[158:161], v[134:137]
	v_mfma_f32_16x16x32_bf16 v[130:133], v[146:149], v[158:161], v[130:133]
	v_mfma_f32_16x16x32_bf16 v[126:129], v[46:49], v[166:169], v[126:129]
	v_mfma_f32_16x16x32_bf16 v[122:125], v[146:149], v[166:169], v[122:125]
	v_mfma_f32_16x16x32_bf16 v[118:121], v[46:49], v[174:177], v[118:121]
	v_mfma_f32_16x16x32_bf16 v[114:117], v[146:149], v[174:177], v[114:117]
	s_barrier
	s_add_i32 s22, 0, 0x1c000
	s_add_i32 s23, s42, s49
	v_add_u32_e32 v190, s22, v241
	v_lshl_add_u64 v[194:195], v[194:195], 0, s[10:11]
	s_mov_b32 m0, s23
	ds_read_b128 v[178:181], v190
	ds_read_b128 v[182:185], v190 offset:1024
	ds_read_b128 v[186:189], v190 offset:2048
	ds_read_b128 v[190:193], v190 offset:3072
	global_load_lds_dwordx4 v[194:195], off
	v_lshl_add_u64 v[194:195], v[196:197], 0, s[10:11]
	s_add_i32 m0, s23, 0x2000
	s_nop 0
	global_load_lds_dwordx4 v[194:195], off
	s_barrier
	s_waitcnt lgkmcnt(0)
	s_waitcnt lgkmcnt(0)
	v_mfma_f32_16x16x32_bf16 v[110:113], v[178:181], v[54:57], v[110:113]
	v_mfma_f32_16x16x32_bf16 v[54:57], v[186:189], v[54:57], v[106:109]
	v_mfma_f32_16x16x32_bf16 v[106:109], v[190:193], v[150:153], v[54:57]
	v_mfma_f32_16x16x32_bf16 v[54:57], v[178:181], v[154:157], v[102:105]
	v_mfma_f32_16x16x32_bf16 v[102:105], v[182:185], v[158:161], v[54:57]
	v_mfma_f32_16x16x32_bf16 v[54:57], v[186:189], v[154:157], v[98:101]
	v_mfma_f32_16x16x32_bf16 v[98:101], v[190:193], v[158:161], v[54:57]
	v_mfma_f32_16x16x32_bf16 v[54:57], v[178:181], v[162:165], v[94:97]
	v_mfma_f32_16x16x32_bf16 v[94:97], v[182:185], v[166:169], v[54:57]
	v_mfma_f32_16x16x32_bf16 v[54:57], v[186:189], v[162:165], v[90:93]
	v_mfma_f32_16x16x32_bf16 v[90:93], v[190:193], v[166:169], v[54:57]
	v_mfma_f32_16x16x32_bf16 v[54:57], v[178:181], v[170:173], v[86:89]
	v_mfma_f32_16x16x32_bf16 v[86:89], v[182:185], v[174:177], v[54:57]
	v_mfma_f32_16x16x32_bf16 v[54:57], v[186:189], v[170:173], v[82:85]
	v_mfma_f32_16x16x32_bf16 v[110:113], v[182:185], v[150:153], v[110:113]
	v_mfma_f32_16x16x32_bf16 v[82:85], v[190:193], v[174:177], v[54:57]
	s_mov_b32 m0, s61
	s_nop 3
	v_lshl_add_u64 v[54:55], v[218:219], 0, s[10:11]
	s_barrier
	ds_read_b128 v[150:153], v243 offset:49152
	ds_read_b128 v[154:157], v243 offset:50176
	ds_read_b128 v[158:161], v243 offset:51200
	ds_read_b128 v[162:165], v243 offset:52224
	ds_read_b128 v[166:169], v243 offset:53248
	ds_read_b128 v[170:173], v243 offset:54272
	ds_read_b128 v[174:177], v243 offset:55296
	ds_read_b128 v[194:197], v243 offset:56320
	global_load_lds_dwordx4 v[54:55], off
	v_lshl_add_u64 v[54:55], v[220:221], 0, s[10:11]
	s_mov_b32 m0, s35
	s_nop 0
	global_load_lds_dwordx4 v[54:55], off
	s_barrier
	s_waitcnt lgkmcnt(0)
	s_waitcnt lgkmcnt(0)
	v_mfma_f32_16x16x32_bf16 v[54:57], v[42:45], v[150:153], v[78:81]
	v_mfma_f32_16x16x32_bf16 v[78:81], v[46:49], v[154:157], v[54:57]
	v_mfma_f32_16x16x32_bf16 v[54:57], v[50:53], v[150:153], v[74:77]
	v_mfma_f32_16x16x32_bf16 v[74:77], v[146:149], v[154:157], v[54:57]
	v_mfma_f32_16x16x32_bf16 v[54:57], v[42:45], v[158:161], v[70:73]
	v_mfma_f32_16x16x32_bf16 v[70:73], v[46:49], v[162:165], v[54:57]
	v_mfma_f32_16x16x32_bf16 v[54:57], v[50:53], v[158:161], v[66:69]
	v_mfma_f32_16x16x32_bf16 v[66:69], v[146:149], v[162:165], v[54:57]
	v_mfma_f32_16x16x32_bf16 v[54:57], v[42:45], v[166:169], v[62:65]
	v_mfma_f32_16x16x32_bf16 v[62:65], v[46:49], v[170:173], v[54:57]
	v_mfma_f32_16x16x32_bf16 v[54:57], v[50:53], v[166:169], v[58:61]
	v_mfma_f32_16x16x32_bf16 v[0:3], v[42:45], v[174:177], v[0:3]
	v_mfma_f32_16x16x32_bf16 v[58:61], v[146:149], v[170:173], v[54:57]
	v_mfma_f32_16x16x32_bf16 v[54:57], v[46:49], v[194:197], v[0:3]
	v_mfma_f32_16x16x32_bf16 v[0:3], v[50:53], v[174:177], v[4:7]
	v_mfma_f32_16x16x32_bf16 v[50:53], v[146:149], v[194:197], v[0:3]
	s_barrier
	s_add_u32 s18, s18, 0x20080
	s_addc_u32 s19, s19, 0
	s_add_i32 s22, s22, s49
	s_nop 1
	v_lshl_add_u64 v[0:1], s[18:19], 0, v[16:17]
	s_mov_b32 m0, s22
	s_nop 0
	global_load_lds_dwordx4 v[0:1], off
	v_lshl_add_u64 v[0:1], s[18:19], 0, v[212:213]
	s_add_i32 m0, s22, 0x2000
	s_nop 0
	global_load_lds_dwordx4 v[0:1], off
	s_waitcnt vmcnt(6)
	s_barrier
	v_mfma_f32_16x16x32_bf16 v[0:3], v[178:181], v[150:153], v[8:11]
	v_mfma_f32_16x16x32_bf16 v[46:49], v[182:185], v[154:157], v[0:3]
	v_mfma_f32_16x16x32_bf16 v[0:3], v[186:189], v[150:153], v[12:15]
	v_mfma_f32_16x16x32_bf16 v[42:45], v[190:193], v[154:157], v[0:3]
	v_mfma_f32_16x16x32_bf16 v[0:3], v[178:181], v[158:161], v[38:41]
	v_mfma_f32_16x16x32_bf16 v[38:41], v[182:185], v[162:165], v[0:3]
	v_mfma_f32_16x16x32_bf16 v[0:3], v[186:189], v[158:161], v[34:37]
	v_mfma_f32_16x16x32_bf16 v[34:37], v[190:193], v[162:165], v[0:3]
	v_mfma_f32_16x16x32_bf16 v[0:3], v[178:181], v[166:169], v[30:33]
	v_mfma_f32_16x16x32_bf16 v[30:33], v[182:185], v[170:173], v[0:3]
	v_mfma_f32_16x16x32_bf16 v[0:3], v[186:189], v[166:169], v[26:29]
	v_mfma_f32_16x16x32_bf16 v[26:29], v[190:193], v[170:173], v[0:3]
	v_mfma_f32_16x16x32_bf16 v[0:3], v[178:181], v[174:177], v[22:25]
	v_mfma_f32_16x16x32_bf16 v[22:25], v[182:185], v[194:197], v[0:3]
	v_mfma_f32_16x16x32_bf16 v[0:3], v[186:189], v[174:177], v[18:21]
	v_mfma_f32_16x16x32_bf16 v[18:21], v[190:193], v[194:197], v[0:3]
	s_add_i32 s41, s41, 2
	s_add_u32 s34, s34, 0x100
	s_addc_u32 s40, s40, 0
	s_add_u32 s16, s16, 0x100
	s_addc_u32 s17, s17, 0
	s_cmp_gt_u32 s41, 5
	s_barrier
	s_cbranch_scc0 .LBB0_211
	s_cmp_eq_u32 s84, 3
	s_cselect_b64 s[16:17], -1, 0
	s_cmp_lg_u32 s84, 3
	v_lshl_add_u32 v220, s8, 8, v240
	v_lshl_or_b32 v218, s14, 8, v242
	s_cselect_b64 s[8:9], -1, 0
	s_lshl_b32 s14, s84, 10
	v_mov_b64_e32 v[0:1], s[94:95]
	s_ashr_i32 s15, s14, 31
	v_mad_i64_i32 v[0:1], s[18:19], v220, s66, v[0:1]
	v_ashrrev_i32_e32 v219, 31, v218
	v_lshl_add_u64 v[0:1], s[14:15], 1, v[0:1]
	v_lshl_add_u64 v[4:5], v[218:219], 1, v[0:1]
	v_add_co_u32_e32 v0, vcc, 0x2000, v4
	s_mov_b64 s[18:19], 0x2400
	s_nop 0
	v_addc_co_u32_e32 v1, vcc, 0, v5, vcc
	global_load_dwordx4 v[0:3], v[0:1], off offset:1024
	s_and_b64 vcc, exec, s[16:17]
	v_lshl_add_u64 v[4:5], v[4:5], 0, s[18:19]
	s_cbranch_vccnz .LBB0_214
	global_load_dwordx4 v[12:15], v[4:5], off offset:2048

.LBB0_978:
	s_ashr_i32 s9, s8, 31
	v_cmp_lt_i64_e32 vcc, s[14:15], v[206:207]
	s_lshl_b64 s[14:15], s[8:9], 19
	s_add_u32 s14, s30, s14
	s_addc_u32 s15, s31, s15
	s_and_b64 s[16:17], vcc, exec
	s_cselect_b32 s9, s15, s23
	s_cselect_b32 s56, s14, s22
	s_ashr_i32 s5, s4, 31
	s_lshl_b64 s[16:17], s[4:5], 19
	s_add_u32 s16, s44, s16
	s_addc_u32 s17, s45, s17
	s_and_b64 s[28:29], vcc, exec
	s_cselect_b32 s5, s17, s21
	s_cselect_b32 s57, s16, s20
	s_add_u32 s58, s20, 0x100
	s_addc_u32 s59, s21, 0
	s_add_u32 s20, s22, 0x40080
	v_mov_b32_e32 v26, 0
	s_addc_u32 s21, s23, 0
	s_mov_b32 s60, -2
	v_mov_b32_e32 v27, v26
	v_mov_b32_e32 v28, v26
	v_mov_b32_e32 v29, v26
	v_mov_b32_e32 v38, v26
	v_mov_b32_e32 v39, v26
	v_mov_b32_e32 v40, v26
	v_mov_b32_e32 v41, v26
	v_mov_b32_e32 v46, v26
	v_mov_b32_e32 v47, v26
	v_mov_b32_e32 v48, v26
	v_mov_b32_e32 v49, v26
	v_mov_b32_e32 v58, v26
	v_mov_b32_e32 v59, v26
	v_mov_b32_e32 v60, v26
	v_mov_b32_e32 v61, v26
	v_mov_b32_e32 v82, v26
	v_mov_b32_e32 v83, v26
	v_mov_b32_e32 v84, v26
	v_mov_b32_e32 v85, v26
	v_mov_b32_e32 v86, v26
	v_mov_b32_e32 v87, v26
	v_mov_b32_e32 v88, v26
	v_mov_b32_e32 v89, v26
	v_mov_b32_e32 v90, v26
	v_mov_b32_e32 v91, v26
	v_mov_b32_e32 v92, v26
	v_mov_b32_e32 v93, v26
	v_mov_b32_e32 v94, v26
	v_mov_b32_e32 v95, v26
	v_mov_b32_e32 v96, v26
	v_mov_b32_e32 v97, v26
	v_mov_b32_e32 v0, v26
	v_mov_b32_e32 v1, v26
	v_mov_b32_e32 v2, v26
	v_mov_b32_e32 v3, v26
	v_mov_b32_e32 v4, v26
	v_mov_b32_e32 v5, v26
	v_mov_b32_e32 v6, v26
	v_mov_b32_e32 v7, v26
	v_mov_b32_e32 v8, v26
	v_mov_b32_e32 v9, v26
	v_mov_b32_e32 v10, v26
	v_mov_b32_e32 v11, v26
	v_mov_b32_e32 v12, v26
	v_mov_b32_e32 v13, v26
	v_mov_b32_e32 v14, v26
	v_mov_b32_e32 v15, v26
	v_mov_b32_e32 v18, v26
	v_mov_b32_e32 v19, v26
	v_mov_b32_e32 v20, v26
	v_mov_b32_e32 v21, v26
	v_mov_b32_e32 v22, v26
	v_mov_b32_e32 v23, v26
	v_mov_b32_e32 v24, v26
	v_mov_b32_e32 v25, v26
	v_mov_b32_e32 v30, v26
	v_mov_b32_e32 v31, v26
	v_mov_b32_e32 v32, v26
	v_mov_b32_e32 v33, v26
	s_waitcnt lgkmcnt(0)
	v_mov_b32_e32 v34, v26
	v_mov_b32_e32 v35, v26
	v_mov_b32_e32 v36, v26
	v_mov_b32_e32 v37, v26
	v_mov_b32_e32 v98, v26
	v_mov_b32_e32 v99, v26
	v_mov_b32_e32 v100, v26
	v_mov_b32_e32 v101, v26
	v_mov_b32_e32 v102, v26
	v_mov_b32_e32 v103, v26
	v_mov_b32_e32 v104, v26
	v_mov_b32_e32 v105, v26
	v_mov_b32_e32 v106, v26
	v_mov_b32_e32 v107, v26
	v_mov_b32_e32 v108, v26
	v_mov_b32_e32 v109, v26
	v_mov_b32_e32 v110, v26
	v_mov_b32_e32 v111, v26
	v_mov_b32_e32 v112, v26
	v_mov_b32_e32 v113, v26
	v_mov_b32_e32 v114, v26
	v_mov_b32_e32 v115, v26
	v_mov_b32_e32 v116, v26
	v_mov_b32_e32 v117, v26
	v_mov_b32_e32 v118, v26
	v_mov_b32_e32 v119, v26
	v_mov_b32_e32 v120, v26
	v_mov_b32_e32 v121, v26
	v_mov_b32_e32 v122, v26
	v_mov_b32_e32 v123, v26
	v_mov_b32_e32 v124, v26
	v_mov_b32_e32 v125, v26
	v_mov_b32_e32 v126, v26
	v_mov_b32_e32 v127, v26
	v_mov_b32_e32 v128, v26
	v_mov_b32_e32 v129, v26
	v_mov_b32_e32 v42, v26
	v_mov_b32_e32 v43, v26
	v_mov_b32_e32 v44, v26
	v_mov_b32_e32 v45, v26
	v_mov_b32_e32 v50, v26
	v_mov_b32_e32 v51, v26
	v_mov_b32_e32 v52, v26
	v_mov_b32_e32 v53, v26
	v_mov_b32_e32 v54, v26
	v_mov_b32_e32 v55, v26
	v_mov_b32_e32 v56, v26
	v_mov_b32_e32 v57, v26
	v_mov_b32_e32 v62, v26
	v_mov_b32_e32 v63, v26
	v_mov_b32_e32 v64, v26
	v_mov_b32_e32 v65, v26
	v_mov_b32_e32 v66, v26
	v_mov_b32_e32 v67, v26
	v_mov_b32_e32 v68, v26
	v_mov_b32_e32 v69, v26
	v_mov_b32_e32 v70, v26
	v_mov_b32_e32 v71, v26
	v_mov_b32_e32 v72, v26
	v_mov_b32_e32 v73, v26
	v_mov_b32_e32 v74, v26
	v_mov_b32_e32 v75, v26
	v_mov_b32_e32 v76, v26
	v_mov_b32_e32 v77, v26
	v_mov_b32_e32 v78, v26
	v_mov_b32_e32 v79, v26
	v_mov_b32_e32 v80, v26
	v_mov_b32_e32 v81, v26
	v_readfirstlane_b32 s98, v228
	s_lshr_b32 s98, s98, 8
	s_cmp_lg_u32 s98, 0
	s_cbranch_scc0 .Lprio_skip_4
	s_setprio 1
.Lprio_skip_4:
.LBB0_979:
	s_add_u32 s22, s20, 0xfffc0080
	s_addc_u32 s23, s21, -1
	s_add_i32 s61, 0, 0x10000
	v_add_u32_e32 v144, s61, v147
	ds_read_b128 v[140:143], v144
	ds_read_b128 v[150:153], v144 offset:1024
	ds_read_b128 v[154:157], v144 offset:2048
	ds_read_b128 v[158:161], v144 offset:3072
	s_cmp_eq_u32 s60, 12
	s_cselect_b32 s29, s9, s23
	s_cselect_b32 s28, s56, s22
	s_cselect_b32 s23, s5, s59
	s_cselect_b32 s22, s57, s58
	v_lshl_add_u64 v[144:145], s[20:21], 0, v[138:139]
	s_add_i32 m0, s12, 0xc000
	ds_read_b128 v[162:165], v149
	ds_read_b128 v[166:169], v149 offset:1024
	ds_read_b128 v[170:173], v149 offset:2048
	ds_read_b128 v[174:177], v149 offset:3072
	ds_read_b128 v[178:181], v149 offset:4096
	ds_read_b128 v[182:185], v149 offset:5120
	ds_read_b128 v[186:189], v149 offset:6144
	ds_read_b128 v[190:193], v149 offset:7168
	global_load_lds_dwordx4 v[144:145], off
	v_lshl_add_u64 v[144:145], s[20:21], 0, v[136:137]
	s_add_i32 m0, s12, 0xe000
	s_nop 0
	global_load_lds_dwordx4 v[144:145], off
	s_waitcnt lgkmcnt(8)
	s_barrier
	s_waitcnt lgkmcnt(0)
	s_waitcnt lgkmcnt(0)
	v_mfma_f32_16x16x32_bf16 v[78:81], v[140:143], v[162:165], v[78:81]
	v_mfma_f32_16x16x32_bf16 v[74:77], v[154:157], v[162:165], v[74:77]
	v_mfma_f32_16x16x32_bf16 v[70:73], v[140:143], v[170:173], v[70:73]
	v_mfma_f32_16x16x32_bf16 v[66:69], v[154:157], v[170:173], v[66:69]
	v_mfma_f32_16x16x32_bf16 v[62:65], v[140:143], v[178:181], v[62:65]
	v_mfma_f32_16x16x32_bf16 v[54:57], v[154:157], v[178:181], v[54:57]
	v_mfma_f32_16x16x32_bf16 v[50:53], v[140:143], v[186:189], v[50:53]
	v_mfma_f32_16x16x32_bf16 v[42:45], v[154:157], v[186:189], v[42:45]
	v_mfma_f32_16x16x32_bf16 v[78:81], v[150:153], v[166:169], v[78:81]
	v_mfma_f32_16x16x32_bf16 v[74:77], v[158:161], v[166:169], v[74:77]
	v_mfma_f32_16x16x32_bf16 v[70:73], v[150:153], v[174:177], v[70:73]
	v_mfma_f32_16x16x32_bf16 v[66:69], v[158:161], v[174:177], v[66:69]
	v_mfma_f32_16x16x32_bf16 v[62:65], v[150:153], v[182:185], v[62:65]
	v_mfma_f32_16x16x32_bf16 v[54:57], v[158:161], v[182:185], v[54:57]
	v_mfma_f32_16x16x32_bf16 v[50:53], v[150:153], v[190:193], v[50:53]
	v_mfma_f32_16x16x32_bf16 v[42:45], v[158:161], v[190:193], v[42:45]
	s_barrier
	s_add_i32 s79, 0, 0x14000
	v_add_u32_e32 v144, s79, v147
	s_add_i32 s61, s61, s48
	ds_read_b128 v[194:197], v144
	ds_read_b128 v[208:211], v144 offset:1024
	ds_read_b128 v[212:215], v144 offset:2048
	ds_read_b128 v[216:219], v144 offset:3072
	v_lshl_add_u64 v[144:145], s[22:23], 0, v[16:17]
	s_mov_b32 m0, s61
	v_lshl_add_u64 v[220:221], s[22:23], 0, v[130:131]
	global_load_lds_dwordx4 v[144:145], off
	s_add_i32 m0, s61, 0x2000
	s_nop 0
	global_load_lds_dwordx4 v[220:221], off
	s_barrier
	s_waitcnt lgkmcnt(0)
	s_waitcnt lgkmcnt(0)
	v_mfma_f32_16x16x32_bf16 v[126:129], v[194:197], v[162:165], v[126:129]
	v_mfma_f32_16x16x32_bf16 v[122:125], v[212:215], v[162:165], v[122:125]
	v_mfma_f32_16x16x32_bf16 v[118:121], v[194:197], v[170:173], v[118:121]
	v_mfma_f32_16x16x32_bf16 v[114:117], v[212:215], v[170:173], v[114:117]
	v_mfma_f32_16x16x32_bf16 v[110:113], v[194:197], v[178:181], v[110:113]
	v_mfma_f32_16x16x32_bf16 v[106:109], v[212:215], v[178:181], v[106:109]
	v_mfma_f32_16x16x32_bf16 v[102:105], v[194:197], v[186:189], v[102:105]
	v_mfma_f32_16x16x32_bf16 v[98:101], v[212:215], v[186:189], v[98:101]
	v_mfma_f32_16x16x32_bf16 v[126:129], v[208:211], v[166:169], v[126:129]
	v_mfma_f32_16x16x32_bf16 v[122:125], v[216:219], v[166:169], v[122:125]
	v_mfma_f32_16x16x32_bf16 v[118:121], v[208:211], v[174:177], v[118:121]
	v_mfma_f32_16x16x32_bf16 v[114:117], v[216:219], v[174:177], v[114:117]
	v_mfma_f32_16x16x32_bf16 v[110:113], v[208:211], v[182:185], v[110:113]
	v_mfma_f32_16x16x32_bf16 v[106:109], v[216:219], v[182:185], v[106:109]
	v_mfma_f32_16x16x32_bf16 v[102:105], v[208:211], v[190:193], v[102:105]
	v_mfma_f32_16x16x32_bf16 v[98:101], v[216:219], v[190:193], v[98:101]
	s_mov_b32 m0, s12
	v_lshl_add_u64 v[222:223], s[28:29], 0, v[134:135]
	s_barrier
	ds_read_b128 v[162:165], v149 offset:16384
	ds_read_b128 v[166:169], v149 offset:17408
	ds_read_b128 v[170:173], v149 offset:18432
	ds_read_b128 v[174:177], v149 offset:19456
	ds_read_b128 v[178:181], v149 offset:20480
	ds_read_b128 v[182:185], v149 offset:21504
	ds_read_b128 v[186:189], v149 offset:22528
	ds_read_b128 v[190:193], v149 offset:23552
	global_load_lds_dwordx4 v[222:223], off
	v_lshl_add_u64 v[224:225], s[28:29], 0, v[132:133]
	s_mov_b32 m0, s34
	s_nop 0
	global_load_lds_dwordx4 v[224:225], off
	s_barrier
	s_waitcnt lgkmcnt(0)
	s_waitcnt lgkmcnt(0)
	v_mfma_f32_16x16x32_bf16 v[34:37], v[140:143], v[162:165], v[34:37]
	v_mfma_f32_16x16x32_bf16 v[30:33], v[154:157], v[162:165], v[30:33]
	v_mfma_f32_16x16x32_bf16 v[22:25], v[140:143], v[170:173], v[22:25]
	v_mfma_f32_16x16x32_bf16 v[18:21], v[154:157], v[170:173], v[18:21]
	v_mfma_f32_16x16x32_bf16 v[12:15], v[140:143], v[178:181], v[12:15]
	v_mfma_f32_16x16x32_bf16 v[8:11], v[154:157], v[178:181], v[8:11]
	v_mfma_f32_16x16x32_bf16 v[4:7], v[140:143], v[186:189], v[4:7]
	v_mfma_f32_16x16x32_bf16 v[0:3], v[154:157], v[186:189], v[0:3]
	v_mfma_f32_16x16x32_bf16 v[34:37], v[150:153], v[166:169], v[34:37]
	v_mfma_f32_16x16x32_bf16 v[30:33], v[158:161], v[166:169], v[30:33]
	v_mfma_f32_16x16x32_bf16 v[22:25], v[150:153], v[174:177], v[22:25]
	v_mfma_f32_16x16x32_bf16 v[18:21], v[158:161], v[174:177], v[18:21]
	v_mfma_f32_16x16x32_bf16 v[12:15], v[150:153], v[182:185], v[12:15]
	v_mfma_f32_16x16x32_bf16 v[8:11], v[158:161], v[182:185], v[8:11]
	v_mfma_f32_16x16x32_bf16 v[4:7], v[150:153], v[190:193], v[4:7]
	v_mfma_f32_16x16x32_bf16 v[0:3], v[158:161], v[190:193], v[0:3]
	s_barrier
	s_add_u32 s82, s22, 0x40000
	s_addc_u32 s83, s23, 0
	s_add_i32 s61, s79, s48
	v_lshl_add_u64 v[140:141], s[82:83], 0, v[16:17]
	s_mov_b32 m0, s61
	s_nop 0
	global_load_lds_dwordx4 v[140:141], off
	v_lshl_add_u64 v[140:141], s[82:83], 0, v[130:131]
	s_add_i32 m0, s61, 0x2000
	s_nop 0
	global_load_lds_dwordx4 v[140:141], off
	s_waitcnt vmcnt(6)
	s_barrier
	v_mfma_f32_16x16x32_bf16 v[94:97], v[194:197], v[162:165], v[94:97]
	v_mfma_f32_16x16x32_bf16 v[90:93], v[212:215], v[162:165], v[90:93]
	v_mfma_f32_16x16x32_bf16 v[86:89], v[194:197], v[170:173], v[86:89]
	v_mfma_f32_16x16x32_bf16 v[82:85], v[212:215], v[170:173], v[82:85]
	v_mfma_f32_16x16x32_bf16 v[58:61], v[194:197], v[178:181], v[58:61]
	v_mfma_f32_16x16x32_bf16 v[46:49], v[212:215], v[178:181], v[46:49]
	v_mfma_f32_16x16x32_bf16 v[38:41], v[194:197], v[186:189], v[38:41]
	v_mfma_f32_16x16x32_bf16 v[26:29], v[212:215], v[186:189], v[26:29]
	v_mfma_f32_16x16x32_bf16 v[94:97], v[208:211], v[166:169], v[94:97]
	v_mfma_f32_16x16x32_bf16 v[90:93], v[216:219], v[166:169], v[90:93]
	v_mfma_f32_16x16x32_bf16 v[86:89], v[208:211], v[174:177], v[86:89]
	v_mfma_f32_16x16x32_bf16 v[82:85], v[216:219], v[174:177], v[82:85]
	v_mfma_f32_16x16x32_bf16 v[58:61], v[208:211], v[182:185], v[58:61]
	v_mfma_f32_16x16x32_bf16 v[46:49], v[216:219], v[182:185], v[46:49]
	v_mfma_f32_16x16x32_bf16 v[38:41], v[208:211], v[190:193], v[38:41]
	v_mfma_f32_16x16x32_bf16 v[26:29], v[216:219], v[190:193], v[26:29]
	s_add_i32 s61, 0, 0x18000
	v_add_u32_e32 v158, s61, v147
	s_barrier
	ds_read_b128 v[140:143], v158
	ds_read_b128 v[150:153], v158 offset:1024
	ds_read_b128 v[154:157], v158 offset:2048
	ds_read_b128 v[158:161], v158 offset:3072
	s_add_u32 s28, s28, 0x40000
	s_addc_u32 s29, s29, 0
	s_mov_b32 m0, s49
	v_lshl_add_u64 v[194:195], s[28:29], 0, v[134:135]
	ds_read_b128 v[162:165], v149 offset:32768
	ds_read_b128 v[166:169], v149 offset:33792
	ds_read_b128 v[170:173], v149 offset:34816
	ds_read_b128 v[174:177], v149 offset:35840
	ds_read_b128 v[178:181], v149 offset:36864
	ds_read_b128 v[182:185], v149 offset:37888
	ds_read_b128 v[186:189], v149 offset:38912
	ds_read_b128 v[190:193], v149 offset:39936
	global_load_lds_dwordx4 v[194:195], off
	v_lshl_add_u64 v[194:195], s[28:29], 0, v[132:133]
	s_mov_b32 m0, s50
	s_nop 0
	global_load_lds_dwordx4 v[194:195], off
	s_waitcnt lgkmcnt(8)
	s_barrier
	s_waitcnt lgkmcnt(0)
	s_waitcnt lgkmcnt(0)
	v_mfma_f32_16x16x32_bf16 v[78:81], v[140:143], v[162:165], v[78:81]
	v_mfma_f32_16x16x32_bf16 v[74:77], v[154:157], v[162:165], v[74:77]
	v_mfma_f32_16x16x32_bf16 v[70:73], v[140:143], v[170:173], v[70:73]
	v_mfma_f32_16x16x32_bf16 v[66:69], v[154:157], v[170:173], v[66:69]
	v_mfma_f32_16x16x32_bf16 v[62:65], v[140:143], v[178:181], v[62:65]
	v_mfma_f32_16x16x32_bf16 v[54:57], v[154:157], v[178:181], v[54:57]
	v_mfma_f32_16x16x32_bf16 v[50:53], v[140:143], v[186:189], v[50:53]
	v_mfma_f32_16x16x32_bf16 v[42:45], v[154:157], v[186:189], v[42:45]
	v_mfma_f32_16x16x32_bf16 v[78:81], v[150:153], v[166:169], v[78:81]
	v_mfma_f32_16x16x32_bf16 v[74:77], v[158:161], v[166:169], v[74:77]
	v_mfma_f32_16x16x32_bf16 v[70:73], v[150:153], v[174:177], v[70:73]
	v_mfma_f32_16x16x32_bf16 v[66:69], v[158:161], v[174:177], v[66:69]
	v_mfma_f32_16x16x32_bf16 v[62:65], v[150:153], v[182:185], v[62:65]
	v_mfma_f32_16x16x32_bf16 v[54:57], v[158:161], v[182:185], v[54:57]
	v_mfma_f32_16x16x32_bf16 v[50:53], v[150:153], v[190:193], v[50:53]
	v_mfma_f32_16x16x32_bf16 v[42:45], v[158:161], v[190:193], v[42:45]
	s_barrier
	s_add_i32 s28, 0, 0x1c000
	s_add_i32 s29, s61, s48
	v_add_u32_e32 v216, s28, v147
	v_lshl_add_u64 v[144:145], v[144:145], 0, s[10:11]
	s_mov_b32 m0, s29
	ds_read_b128 v[194:197], v216
	ds_read_b128 v[208:211], v216 offset:1024
	ds_read_b128 v[212:215], v216 offset:2048
	ds_read_b128 v[216:219], v216 offset:3072
	global_load_lds_dwordx4 v[144:145], off
	v_lshl_add_u64 v[144:145], v[220:221], 0, s[10:11]
	s_add_i32 m0, s29, 0x2000
	s_nop 0
	global_load_lds_dwordx4 v[144:145], off
	s_barrier
	s_waitcnt lgkmcnt(0)
	s_waitcnt lgkmcnt(0)
	v_mfma_f32_16x16x32_bf16 v[126:129], v[194:197], v[162:165], v[126:129]
	v_mfma_f32_16x16x32_bf16 v[122:125], v[212:215], v[162:165], v[122:125]
	v_mfma_f32_16x16x32_bf16 v[118:121], v[194:197], v[170:173], v[118:121]
	v_mfma_f32_16x16x32_bf16 v[114:117], v[212:215], v[170:173], v[114:117]
	v_mfma_f32_16x16x32_bf16 v[110:113], v[194:197], v[178:181], v[110:113]
	v_mfma_f32_16x16x32_bf16 v[106:109], v[212:215], v[178:181], v[106:109]
	v_mfma_f32_16x16x32_bf16 v[102:105], v[194:197], v[186:189], v[102:105]
	v_mfma_f32_16x16x32_bf16 v[98:101], v[212:215], v[186:189], v[98:101]
	v_mfma_f32_16x16x32_bf16 v[126:129], v[208:211], v[166:169], v[126:129]
	v_mfma_f32_16x16x32_bf16 v[122:125], v[216:219], v[166:169], v[122:125]
	v_mfma_f32_16x16x32_bf16 v[118:121], v[208:211], v[174:177], v[118:121]
	v_mfma_f32_16x16x32_bf16 v[114:117], v[216:219], v[174:177], v[114:117]
	v_mfma_f32_16x16x32_bf16 v[110:113], v[208:211], v[182:185], v[110:113]
	v_mfma_f32_16x16x32_bf16 v[106:109], v[216:219], v[182:185], v[106:109]
	v_mfma_f32_16x16x32_bf16 v[102:105], v[208:211], v[190:193], v[102:105]
	v_mfma_f32_16x16x32_bf16 v[98:101], v[216:219], v[190:193], v[98:101]
	s_mov_b32 m0, s51
	v_lshl_add_u64 v[144:145], v[222:223], 0, s[10:11]
	s_barrier
	ds_read_b128 v[162:165], v149 offset:49152
	ds_read_b128 v[166:169], v149 offset:50176
	ds_read_b128 v[170:173], v149 offset:51200
	ds_read_b128 v[174:177], v149 offset:52224
	ds_read_b128 v[178:181], v149 offset:53248
	ds_read_b128 v[182:185], v149 offset:54272
	ds_read_b128 v[186:189], v149 offset:55296
	ds_read_b128 v[190:193], v149 offset:56320
	global_load_lds_dwordx4 v[144:145], off
	v_lshl_add_u64 v[144:145], v[224:225], 0, s[10:11]
	s_mov_b32 m0, s52
	s_nop 0
	global_load_lds_dwordx4 v[144:145], off
	s_barrier
	s_waitcnt lgkmcnt(0)
	s_waitcnt lgkmcnt(0)
	v_mfma_f32_16x16x32_bf16 v[34:37], v[140:143], v[162:165], v[34:37]
	v_mfma_f32_16x16x32_bf16 v[30:33], v[154:157], v[162:165], v[30:33]
	v_mfma_f32_16x16x32_bf16 v[22:25], v[140:143], v[170:173], v[22:25]
	v_mfma_f32_16x16x32_bf16 v[18:21], v[154:157], v[170:173], v[18:21]
	v_mfma_f32_16x16x32_bf16 v[12:15], v[140:143], v[178:181], v[12:15]
	v_mfma_f32_16x16x32_bf16 v[8:11], v[154:157], v[178:181], v[8:11]
	v_mfma_f32_16x16x32_bf16 v[4:7], v[140:143], v[186:189], v[4:7]
	v_mfma_f32_16x16x32_bf16 v[0:3], v[154:157], v[186:189], v[0:3]
	v_mfma_f32_16x16x32_bf16 v[34:37], v[150:153], v[166:169], v[34:37]
	v_mfma_f32_16x16x32_bf16 v[30:33], v[158:161], v[166:169], v[30:33]
	v_mfma_f32_16x16x32_bf16 v[22:25], v[150:153], v[174:177], v[22:25]
	v_mfma_f32_16x16x32_bf16 v[18:21], v[158:161], v[174:177], v[18:21]
	v_mfma_f32_16x16x32_bf16 v[12:15], v[150:153], v[182:185], v[12:15]
	v_mfma_f32_16x16x32_bf16 v[8:11], v[158:161], v[182:185], v[8:11]
	v_mfma_f32_16x16x32_bf16 v[4:7], v[150:153], v[190:193], v[4:7]
	v_mfma_f32_16x16x32_bf16 v[0:3], v[158:161], v[190:193], v[0:3]
	s_barrier
	s_add_u32 s22, s22, 0x40080
	s_addc_u32 s23, s23, 0
	s_add_i32 s28, s28, s48
	v_lshl_add_u64 v[140:141], s[22:23], 0, v[16:17]
	s_mov_b32 m0, s28
	s_nop 0
	global_load_lds_dwordx4 v[140:141], off
	v_lshl_add_u64 v[140:141], s[22:23], 0, v[130:131]
	s_add_i32 m0, s28, 0x2000
	s_nop 0
	global_load_lds_dwordx4 v[140:141], off
	s_waitcnt vmcnt(6)
	s_barrier
	v_mfma_f32_16x16x32_bf16 v[94:97], v[194:197], v[162:165], v[94:97]
	v_mfma_f32_16x16x32_bf16 v[90:93], v[212:215], v[162:165], v[90:93]
	v_mfma_f32_16x16x32_bf16 v[86:89], v[194:197], v[170:173], v[86:89]
	v_mfma_f32_16x16x32_bf16 v[82:85], v[212:215], v[170:173], v[82:85]
	v_mfma_f32_16x16x32_bf16 v[58:61], v[194:197], v[178:181], v[58:61]
	v_mfma_f32_16x16x32_bf16 v[46:49], v[212:215], v[178:181], v[46:49]
	v_mfma_f32_16x16x32_bf16 v[38:41], v[194:197], v[186:189], v[38:41]
	v_mfma_f32_16x16x32_bf16 v[26:29], v[212:215], v[186:189], v[26:29]
	v_mfma_f32_16x16x32_bf16 v[94:97], v[208:211], v[166:169], v[94:97]
	v_mfma_f32_16x16x32_bf16 v[90:93], v[216:219], v[166:169], v[90:93]
	v_mfma_f32_16x16x32_bf16 v[86:89], v[208:211], v[174:177], v[86:89]
	v_mfma_f32_16x16x32_bf16 v[82:85], v[216:219], v[174:177], v[82:85]
	v_mfma_f32_16x16x32_bf16 v[58:61], v[208:211], v[182:185], v[58:61]
	v_mfma_f32_16x16x32_bf16 v[46:49], v[216:219], v[182:185], v[46:49]
	v_mfma_f32_16x16x32_bf16 v[38:41], v[208:211], v[190:193], v[38:41]
	v_mfma_f32_16x16x32_bf16 v[26:29], v[216:219], v[190:193], v[26:29]
	s_add_i32 s60, s60, 2
	s_add_u32 s58, s58, 0x100
	s_addc_u32 s59, s59, 0
	s_add_u32 s20, s20, 0x100
	s_addc_u32 s21, s21, 0
	s_cmp_gt_u32 s60, 13
	s_barrier
	s_cbranch_scc0 .LBB0_979
	v_lshl_or_b32 v144, s19, 8, v148
	v_lshl_add_u32 v140, s18, 8, v146
	v_ashrrev_i32_e32 v145, 31, v144
	v_mov_b64_e32 v[142:143], s[94:95]
	v_mad_i64_i32 v[150:151], s[20:21], v140, s66, v[142:143]
	v_lshlrev_b64 v[144:145], 1, v[144:145]
	v_lshl_add_u64 v[154:155], v[150:151], 0, v[144:145]
	v_cvt_pk_bf16_f32 v150, v78, v79
	v_cvt_pk_bf16_f32 v151, v80, v81
	v_cvt_pk_bf16_f32 v152, v74, v75
	v_cvt_pk_bf16_f32 v153, v76, v77
	global_store_dwordx4 v[154:155], v[150:153], off
	v_cvt_pk_bf16_f32 v126, v126, v127
	v_cvt_pk_bf16_f32 v127, v128, v129
	v_cvt_pk_bf16_f32 v128, v122, v123
	v_cvt_pk_bf16_f32 v129, v124, v125
	global_store_dwordx4 v[154:155], v[126:129], off offset:256
	v_or_b32_e32 v122, 16, v140
	v_mad_i64_i32 v[124:125], s[20:21], v122, s66, v[142:143]
	v_lshl_add_u64 v[128:129], v[124:125], 0, v[144:145]
	v_cvt_pk_bf16_f32 v124, v70, v71
	v_cvt_pk_bf16_f32 v125, v72, v73
	v_cvt_pk_bf16_f32 v126, v66, v67
	v_cvt_pk_bf16_f32 v127, v68, v69
	global_store_dwordx4 v[128:129], v[124:127], off
	v_cvt_pk_bf16_f32 v118, v118, v119
	v_cvt_pk_bf16_f32 v119, v120, v121
	v_cvt_pk_bf16_f32 v120, v114, v115
	v_cvt_pk_bf16_f32 v121, v116, v117
	global_store_dwordx4 v[128:129], v[118:121], off offset:256
	v_or_b32_e32 v114, 32, v140
	v_mad_i64_i32 v[116:117], s[20:21], v114, s66, v[142:143]
	v_lshl_add_u64 v[120:121], v[116:117], 0, v[144:145]
	v_cvt_pk_bf16_f32 v116, v62, v63
	v_cvt_pk_bf16_f32 v117, v64, v65
	v_cvt_pk_bf16_f32 v118, v54, v55
	v_cvt_pk_bf16_f32 v119, v56, v57
	global_store_dwordx4 v[120:121], v[116:119], off
	v_cvt_pk_bf16_f32 v110, v110, v111
	v_cvt_pk_bf16_f32 v111, v112, v113
	v_cvt_pk_bf16_f32 v112, v106, v107
	v_cvt_pk_bf16_f32 v113, v108, v109
	global_store_dwordx4 v[120:121], v[110:113], off offset:256
	v_or_b32_e32 v106, 48, v140
	v_mad_i64_i32 v[108:109], s[20:21], v106, s66, v[142:143]
	v_lshl_add_u64 v[112:113], v[108:109], 0, v[144:145]
	v_cvt_pk_bf16_f32 v108, v50, v51
	v_cvt_pk_bf16_f32 v109, v52, v53
	v_cvt_pk_bf16_f32 v110, v42, v43
	v_cvt_pk_bf16_f32 v111, v44, v45
	global_store_dwordx4 v[112:113], v[108:111], off
	v_cvt_pk_bf16_f32 v102, v102, v103
	v_cvt_pk_bf16_f32 v103, v104, v105
	v_cvt_pk_bf16_f32 v104, v98, v99
	v_cvt_pk_bf16_f32 v105, v100, v101
	global_store_dwordx4 v[112:113], v[102:105], off offset:256
	v_add_u32_e32 v98, 0x80, v140
	v_mad_i64_i32 v[100:101], s[20:21], v98, s66, v[142:143]
	v_lshl_add_u64 v[104:105], v[100:101], 0, v[144:145]
	v_cvt_pk_bf16_f32 v100, v34, v35
	v_cvt_pk_bf16_f32 v101, v36, v37
	v_cvt_pk_bf16_f32 v102, v30, v31
	v_cvt_pk_bf16_f32 v103, v32, v33
	global_store_dwordx4 v[104:105], v[100:103], off
	v_cvt_pk_bf16_f32 v94, v94, v95
	v_cvt_pk_bf16_f32 v95, v96, v97
	v_cvt_pk_bf16_f32 v96, v90, v91
	v_cvt_pk_bf16_f32 v97, v92, v93
	global_store_dwordx4 v[104:105], v[94:97], off offset:256
	v_add_u32_e32 v90, 0x90, v140
	v_mad_i64_i32 v[92:93], s[20:21], v90, s66, v[142:143]
	v_lshl_add_u64 v[96:97], v[92:93], 0, v[144:145]
	v_cvt_pk_bf16_f32 v92, v22, v23
	v_cvt_pk_bf16_f32 v93, v24, v25
	v_cvt_pk_bf16_f32 v94, v18, v19
	v_cvt_pk_bf16_f32 v95, v20, v21
	global_store_dwordx4 v[96:97], v[92:95], off
	v_cvt_pk_bf16_f32 v86, v86, v87
	v_cvt_pk_bf16_f32 v87, v88, v89
	v_cvt_pk_bf16_f32 v88, v82, v83
	v_cvt_pk_bf16_f32 v89, v84, v85
	global_store_dwordx4 v[96:97], v[86:89], off offset:256
	v_add_u32_e32 v82, 0xa0, v140
	v_mad_i64_i32 v[84:85], s[20:21], v82, s66, v[142:143]
	v_lshl_add_u64 v[88:89], v[84:85], 0, v[144:145]
	v_cvt_pk_bf16_f32 v84, v12, v13
	v_cvt_pk_bf16_f32 v85, v14, v15
	v_cvt_pk_bf16_f32 v86, v8, v9
	v_cvt_pk_bf16_f32 v87, v10, v11
	global_store_dwordx4 v[88:89], v[84:87], off
	v_cvt_pk_bf16_f32 v58, v58, v59
	v_cvt_pk_bf16_f32 v59, v60, v61
	v_cvt_pk_bf16_f32 v60, v46, v47
	v_cvt_pk_bf16_f32 v61, v48, v49
	global_store_dwordx4 v[88:89], v[58:61], off offset:256
	v_add_u32_e32 v46, 0xb0, v140
	v_mad_i64_i32 v[48:49], s[20:21], v46, s66, v[142:143]
	v_lshl_add_u64 v[48:49], v[48:49], 0, v[144:145]
	v_cvt_pk_bf16_f32 v58, v4, v5
	v_cvt_pk_bf16_f32 v59, v6, v7
	v_cvt_pk_bf16_f32 v60, v0, v1
	v_cvt_pk_bf16_f32 v61, v2, v3
	global_store_dwordx4 v[48:49], v[58:61], off
	v_cvt_pk_bf16_f32 v38, v38, v39
	v_cvt_pk_bf16_f32 v39, v40, v41
	v_cvt_pk_bf16_f32 v40, v26, v27
	v_cvt_pk_bf16_f32 v41, v28, v29
	global_store_dwordx4 v[48:49], v[38:41], off offset:256
	s_cmp_eq_u32 s19, 34
	s_cselect_b64 s[18:19], -1, 0
	s_and_b64 s[20:21], s[38:39], s[18:19]
	s_and_saveexec_b64 s[18:19], s[20:21]
	s_cbranch_execz .LBB0_975
	v_ashrrev_i32_e32 v141, 31, v140
	v_lshlrev_b64 v[26:27], 5, v[140:141]
	v_ashrrev_i32_e32 v123, 31, v122
	v_lshl_add_u64 v[26:27], s[42:43], 0, v[26:27]
	global_store_dwordx4 v[26:27], v[78:81], off
	global_store_dwordx4 v[26:27], v[74:77], off offset:16
	v_lshlrev_b64 v[26:27], 5, v[122:123]
	v_ashrrev_i32_e32 v115, 31, v114
	v_lshl_add_u64 v[26:27], s[42:43], 0, v[26:27]
	global_store_dwordx4 v[26:27], v[70:73], off
	global_store_dwordx4 v[26:27], v[66:69], off offset:16
	v_lshlrev_b64 v[26:27], 5, v[114:115]
	v_ashrrev_i32_e32 v107, 31, v106
	v_lshl_add_u64 v[26:27], s[42:43], 0, v[26:27]
	global_store_dwordx4 v[26:27], v[62:65], off
	global_store_dwordx4 v[26:27], v[54:57], off offset:16
	v_lshlrev_b64 v[26:27], 5, v[106:107]
	v_ashrrev_i32_e32 v99, 31, v98
	v_lshl_add_u64 v[26:27], s[42:43], 0, v[26:27]
	global_store_dwordx4 v[26:27], v[50:53], off
	global_store_dwordx4 v[26:27], v[42:45], off offset:16
	v_lshlrev_b64 v[26:27], 5, v[98:99]
	v_ashrrev_i32_e32 v91, 31, v90
	v_lshl_add_u64 v[26:27], s[42:43], 0, v[26:27]
	global_store_dwordx4 v[26:27], v[34:37], off
	global_store_dwordx4 v[26:27], v[30:33], off offset:16
	v_lshlrev_b64 v[26:27], 5, v[90:91]
	v_ashrrev_i32_e32 v83, 31, v82
	v_lshl_add_u64 v[26:27], s[42:43], 0, v[26:27]
	global_store_dwordx4 v[26:27], v[22:25], off
	global_store_dwordx4 v[26:27], v[18:21], off offset:16
	v_ashrrev_i32_e32 v47, 31, v46
	s_nop 0
	v_lshlrev_b64 v[18:19], 5, v[82:83]
	v_lshl_add_u64 v[18:19], s[42:43], 0, v[18:19]
	global_store_dwordx4 v[18:19], v[12:15], off
	global_store_dwordx4 v[18:19], v[8:11], off offset:16
	s_nop 1
	v_lshlrev_b64 v[8:9], 5, v[46:47]
	v_lshl_add_u64 v[8:9], s[42:43], 0, v[8:9]
	global_store_dwordx4 v[8:9], v[4:7], off
	global_store_dwordx4 v[8:9], v[0:3], off offset:16
	s_branch .LBB0_975
